# MLA exp/PV group interleave + DMA issues spread in S burst; pool-diff rewrite (no NA hoist)
# speedup vs baseline: 1.0334x; 1.0125x over previous
.LBB0_295:
	v_exp_f32_e32 v82, v82
	v_exp_f32_e32 v83, v83
	v_exp_f32_e32 v84, v84
	v_exp_f32_e32 v85, v85
	v_exp_f32_e32 v86, v86
	v_exp_f32_e32 v87, v87
	v_exp_f32_e32 v88, v88
	v_exp_f32_e32 v89, v89
	v_cvt_pk_bf16_f32 v82, v82, v83
	v_cvt_pk_bf16_f32 v83, v84, v85
	v_cvt_pk_bf16_f32 v84, v86, v87
	v_cvt_pk_bf16_f32 v85, v88, v89
	s_add_i32 s5, s0, 1
	s_cmp_lg_u32 s0, 2
	s_waitcnt lgkmcnt(0)
	v_mfma_f32_16x16x32_bf16 v[26:29], v[98:101], v[82:85], v[26:29]
	v_exp_f32_e32 v74, v74
	v_exp_f32_e32 v75, v75
	v_mfma_f32_16x16x32_bf16 v[2:5], v[94:97], v[82:85], v[2:5]
	v_exp_f32_e32 v76, v76
	v_exp_f32_e32 v77, v77
	v_mfma_f32_16x16x32_bf16 v[10:13], v[110:113], v[82:85], v[10:13]
	v_exp_f32_e32 v78, v78
	v_exp_f32_e32 v79, v79
	v_mfma_f32_16x16x32_bf16 v[22:25], v[114:117], v[82:85], v[22:25]
	v_exp_f32_e32 v80, v80
	v_exp_f32_e32 v81, v81
	v_cvt_pk_bf16_f32 v74, v74, v75
	v_cvt_pk_bf16_f32 v75, v76, v77
	v_mfma_f32_16x16x32_bf16 v[38:41], v[236:239], v[82:85], v[38:41]
	v_cvt_pk_bf16_f32 v76, v78, v79
	v_cvt_pk_bf16_f32 v77, v80, v81
	s_cselect_b32 s0, s5, 0
	s_add_i32 s5, s4, 1
	v_mfma_f32_16x16x32_bf16 v[30:33], v[98:101], v[74:77], v[30:33]
	v_exp_f32_e32 v86, v118
	v_exp_f32_e32 v87, v119
	v_mfma_f32_16x16x32_bf16 v[6:9], v[94:97], v[74:77], v[6:9]
	v_exp_f32_e32 v88, v120
	v_exp_f32_e32 v89, v121
	v_mfma_f32_16x16x32_bf16 v[14:17], v[110:113], v[74:77], v[14:17]
	v_exp_f32_e32 v118, v122
	v_exp_f32_e32 v119, v123
	v_mfma_f32_16x16x32_bf16 v[18:21], v[114:117], v[74:77], v[18:21]
	v_exp_f32_e32 v120, v124
	v_exp_f32_e32 v121, v125
	v_cvt_pk_bf16_f32 v86, v86, v87
	v_cvt_pk_bf16_f32 v87, v88, v89
	v_mfma_f32_16x16x32_bf16 v[34:37], v[236:239], v[74:77], v[34:37]
	v_cvt_pk_bf16_f32 v88, v118, v119
	v_cvt_pk_bf16_f32 v89, v120, v121
	s_cmp_lg_u32 s4, 2
	s_cselect_b32 s4, s5, 0
	v_mfma_f32_16x16x32_bf16 v[26:29], v[90:93], v[86:89], v[26:29]
	v_exp_f32_e32 v66, v66
	v_exp_f32_e32 v67, v67
	v_mfma_f32_16x16x32_bf16 v[2:5], v[106:109], v[86:89], v[2:5]
	v_exp_f32_e32 v68, v68
	v_exp_f32_e32 v69, v69
	v_mfma_f32_16x16x32_bf16 v[10:13], v[102:105], v[86:89], v[10:13]
	v_exp_f32_e32 v70, v70
	v_exp_f32_e32 v71, v71
	v_mfma_f32_16x16x32_bf16 v[22:25], v[126:129], v[86:89], v[22:25]
	v_exp_f32_e32 v72, v72
	v_exp_f32_e32 v73, v73
	v_cvt_pk_bf16_f32 v66, v66, v67
	v_cvt_pk_bf16_f32 v67, v68, v69
	v_mfma_f32_16x16x32_bf16 v[38:41], v[236:239], v[86:89], v[38:41]
	v_cvt_pk_bf16_f32 v68, v70, v71
	v_cvt_pk_bf16_f32 v69, v72, v73
	v_lshl_add_u64 v[136:137], v[136:137], 0, s[24:25]
	v_lshl_add_u64 v[138:139], v[138:139], 0, s[78:79]
	s_cmp_lg_u32 s2, s1
	v_mfma_f32_16x16x32_bf16 v[30:33], v[90:93], v[66:69], v[30:33]
	v_mfma_f32_16x16x32_bf16 v[6:9], v[106:109], v[66:69], v[6:9]
	v_mfma_f32_16x16x32_bf16 v[14:17], v[102:105], v[66:69], v[14:17]
	v_mfma_f32_16x16x32_bf16 v[18:21], v[126:129], v[66:69], v[18:21]
	v_mfma_f32_16x16x32_bf16 v[34:37], v[236:239], v[66:69], v[34:37]
	s_cbranch_scc0 .LBB0_302
.LBB0_296:
	s_waitcnt vmcnt(5) lgkmcnt(0)
	s_barrier
	s_mul_i32 s5, s0, 0x5000
	v_add_u32_e32 v144, s5, v143
	ds_read_b128 v[66:69], v144
	ds_read_b128 v[74:77], v144 offset:4096
	ds_read_b128 v[78:81], v144 offset:8192
	ds_read_b128 v[86:89], v144 offset:1024
	ds_read_b128 v[90:93], v144 offset:5120
	ds_read_b128 v[94:97], v144 offset:9216
	ds_read_b128 v[98:101], v144 offset:2048
	ds_read_b128 v[102:105], v144 offset:6144
	ds_read_b128 v[106:109], v144 offset:10240
	ds_read_b128 v[110:113], v144 offset:3072
	ds_read_b128 v[114:117], v144 offset:7168
	ds_read_b128 v[126:129], v144 offset:11264
	s_add_i32 s1, s1, 1
	s_mul_i32 s5, s4, 0x5000
	s_add_i32 s5, s5, s100
	s_mov_b32 m0, s5
	s_add_i32 s6, s5, 0xfc0
	s_waitcnt lgkmcnt(9)
	v_mfma_f32_16x16x32_bf16 v[82:85], v[66:69], v[46:49], v[228:231]
	v_mfma_f32_16x16x32_bf16 v[66:69], v[66:69], v[62:65], v[232:235]
	v_mfma_f32_16x16x32_bf16 v[66:69], v[74:77], v[58:61], v[66:69]
	global_load_lds_dwordx4 v[136:137], off
	v_mfma_f32_16x16x32_bf16 v[82:85], v[74:77], v[42:45], v[82:85]
	s_mov_b32 m0, s6
	v_mfma_f32_16x16x32_bf16 v[74:77], v[78:81], v[54:57], v[66:69]
	s_add_i32 s6, s5, 0x1f80
	s_waitcnt lgkmcnt(6)
	v_mfma_f32_16x16x32_bf16 v[66:69], v[86:89], v[46:49], v[228:231]
	v_mfma_f32_16x16x32_bf16 v[82:85], v[78:81], v[50:53], v[82:85]
	global_load_lds_dwordx4 v[136:137], off offset:64
	v_mfma_f32_16x16x32_bf16 v[78:81], v[86:89], v[62:65], v[232:235]
	s_mov_b32 m0, s6
	v_mfma_f32_16x16x32_bf16 v[66:69], v[90:93], v[42:45], v[66:69]
	s_add_i32 s6, s5, 0x3000
	v_mfma_f32_16x16x32_bf16 v[78:81], v[90:93], v[58:61], v[78:81]
	global_load_lds_dwordx4 v[136:137], off offset:128
	v_mfma_f32_16x16x32_bf16 v[86:89], v[94:97], v[50:53], v[66:69]
	s_mov_b32 m0, s6
	s_add_i32 s6, s5, 0x3fc0
	s_waitcnt lgkmcnt(3)
	v_mfma_f32_16x16x32_bf16 v[66:69], v[98:101], v[46:49], v[228:231]
	v_mfma_f32_16x16x32_bf16 v[90:93], v[98:101], v[62:65], v[232:235]
	global_load_lds_dwordx4 v[138:139], off
	v_mfma_f32_16x16x32_bf16 v[66:69], v[102:105], v[42:45], v[66:69]
	s_mov_b32 m0, s6
	v_mfma_f32_16x16x32_bf16 v[90:93], v[102:105], v[58:61], v[90:93]
	v_mfma_f32_16x16x32_bf16 v[118:121], v[106:109], v[50:53], v[66:69]
	global_load_lds_dwordx4 v[138:139], off offset:64
	v_mfma_f32_16x16x32_bf16 v[66:69], v[106:109], v[54:57], v[90:93]
	s_waitcnt lgkmcnt(0)
	v_mfma_f32_16x16x32_bf16 v[90:93], v[110:113], v[46:49], v[228:231]
	v_mfma_f32_16x16x32_bf16 v[70:73], v[110:113], v[62:65], v[232:235]
	v_mfma_f32_16x16x32_bf16 v[90:93], v[114:117], v[42:45], v[90:93]
	v_mfma_f32_16x16x32_bf16 v[70:73], v[114:117], v[58:61], v[70:73]
	v_mfma_f32_16x16x32_bf16 v[78:81], v[94:97], v[54:57], v[78:81]
	v_mfma_f32_16x16x32_bf16 v[122:125], v[126:129], v[50:53], v[90:93]
	v_mfma_f32_16x16x32_bf16 v[70:73], v[126:129], v[54:57], v[70:73]
	ds_read_b128 v[98:101], v144 offset:12288
	s_nop 2
	ds_read_b128 v[90:93], v144 offset:16384
	ds_read_b128 v[94:97], v144 offset:13312
	ds_read_b128 v[106:109], v144 offset:17408
	ds_read_b128 v[110:113], v144 offset:14336
	ds_read_b128 v[102:105], v144 offset:18432
	ds_read_b128 v[114:117], v144 offset:15360
	ds_read_b128 v[126:129], v144 offset:19456
	v_max3_f32 v144, v82, v83, v84
	v_max3_f32 v144, v144, v85, v86
	v_max3_f32 v144, v144, v87, v88
	v_max3_f32 v144, v144, v89, v118
	v_max3_f32 v144, v144, v119, v120
	v_max3_f32 v144, v144, v121, v122
	v_max3_f32 v144, v144, v123, v124
	v_max_f32_e32 v144, v144, v125
	v_cmp_lt_f32_e32 vcc, s8, v144
	s_cbranch_vccz .LBB0_300
	v_mov_b32_e32 v145, v144
	s_nop 1
	v_permlane32_swap_b32_e32 v144, v145
	v_max_f32_e32 v145, v145, v145
	v_max_f32_e32 v144, v144, v144
	v_max_f32_e32 v144, v144, v145
	v_mov_b32_e32 v145, v144
	s_nop 1
	v_permlane16_swap_b32_e32 v144, v145
	v_max_f32_e32 v145, v145, v145
	v_max_f32_e32 v144, v144, v144
	v_max_f32_e32 v144, v144, v145
	v_max_f32_e32 v144, v144, v144
	v_max_f32_e32 v145, 0, v144
	v_exp_f32_e64 v144, -v145
	v_add_f32_e32 v134, v134, v145
	v_sub_f32_e32 v82, v82, v145
	v_sub_f32_e32 v83, v83, v145
	v_pk_mul_f32 v[40:41], v[40:41], v[144:145] op_sel_hi:[1,0]
	v_pk_mul_f32 v[38:39], v[38:39], v[144:145] op_sel_hi:[1,0]
	v_pk_mul_f32 v[28:29], v[28:29], v[144:145] op_sel_hi:[1,0]
	v_pk_mul_f32 v[26:27], v[26:27], v[144:145] op_sel_hi:[1,0]
	v_sub_f32_e32 v84, v84, v145
	v_sub_f32_e32 v85, v85, v145
	v_pk_mul_f32 v[4:5], v[4:5], v[144:145] op_sel_hi:[1,0]
	v_pk_mul_f32 v[2:3], v[2:3], v[144:145] op_sel_hi:[1,0]
	v_sub_f32_e32 v86, v86, v145
	v_sub_f32_e32 v87, v87, v145
	v_sub_f32_e32 v88, v88, v145
	v_sub_f32_e32 v89, v89, v145
	v_pk_mul_f32 v[12:13], v[12:13], v[144:145] op_sel_hi:[1,0]
	v_pk_mul_f32 v[10:11], v[10:11], v[144:145] op_sel_hi:[1,0]
	v_sub_f32_e32 v118, v118, v145
	v_sub_f32_e32 v119, v119, v145
	v_sub_f32_e32 v120, v120, v145
	v_sub_f32_e32 v121, v121, v145
	v_pk_mul_f32 v[24:25], v[24:25], v[144:145] op_sel_hi:[1,0]
	v_pk_mul_f32 v[22:23], v[22:23], v[144:145] op_sel_hi:[1,0]
	v_sub_f32_e32 v122, v122, v145
	v_sub_f32_e32 v123, v123, v145
	v_sub_f32_e32 v124, v124, v145
	v_sub_f32_e32 v125, v125, v145
	v_xor_b32_e32 v228, 0x80000000, v134
	v_mov_b32_e32 v229, v228
	v_mov_b32_e32 v230, v228
	v_mov_b32_e32 v231, v228

.LBB0_317:
	s_cmpk_gt_u32 s24, 0xf77
	s_cbranch_scc0 .LBB0_328
	s_lshl_b32 s0, s24, 4
	s_add_i32 s0, s0, 0xffff0880
	s_cmpk_gt_u32 s0, 0x7fff
	s_movk_i32 s2, 0x100
	s_movk_i32 s1, 0xe000
	s_cselect_b32 s18, s2, 0x2000
	s_movk_i32 s2, 0x1ff0
	s_cselect_b32 s1, 0x7fffff00, s1
	s_cselect_b32 s2, 0xf0, s2
	s_and_b32 s19, s2, s0
	s_and_b32 s2, s1, s0
	s_mov_b32 s1, s3
	s_lshl_b64 s[10:11], s[2:3], 10
	s_lshl_b64 s[0:1], s[0:1], 10
	v_lshl_add_u64 v[4:5], v[66:67], 0, s[10:11]
	v_lshl_add_u64 v[2:3], v[68:69], 0, s[0:1]
	s_branch .Lpd_start
.Lpd_start:
	v_readfirstlane_b32 s46, v4
	v_readfirstlane_b32 s47, v5
	v_readfirstlane_b32 s36, v2
	v_readfirstlane_b32 s37, v3
	v_readfirstlane_b32 s25, v196
	v_and_b32_e32 v0, 63, v196
	v_lshlrev_b32_e32 v0, 2, v0
	v_readlane_b32 s50, v226, 7
	v_readlane_b32 s51, v226, 8
	s_nop 3
	s_lshr_b32 s25, s25, 6
	s_cmp_eq_u32 s25, 0
	s_cbranch_scc1 .Lpd_hw1
	s_cmp_eq_u32 s25, 1
	s_cbranch_scc1 .Lpd_hw2
	s_cmp_eq_u32 s25, 2
	s_cbranch_scc1 .Lpd_hw4
	s_branch .Lpd_hw8
.Lpd_hw1:
	s_add_i32 s0, s19, -1
	s_cmp_lt_u32 s0, s18
	s_cbranch_scc0 .Lpd_z1_0
	s_lshl_b32 s0, s0, 10
	s_add_u32 s48, s46, s0
	s_addc_u32 s49, s47, 0
	global_load_dword v6, v0, s[48:49]
	s_branch .Lpd_n1_0
.Lpd_z1_0:
	global_load_dword v6, v0, s[50:51]
.Lpd_n1_0:
	s_lshl_b32 s0, s19, 10
	s_add_u32 s48, s46, s0
	s_addc_u32 s49, s47, 0
	global_load_dword v7, v0, s[48:49]
	s_add_i32 s0, s19, 1
	s_cmp_lt_u32 s0, s18
	s_cbranch_scc0 .Lpd_z1_2
	s_lshl_b32 s0, s0, 10
	s_add_u32 s48, s46, s0
	s_addc_u32 s49, s47, 0
	global_load_dword v8, v0, s[48:49]
	s_branch .Lpd_n1_2
.Lpd_z1_2:
	global_load_dword v8, v0, s[50:51]
.Lpd_n1_2:
	s_add_i32 s0, s19, 2
	s_cmp_lt_u32 s0, s18
	s_cbranch_scc0 .Lpd_z1_3
	s_lshl_b32 s0, s0, 10
	s_add_u32 s48, s46, s0
	s_addc_u32 s49, s47, 0
	global_load_dword v9, v0, s[48:49]
	s_branch .Lpd_n1_3
.Lpd_z1_3:
	global_load_dword v9, v0, s[50:51]
.Lpd_n1_3:
	s_add_i32 s0, s19, 3
	s_cmp_lt_u32 s0, s18
	s_cbranch_scc0 .Lpd_z1_4
	s_lshl_b32 s0, s0, 10
	s_add_u32 s48, s46, s0
	s_addc_u32 s49, s47, 0
	global_load_dword v10, v0, s[48:49]
	s_branch .Lpd_n1_4
.Lpd_z1_4:
	global_load_dword v10, v0, s[50:51]
.Lpd_n1_4:
	s_add_i32 s0, s19, 4
	s_cmp_lt_u32 s0, s18
	s_cbranch_scc0 .Lpd_z1_5
	s_lshl_b32 s0, s0, 10
	s_add_u32 s48, s46, s0
	s_addc_u32 s49, s47, 0
	global_load_dword v11, v0, s[48:49]
	s_branch .Lpd_n1_5
.Lpd_z1_5:
	global_load_dword v11, v0, s[50:51]
.Lpd_n1_5:
	s_add_i32 s0, s19, 5
	s_cmp_lt_u32 s0, s18
	s_cbranch_scc0 .Lpd_z1_6
	s_lshl_b32 s0, s0, 10
	s_add_u32 s48, s46, s0
	s_addc_u32 s49, s47, 0
	global_load_dword v12, v0, s[48:49]
	s_branch .Lpd_n1_6
.Lpd_z1_6:
	global_load_dword v12, v0, s[50:51]
.Lpd_n1_6:
	s_add_i32 s0, s19, 6
	s_cmp_lt_u32 s0, s18
	s_cbranch_scc0 .Lpd_z1_7
	s_lshl_b32 s0, s0, 10
	s_add_u32 s48, s46, s0
	s_addc_u32 s49, s47, 0
	global_load_dword v13, v0, s[48:49]
	s_branch .Lpd_n1_7
.Lpd_z1_7:
	global_load_dword v13, v0, s[50:51]
.Lpd_n1_7:
	s_add_i32 s0, s19, 7
	s_cmp_lt_u32 s0, s18
	s_cbranch_scc0 .Lpd_z1_8
	s_lshl_b32 s0, s0, 10
	s_add_u32 s48, s46, s0
	s_addc_u32 s49, s47, 0
	global_load_dword v14, v0, s[48:49]
	s_branch .Lpd_n1_8
.Lpd_z1_8:
	global_load_dword v14, v0, s[50:51]
.Lpd_n1_8:
	s_add_i32 s0, s19, 8
	s_cmp_lt_u32 s0, s18
	s_cbranch_scc0 .Lpd_z1_9
	s_lshl_b32 s0, s0, 10
	s_add_u32 s48, s46, s0
	s_addc_u32 s49, s47, 0
	global_load_dword v15, v0, s[48:49]
	s_branch .Lpd_n1_9
.Lpd_z1_9:
	global_load_dword v15, v0, s[50:51]
.Lpd_n1_9:
	s_add_i32 s0, s19, 9
	s_cmp_lt_u32 s0, s18
	s_cbranch_scc0 .Lpd_z1_10
	s_lshl_b32 s0, s0, 10
	s_add_u32 s48, s46, s0
	s_addc_u32 s49, s47, 0
	global_load_dword v16, v0, s[48:49]
	s_branch .Lpd_n1_10
.Lpd_z1_10:
	global_load_dword v16, v0, s[50:51]
.Lpd_n1_10:
	s_add_i32 s0, s19, 10
	s_cmp_lt_u32 s0, s18
	s_cbranch_scc0 .Lpd_z1_11
	s_lshl_b32 s0, s0, 10
	s_add_u32 s48, s46, s0
	s_addc_u32 s49, s47, 0
	global_load_dword v17, v0, s[48:49]
	s_branch .Lpd_n1_11
.Lpd_z1_11:
	global_load_dword v17, v0, s[50:51]
.Lpd_n1_11:
	s_add_i32 s0, s19, 11
	s_cmp_lt_u32 s0, s18
	s_cbranch_scc0 .Lpd_z1_12
	s_lshl_b32 s0, s0, 10
	s_add_u32 s48, s46, s0
	s_addc_u32 s49, s47, 0
	global_load_dword v18, v0, s[48:49]
	s_branch .Lpd_n1_12
.Lpd_z1_12:
	global_load_dword v18, v0, s[50:51]
.Lpd_n1_12:
	s_add_i32 s0, s19, 12
	s_cmp_lt_u32 s0, s18
	s_cbranch_scc0 .Lpd_z1_13
	s_lshl_b32 s0, s0, 10
	s_add_u32 s48, s46, s0
	s_addc_u32 s49, s47, 0
	global_load_dword v19, v0, s[48:49]
	s_branch .Lpd_n1_13
.Lpd_z1_13:
	global_load_dword v19, v0, s[50:51]
.Lpd_n1_13:
	s_add_i32 s0, s19, 13
	s_cmp_lt_u32 s0, s18
	s_cbranch_scc0 .Lpd_z1_14
	s_lshl_b32 s0, s0, 10
	s_add_u32 s48, s46, s0
	s_addc_u32 s49, s47, 0
	global_load_dword v20, v0, s[48:49]
	s_branch .Lpd_n1_14
.Lpd_z1_14:
	global_load_dword v20, v0, s[50:51]
.Lpd_n1_14:
	s_add_i32 s0, s19, 14
	s_cmp_lt_u32 s0, s18
	s_cbranch_scc0 .Lpd_z1_15
	s_lshl_b32 s0, s0, 10
	s_add_u32 s48, s46, s0
	s_addc_u32 s49, s47, 0
	global_load_dword v21, v0, s[48:49]
	s_branch .Lpd_n1_15
.Lpd_z1_15:
	global_load_dword v21, v0, s[50:51]
.Lpd_n1_15:
	s_add_i32 s0, s19, 15
	s_cmp_lt_u32 s0, s18
	s_cbranch_scc0 .Lpd_z1_16
	s_lshl_b32 s0, s0, 10
	s_add_u32 s48, s46, s0
	s_addc_u32 s49, s47, 0
	global_load_dword v22, v0, s[48:49]
	s_branch .Lpd_n1_16
.Lpd_z1_16:
	global_load_dword v22, v0, s[50:51]
.Lpd_n1_16:
	s_add_i32 s0, s19, 1
	s_min_u32 s0, s0, s18
	s_add_i32 s1, s19, -1
	s_max_i32 s1, s1, 0
	s_sub_i32 s0, s0, s1
	v_cvt_f32_i32_e32 v37, s0
	v_div_scale_f32 v38, s[0:1], v37, v37, 1.0
	v_rcp_f32_e32 v39, v38
	v_div_scale_f32 v41, vcc, 1.0, v37, 1.0
	v_fma_f32 v40, -v38, v39, 1.0
	v_fmac_f32_e32 v39, v40, v39
	v_mul_f32_e32 v42, v41, v39
	v_fma_f32 v43, -v38, v42, v41
	v_fmac_f32_e32 v42, v43, v39
	v_fma_f32 v38, -v38, v42, v41
	v_div_fmas_f32 v38, v38, v39, v42
	v_div_fixup_f32 v44, v38, v37, 1.0
	s_waitcnt vmcnt(15)
	v_lshlrev_b32_e32 v47, 16, v6
	v_and_b32_e32 v48, 0xffff0000, v6
	v_add_f32_e32 v45, 0, v47
	v_add_f32_e32 v46, 0, v48
	v_lshlrev_b32_e32 v47, 16, v7
	v_and_b32_e32 v48, 0xffff0000, v7
	v_add_f32_e32 v45, v45, v47
	v_add_f32_e32 v46, v46, v48
	v_lshlrev_b32_e32 v47, 16, v7
	v_and_b32_e32 v48, 0xffff0000, v7
	v_fma_f32 v45, v44, v45, -v47
	v_fma_f32 v46, v44, v46, -v48
	v_cvt_pk_bf16_f32 v45, v45, v46
	global_store_dword v0, v45, s[36:37]
	s_add_u32 s36, s36, 0x400
	s_addc_u32 s37, s37, 0
	s_add_i32 s0, s19, 2
	s_min_u32 s0, s0, s18
	s_add_i32 s1, s19, 0
	s_max_i32 s1, s1, 0
	s_sub_i32 s0, s0, s1
	v_cvt_f32_i32_e32 v37, s0
	v_div_scale_f32 v38, s[0:1], v37, v37, 1.0
	v_rcp_f32_e32 v39, v38
	v_div_scale_f32 v41, vcc, 1.0, v37, 1.0
	v_fma_f32 v40, -v38, v39, 1.0
	v_fmac_f32_e32 v39, v40, v39
	v_mul_f32_e32 v42, v41, v39
	v_fma_f32 v43, -v38, v42, v41
	v_fmac_f32_e32 v42, v43, v39
	v_fma_f32 v38, -v38, v42, v41
	v_div_fmas_f32 v38, v38, v39, v42
	v_div_fixup_f32 v44, v38, v37, 1.0
	s_waitcnt vmcnt(15)
	v_lshlrev_b32_e32 v47, 16, v7
	v_and_b32_e32 v48, 0xffff0000, v7
	v_add_f32_e32 v45, 0, v47
	v_add_f32_e32 v46, 0, v48
	v_lshlrev_b32_e32 v47, 16, v8
	v_and_b32_e32 v48, 0xffff0000, v8
	v_add_f32_e32 v45, v45, v47
	v_add_f32_e32 v46, v46, v48
	v_lshlrev_b32_e32 v47, 16, v8
	v_and_b32_e32 v48, 0xffff0000, v8
	v_fma_f32 v45, v44, v45, -v47
	v_fma_f32 v46, v44, v46, -v48
	v_cvt_pk_bf16_f32 v45, v45, v46
	global_store_dword v0, v45, s[36:37]
	s_add_u32 s36, s36, 0x400
	s_addc_u32 s37, s37, 0
	s_add_i32 s0, s19, 3
	s_min_u32 s0, s0, s18
	s_add_i32 s1, s19, 1
	s_max_i32 s1, s1, 0
	s_sub_i32 s0, s0, s1
	v_cvt_f32_i32_e32 v37, s0
	v_div_scale_f32 v38, s[0:1], v37, v37, 1.0
	v_rcp_f32_e32 v39, v38
	v_div_scale_f32 v41, vcc, 1.0, v37, 1.0
	v_fma_f32 v40, -v38, v39, 1.0
	v_fmac_f32_e32 v39, v40, v39
	v_mul_f32_e32 v42, v41, v39
	v_fma_f32 v43, -v38, v42, v41
	v_fmac_f32_e32 v42, v43, v39
	v_fma_f32 v38, -v38, v42, v41
	v_div_fmas_f32 v38, v38, v39, v42
	v_div_fixup_f32 v44, v38, v37, 1.0
	s_waitcnt vmcnt(15)
	v_lshlrev_b32_e32 v47, 16, v8
	v_and_b32_e32 v48, 0xffff0000, v8
	v_add_f32_e32 v45, 0, v47
	v_add_f32_e32 v46, 0, v48
	v_lshlrev_b32_e32 v47, 16, v9
	v_and_b32_e32 v48, 0xffff0000, v9
	v_add_f32_e32 v45, v45, v47
	v_add_f32_e32 v46, v46, v48
	v_lshlrev_b32_e32 v47, 16, v9
	v_and_b32_e32 v48, 0xffff0000, v9
	v_fma_f32 v45, v44, v45, -v47
	v_fma_f32 v46, v44, v46, -v48
	v_cvt_pk_bf16_f32 v45, v45, v46
	global_store_dword v0, v45, s[36:37]
	s_add_u32 s36, s36, 0x400
	s_addc_u32 s37, s37, 0
	s_add_i32 s0, s19, 4
	s_min_u32 s0, s0, s18
	s_add_i32 s1, s19, 2
	s_max_i32 s1, s1, 0
	s_sub_i32 s0, s0, s1
	v_cvt_f32_i32_e32 v37, s0
	v_div_scale_f32 v38, s[0:1], v37, v37, 1.0
	v_rcp_f32_e32 v39, v38
	v_div_scale_f32 v41, vcc, 1.0, v37, 1.0
	v_fma_f32 v40, -v38, v39, 1.0
	v_fmac_f32_e32 v39, v40, v39
	v_mul_f32_e32 v42, v41, v39
	v_fma_f32 v43, -v38, v42, v41
	v_fmac_f32_e32 v42, v43, v39
	v_fma_f32 v38, -v38, v42, v41
	v_div_fmas_f32 v38, v38, v39, v42
	v_div_fixup_f32 v44, v38, v37, 1.0
	s_waitcnt vmcnt(15)
	v_lshlrev_b32_e32 v47, 16, v9
	v_and_b32_e32 v48, 0xffff0000, v9
	v_add_f32_e32 v45, 0, v47
	v_add_f32_e32 v46, 0, v48
	v_lshlrev_b32_e32 v47, 16, v10
	v_and_b32_e32 v48, 0xffff0000, v10
	v_add_f32_e32 v45, v45, v47
	v_add_f32_e32 v46, v46, v48
	v_lshlrev_b32_e32 v47, 16, v10
	v_and_b32_e32 v48, 0xffff0000, v10
	v_fma_f32 v45, v44, v45, -v47
	v_fma_f32 v46, v44, v46, -v48
	v_cvt_pk_bf16_f32 v45, v45, v46
	global_store_dword v0, v45, s[36:37]
	s_add_u32 s36, s36, 0x400
	s_addc_u32 s37, s37, 0
	s_add_i32 s0, s19, 5
	s_min_u32 s0, s0, s18
	s_add_i32 s1, s19, 3
	s_max_i32 s1, s1, 0
	s_sub_i32 s0, s0, s1
	v_cvt_f32_i32_e32 v37, s0
	v_div_scale_f32 v38, s[0:1], v37, v37, 1.0
	v_rcp_f32_e32 v39, v38
	v_div_scale_f32 v41, vcc, 1.0, v37, 1.0
	v_fma_f32 v40, -v38, v39, 1.0
	v_fmac_f32_e32 v39, v40, v39
	v_mul_f32_e32 v42, v41, v39
	v_fma_f32 v43, -v38, v42, v41
	v_fmac_f32_e32 v42, v43, v39
	v_fma_f32 v38, -v38, v42, v41
	v_div_fmas_f32 v38, v38, v39, v42
	v_div_fixup_f32 v44, v38, v37, 1.0
	s_waitcnt vmcnt(15)
	v_lshlrev_b32_e32 v47, 16, v10
	v_and_b32_e32 v48, 0xffff0000, v10
	v_add_f32_e32 v45, 0, v47
	v_add_f32_e32 v46, 0, v48
	v_lshlrev_b32_e32 v47, 16, v11
	v_and_b32_e32 v48, 0xffff0000, v11
	v_add_f32_e32 v45, v45, v47
	v_add_f32_e32 v46, v46, v48
	v_lshlrev_b32_e32 v47, 16, v11
	v_and_b32_e32 v48, 0xffff0000, v11
	v_fma_f32 v45, v44, v45, -v47
	v_fma_f32 v46, v44, v46, -v48
	v_cvt_pk_bf16_f32 v45, v45, v46
	global_store_dword v0, v45, s[36:37]
	s_add_u32 s36, s36, 0x400
	s_addc_u32 s37, s37, 0
	s_add_i32 s0, s19, 6
	s_min_u32 s0, s0, s18
	s_add_i32 s1, s19, 4
	s_max_i32 s1, s1, 0
	s_sub_i32 s0, s0, s1
	v_cvt_f32_i32_e32 v37, s0
	v_div_scale_f32 v38, s[0:1], v37, v37, 1.0
	v_rcp_f32_e32 v39, v38
	v_div_scale_f32 v41, vcc, 1.0, v37, 1.0
	v_fma_f32 v40, -v38, v39, 1.0
	v_fmac_f32_e32 v39, v40, v39
	v_mul_f32_e32 v42, v41, v39
	v_fma_f32 v43, -v38, v42, v41
	v_fmac_f32_e32 v42, v43, v39
	v_fma_f32 v38, -v38, v42, v41
	v_div_fmas_f32 v38, v38, v39, v42
	v_div_fixup_f32 v44, v38, v37, 1.0
	s_waitcnt vmcnt(15)
	v_lshlrev_b32_e32 v47, 16, v11
	v_and_b32_e32 v48, 0xffff0000, v11
	v_add_f32_e32 v45, 0, v47
	v_add_f32_e32 v46, 0, v48
	v_lshlrev_b32_e32 v47, 16, v12
	v_and_b32_e32 v48, 0xffff0000, v12
	v_add_f32_e32 v45, v45, v47
	v_add_f32_e32 v46, v46, v48
	v_lshlrev_b32_e32 v47, 16, v12
	v_and_b32_e32 v48, 0xffff0000, v12
	v_fma_f32 v45, v44, v45, -v47
	v_fma_f32 v46, v44, v46, -v48
	v_cvt_pk_bf16_f32 v45, v45, v46
	global_store_dword v0, v45, s[36:37]
	s_add_u32 s36, s36, 0x400
	s_addc_u32 s37, s37, 0
	s_add_i32 s0, s19, 7
	s_min_u32 s0, s0, s18
	s_add_i32 s1, s19, 5
	s_max_i32 s1, s1, 0
	s_sub_i32 s0, s0, s1
	v_cvt_f32_i32_e32 v37, s0
	v_div_scale_f32 v38, s[0:1], v37, v37, 1.0
	v_rcp_f32_e32 v39, v38
	v_div_scale_f32 v41, vcc, 1.0, v37, 1.0
	v_fma_f32 v40, -v38, v39, 1.0
	v_fmac_f32_e32 v39, v40, v39
	v_mul_f32_e32 v42, v41, v39
	v_fma_f32 v43, -v38, v42, v41
	v_fmac_f32_e32 v42, v43, v39
	v_fma_f32 v38, -v38, v42, v41
	v_div_fmas_f32 v38, v38, v39, v42
	v_div_fixup_f32 v44, v38, v37, 1.0
	s_waitcnt vmcnt(15)
	v_lshlrev_b32_e32 v47, 16, v12
	v_and_b32_e32 v48, 0xffff0000, v12
	v_add_f32_e32 v45, 0, v47
	v_add_f32_e32 v46, 0, v48
	v_lshlrev_b32_e32 v47, 16, v13
	v_and_b32_e32 v48, 0xffff0000, v13
	v_add_f32_e32 v45, v45, v47
	v_add_f32_e32 v46, v46, v48
	v_lshlrev_b32_e32 v47, 16, v13
	v_and_b32_e32 v48, 0xffff0000, v13
	v_fma_f32 v45, v44, v45, -v47
	v_fma_f32 v46, v44, v46, -v48
	v_cvt_pk_bf16_f32 v45, v45, v46
	global_store_dword v0, v45, s[36:37]
	s_add_u32 s36, s36, 0x400
	s_addc_u32 s37, s37, 0
	s_add_i32 s0, s19, 8
	s_min_u32 s0, s0, s18
	s_add_i32 s1, s19, 6
	s_max_i32 s1, s1, 0
	s_sub_i32 s0, s0, s1
	v_cvt_f32_i32_e32 v37, s0
	v_div_scale_f32 v38, s[0:1], v37, v37, 1.0
	v_rcp_f32_e32 v39, v38
	v_div_scale_f32 v41, vcc, 1.0, v37, 1.0
	v_fma_f32 v40, -v38, v39, 1.0
	v_fmac_f32_e32 v39, v40, v39
	v_mul_f32_e32 v42, v41, v39
	v_fma_f32 v43, -v38, v42, v41
	v_fmac_f32_e32 v42, v43, v39
	v_fma_f32 v38, -v38, v42, v41
	v_div_fmas_f32 v38, v38, v39, v42
	v_div_fixup_f32 v44, v38, v37, 1.0
	s_waitcnt vmcnt(15)
	v_lshlrev_b32_e32 v47, 16, v13
	v_and_b32_e32 v48, 0xffff0000, v13
	v_add_f32_e32 v45, 0, v47
	v_add_f32_e32 v46, 0, v48
	v_lshlrev_b32_e32 v47, 16, v14
	v_and_b32_e32 v48, 0xffff0000, v14
	v_add_f32_e32 v45, v45, v47
	v_add_f32_e32 v46, v46, v48
	v_lshlrev_b32_e32 v47, 16, v14
	v_and_b32_e32 v48, 0xffff0000, v14
	v_fma_f32 v45, v44, v45, -v47
	v_fma_f32 v46, v44, v46, -v48
	v_cvt_pk_bf16_f32 v45, v45, v46
	global_store_dword v0, v45, s[36:37]
	s_add_u32 s36, s36, 0x400
	s_addc_u32 s37, s37, 0
	s_add_i32 s0, s19, 9
	s_min_u32 s0, s0, s18
	s_add_i32 s1, s19, 7
	s_max_i32 s1, s1, 0
	s_sub_i32 s0, s0, s1
	v_cvt_f32_i32_e32 v37, s0
	v_div_scale_f32 v38, s[0:1], v37, v37, 1.0
	v_rcp_f32_e32 v39, v38
	v_div_scale_f32 v41, vcc, 1.0, v37, 1.0
	v_fma_f32 v40, -v38, v39, 1.0
	v_fmac_f32_e32 v39, v40, v39
	v_mul_f32_e32 v42, v41, v39
	v_fma_f32 v43, -v38, v42, v41
	v_fmac_f32_e32 v42, v43, v39
	v_fma_f32 v38, -v38, v42, v41
	v_div_fmas_f32 v38, v38, v39, v42
	v_div_fixup_f32 v44, v38, v37, 1.0
	s_waitcnt vmcnt(15)
	v_lshlrev_b32_e32 v47, 16, v14
	v_and_b32_e32 v48, 0xffff0000, v14
	v_add_f32_e32 v45, 0, v47
	v_add_f32_e32 v46, 0, v48
	v_lshlrev_b32_e32 v47, 16, v15
	v_and_b32_e32 v48, 0xffff0000, v15
	v_add_f32_e32 v45, v45, v47
	v_add_f32_e32 v46, v46, v48
	v_lshlrev_b32_e32 v47, 16, v15
	v_and_b32_e32 v48, 0xffff0000, v15
	v_fma_f32 v45, v44, v45, -v47
	v_fma_f32 v46, v44, v46, -v48
	v_cvt_pk_bf16_f32 v45, v45, v46
	global_store_dword v0, v45, s[36:37]
	s_add_u32 s36, s36, 0x400
	s_addc_u32 s37, s37, 0
	s_add_i32 s0, s19, 10
	s_min_u32 s0, s0, s18
	s_add_i32 s1, s19, 8
	s_max_i32 s1, s1, 0
	s_sub_i32 s0, s0, s1
	v_cvt_f32_i32_e32 v37, s0
	v_div_scale_f32 v38, s[0:1], v37, v37, 1.0
	v_rcp_f32_e32 v39, v38
	v_div_scale_f32 v41, vcc, 1.0, v37, 1.0
	v_fma_f32 v40, -v38, v39, 1.0
	v_fmac_f32_e32 v39, v40, v39
	v_mul_f32_e32 v42, v41, v39
	v_fma_f32 v43, -v38, v42, v41
	v_fmac_f32_e32 v42, v43, v39
	v_fma_f32 v38, -v38, v42, v41
	v_div_fmas_f32 v38, v38, v39, v42
	v_div_fixup_f32 v44, v38, v37, 1.0
	s_waitcnt vmcnt(15)
	v_lshlrev_b32_e32 v47, 16, v15
	v_and_b32_e32 v48, 0xffff0000, v15
	v_add_f32_e32 v45, 0, v47
	v_add_f32_e32 v46, 0, v48
	v_lshlrev_b32_e32 v47, 16, v16
	v_and_b32_e32 v48, 0xffff0000, v16
	v_add_f32_e32 v45, v45, v47
	v_add_f32_e32 v46, v46, v48
	v_lshlrev_b32_e32 v47, 16, v16
	v_and_b32_e32 v48, 0xffff0000, v16
	v_fma_f32 v45, v44, v45, -v47
	v_fma_f32 v46, v44, v46, -v48
	v_cvt_pk_bf16_f32 v45, v45, v46
	global_store_dword v0, v45, s[36:37]
	s_add_u32 s36, s36, 0x400
	s_addc_u32 s37, s37, 0
	s_add_i32 s0, s19, 11
	s_min_u32 s0, s0, s18
	s_add_i32 s1, s19, 9
	s_max_i32 s1, s1, 0
	s_sub_i32 s0, s0, s1
	v_cvt_f32_i32_e32 v37, s0
	v_div_scale_f32 v38, s[0:1], v37, v37, 1.0
	v_rcp_f32_e32 v39, v38
	v_div_scale_f32 v41, vcc, 1.0, v37, 1.0
	v_fma_f32 v40, -v38, v39, 1.0
	v_fmac_f32_e32 v39, v40, v39
	v_mul_f32_e32 v42, v41, v39
	v_fma_f32 v43, -v38, v42, v41
	v_fmac_f32_e32 v42, v43, v39
	v_fma_f32 v38, -v38, v42, v41
	v_div_fmas_f32 v38, v38, v39, v42
	v_div_fixup_f32 v44, v38, v37, 1.0
	s_waitcnt vmcnt(15)
	v_lshlrev_b32_e32 v47, 16, v16
	v_and_b32_e32 v48, 0xffff0000, v16
	v_add_f32_e32 v45, 0, v47
	v_add_f32_e32 v46, 0, v48
	v_lshlrev_b32_e32 v47, 16, v17
	v_and_b32_e32 v48, 0xffff0000, v17
	v_add_f32_e32 v45, v45, v47
	v_add_f32_e32 v46, v46, v48
	v_lshlrev_b32_e32 v47, 16, v17
	v_and_b32_e32 v48, 0xffff0000, v17
	v_fma_f32 v45, v44, v45, -v47
	v_fma_f32 v46, v44, v46, -v48
	v_cvt_pk_bf16_f32 v45, v45, v46
	global_store_dword v0, v45, s[36:37]
	s_add_u32 s36, s36, 0x400
	s_addc_u32 s37, s37, 0
	s_add_i32 s0, s19, 12
	s_min_u32 s0, s0, s18
	s_add_i32 s1, s19, 10
	s_max_i32 s1, s1, 0
	s_sub_i32 s0, s0, s1
	v_cvt_f32_i32_e32 v37, s0
	v_div_scale_f32 v38, s[0:1], v37, v37, 1.0
	v_rcp_f32_e32 v39, v38
	v_div_scale_f32 v41, vcc, 1.0, v37, 1.0
	v_fma_f32 v40, -v38, v39, 1.0
	v_fmac_f32_e32 v39, v40, v39
	v_mul_f32_e32 v42, v41, v39
	v_fma_f32 v43, -v38, v42, v41
	v_fmac_f32_e32 v42, v43, v39
	v_fma_f32 v38, -v38, v42, v41
	v_div_fmas_f32 v38, v38, v39, v42
	v_div_fixup_f32 v44, v38, v37, 1.0
	s_waitcnt vmcnt(15)
	v_lshlrev_b32_e32 v47, 16, v17
	v_and_b32_e32 v48, 0xffff0000, v17
	v_add_f32_e32 v45, 0, v47
	v_add_f32_e32 v46, 0, v48
	v_lshlrev_b32_e32 v47, 16, v18
	v_and_b32_e32 v48, 0xffff0000, v18
	v_add_f32_e32 v45, v45, v47
	v_add_f32_e32 v46, v46, v48
	v_lshlrev_b32_e32 v47, 16, v18
	v_and_b32_e32 v48, 0xffff0000, v18
	v_fma_f32 v45, v44, v45, -v47
	v_fma_f32 v46, v44, v46, -v48
	v_cvt_pk_bf16_f32 v45, v45, v46
	global_store_dword v0, v45, s[36:37]
	s_add_u32 s36, s36, 0x400
	s_addc_u32 s37, s37, 0
	s_add_i32 s0, s19, 13
	s_min_u32 s0, s0, s18
	s_add_i32 s1, s19, 11
	s_max_i32 s1, s1, 0
	s_sub_i32 s0, s0, s1
	v_cvt_f32_i32_e32 v37, s0
	v_div_scale_f32 v38, s[0:1], v37, v37, 1.0
	v_rcp_f32_e32 v39, v38
	v_div_scale_f32 v41, vcc, 1.0, v37, 1.0
	v_fma_f32 v40, -v38, v39, 1.0
	v_fmac_f32_e32 v39, v40, v39
	v_mul_f32_e32 v42, v41, v39
	v_fma_f32 v43, -v38, v42, v41
	v_fmac_f32_e32 v42, v43, v39
	v_fma_f32 v38, -v38, v42, v41
	v_div_fmas_f32 v38, v38, v39, v42
	v_div_fixup_f32 v44, v38, v37, 1.0
	s_waitcnt vmcnt(15)
	v_lshlrev_b32_e32 v47, 16, v18
	v_and_b32_e32 v48, 0xffff0000, v18
	v_add_f32_e32 v45, 0, v47
	v_add_f32_e32 v46, 0, v48
	v_lshlrev_b32_e32 v47, 16, v19
	v_and_b32_e32 v48, 0xffff0000, v19
	v_add_f32_e32 v45, v45, v47
	v_add_f32_e32 v46, v46, v48
	v_lshlrev_b32_e32 v47, 16, v19
	v_and_b32_e32 v48, 0xffff0000, v19
	v_fma_f32 v45, v44, v45, -v47
	v_fma_f32 v46, v44, v46, -v48
	v_cvt_pk_bf16_f32 v45, v45, v46
	global_store_dword v0, v45, s[36:37]
	s_add_u32 s36, s36, 0x400
	s_addc_u32 s37, s37, 0
	s_add_i32 s0, s19, 14
	s_min_u32 s0, s0, s18
	s_add_i32 s1, s19, 12
	s_max_i32 s1, s1, 0
	s_sub_i32 s0, s0, s1
	v_cvt_f32_i32_e32 v37, s0
	v_div_scale_f32 v38, s[0:1], v37, v37, 1.0
	v_rcp_f32_e32 v39, v38
	v_div_scale_f32 v41, vcc, 1.0, v37, 1.0
	v_fma_f32 v40, -v38, v39, 1.0
	v_fmac_f32_e32 v39, v40, v39
	v_mul_f32_e32 v42, v41, v39
	v_fma_f32 v43, -v38, v42, v41
	v_fmac_f32_e32 v42, v43, v39
	v_fma_f32 v38, -v38, v42, v41
	v_div_fmas_f32 v38, v38, v39, v42
	v_div_fixup_f32 v44, v38, v37, 1.0
	s_waitcnt vmcnt(15)
	v_lshlrev_b32_e32 v47, 16, v19
	v_and_b32_e32 v48, 0xffff0000, v19
	v_add_f32_e32 v45, 0, v47
	v_add_f32_e32 v46, 0, v48
	v_lshlrev_b32_e32 v47, 16, v20
	v_and_b32_e32 v48, 0xffff0000, v20
	v_add_f32_e32 v45, v45, v47
	v_add_f32_e32 v46, v46, v48
	v_lshlrev_b32_e32 v47, 16, v20
	v_and_b32_e32 v48, 0xffff0000, v20
	v_fma_f32 v45, v44, v45, -v47
	v_fma_f32 v46, v44, v46, -v48
	v_cvt_pk_bf16_f32 v45, v45, v46
	global_store_dword v0, v45, s[36:37]
	s_add_u32 s36, s36, 0x400
	s_addc_u32 s37, s37, 0
	s_add_i32 s0, s19, 15
	s_min_u32 s0, s0, s18
	s_add_i32 s1, s19, 13
	s_max_i32 s1, s1, 0
	s_sub_i32 s0, s0, s1
	v_cvt_f32_i32_e32 v37, s0
	v_div_scale_f32 v38, s[0:1], v37, v37, 1.0
	v_rcp_f32_e32 v39, v38
	v_div_scale_f32 v41, vcc, 1.0, v37, 1.0
	v_fma_f32 v40, -v38, v39, 1.0
	v_fmac_f32_e32 v39, v40, v39
	v_mul_f32_e32 v42, v41, v39
	v_fma_f32 v43, -v38, v42, v41
	v_fmac_f32_e32 v42, v43, v39
	v_fma_f32 v38, -v38, v42, v41
	v_div_fmas_f32 v38, v38, v39, v42
	v_div_fixup_f32 v44, v38, v37, 1.0
	s_waitcnt vmcnt(15)
	v_lshlrev_b32_e32 v47, 16, v20
	v_and_b32_e32 v48, 0xffff0000, v20
	v_add_f32_e32 v45, 0, v47
	v_add_f32_e32 v46, 0, v48
	v_lshlrev_b32_e32 v47, 16, v21
	v_and_b32_e32 v48, 0xffff0000, v21
	v_add_f32_e32 v45, v45, v47
	v_add_f32_e32 v46, v46, v48
	v_lshlrev_b32_e32 v47, 16, v21
	v_and_b32_e32 v48, 0xffff0000, v21
	v_fma_f32 v45, v44, v45, -v47
	v_fma_f32 v46, v44, v46, -v48
	v_cvt_pk_bf16_f32 v45, v45, v46
	global_store_dword v0, v45, s[36:37]
	s_add_u32 s36, s36, 0x400
	s_addc_u32 s37, s37, 0
	s_add_i32 s0, s19, 16
	s_min_u32 s0, s0, s18
	s_add_i32 s1, s19, 14
	s_max_i32 s1, s1, 0
	s_sub_i32 s0, s0, s1
	v_cvt_f32_i32_e32 v37, s0
	v_div_scale_f32 v38, s[0:1], v37, v37, 1.0
	v_rcp_f32_e32 v39, v38
	v_div_scale_f32 v41, vcc, 1.0, v37, 1.0
	v_fma_f32 v40, -v38, v39, 1.0
	v_fmac_f32_e32 v39, v40, v39
	v_mul_f32_e32 v42, v41, v39
	v_fma_f32 v43, -v38, v42, v41
	v_fmac_f32_e32 v42, v43, v39
	v_fma_f32 v38, -v38, v42, v41
	v_div_fmas_f32 v38, v38, v39, v42
	v_div_fixup_f32 v44, v38, v37, 1.0
	s_waitcnt vmcnt(15)
	v_lshlrev_b32_e32 v47, 16, v21
	v_and_b32_e32 v48, 0xffff0000, v21
	v_add_f32_e32 v45, 0, v47
	v_add_f32_e32 v46, 0, v48
	v_lshlrev_b32_e32 v47, 16, v22
	v_and_b32_e32 v48, 0xffff0000, v22
	v_add_f32_e32 v45, v45, v47
	v_add_f32_e32 v46, v46, v48
	v_lshlrev_b32_e32 v47, 16, v22
	v_and_b32_e32 v48, 0xffff0000, v22
	v_fma_f32 v45, v44, v45, -v47
	v_fma_f32 v46, v44, v46, -v48
	v_cvt_pk_bf16_f32 v45, v45, v46
	global_store_dword v0, v45, s[36:37]
	s_branch .Lpd_done
.Lpd_hw2:
	s_add_i32 s0, s19, -2
	s_cmp_lt_u32 s0, s18
	s_cbranch_scc0 .Lpd_z2_0
	s_lshl_b32 s0, s0, 10
	s_add_u32 s48, s46, s0
	s_addc_u32 s49, s47, 0
	global_load_dword v6, v0, s[48:49]
	s_branch .Lpd_n2_0

.Lpd_n2_0:
	s_add_i32 s0, s19, -1
	s_cmp_lt_u32 s0, s18
	s_cbranch_scc0 .Lpd_z2_1
	s_lshl_b32 s0, s0, 10
	s_add_u32 s48, s46, s0
	s_addc_u32 s49, s47, 0
	global_load_dword v7, v0, s[48:49]
	s_branch .Lpd_n2_1
.Lpd_z2_1:
	global_load_dword v7, v0, s[50:51]
.Lpd_n2_1:
	s_lshl_b32 s0, s19, 10
	s_add_u32 s48, s46, s0
	s_addc_u32 s49, s47, 0
	global_load_dword v8, v0, s[48:49]
	s_add_i32 s0, s19, 1
	s_cmp_lt_u32 s0, s18
	s_cbranch_scc0 .Lpd_z2_3
	s_lshl_b32 s0, s0, 10
	s_add_u32 s48, s46, s0
	s_addc_u32 s49, s47, 0
	global_load_dword v9, v0, s[48:49]
	s_branch .Lpd_n2_3

.Lpd_n2_3:
	s_add_i32 s0, s19, 2
	s_cmp_lt_u32 s0, s18
	s_cbranch_scc0 .Lpd_z2_4
	s_lshl_b32 s0, s0, 10
	s_add_u32 s48, s46, s0
	s_addc_u32 s49, s47, 0
	global_load_dword v10, v0, s[48:49]
	s_branch .Lpd_n2_4

.Lpd_n2_4:
	s_add_i32 s0, s19, 3
	s_cmp_lt_u32 s0, s18
	s_cbranch_scc0 .Lpd_z2_5
	s_lshl_b32 s0, s0, 10
	s_add_u32 s48, s46, s0
	s_addc_u32 s49, s47, 0
	global_load_dword v11, v0, s[48:49]
	s_branch .Lpd_n2_5

.Lpd_n2_5:
	s_add_i32 s0, s19, 4
	s_cmp_lt_u32 s0, s18
	s_cbranch_scc0 .Lpd_z2_6
	s_lshl_b32 s0, s0, 10
	s_add_u32 s48, s46, s0
	s_addc_u32 s49, s47, 0
	global_load_dword v12, v0, s[48:49]
	s_branch .Lpd_n2_6

.Lpd_n2_6:
	s_add_i32 s0, s19, 5
	s_cmp_lt_u32 s0, s18
	s_cbranch_scc0 .Lpd_z2_7
	s_lshl_b32 s0, s0, 10
	s_add_u32 s48, s46, s0
	s_addc_u32 s49, s47, 0
	global_load_dword v13, v0, s[48:49]
	s_branch .Lpd_n2_7

.Lpd_n2_7:
	s_add_i32 s0, s19, 6
	s_cmp_lt_u32 s0, s18
	s_cbranch_scc0 .Lpd_z2_8
	s_lshl_b32 s0, s0, 10
	s_add_u32 s48, s46, s0
	s_addc_u32 s49, s47, 0
	global_load_dword v14, v0, s[48:49]
	s_branch .Lpd_n2_8

.Lpd_n2_8:
	s_add_i32 s0, s19, 7
	s_cmp_lt_u32 s0, s18
	s_cbranch_scc0 .Lpd_z2_9
	s_lshl_b32 s0, s0, 10
	s_add_u32 s48, s46, s0
	s_addc_u32 s49, s47, 0
	global_load_dword v15, v0, s[48:49]
	s_branch .Lpd_n2_9

.Lpd_n2_9:
	s_add_i32 s0, s19, 8
	s_cmp_lt_u32 s0, s18
	s_cbranch_scc0 .Lpd_z2_10
	s_lshl_b32 s0, s0, 10
	s_add_u32 s48, s46, s0
	s_addc_u32 s49, s47, 0
	global_load_dword v16, v0, s[48:49]
	s_branch .Lpd_n2_10

.Lpd_n2_10:
	s_add_i32 s0, s19, 9
	s_cmp_lt_u32 s0, s18
	s_cbranch_scc0 .Lpd_z2_11
	s_lshl_b32 s0, s0, 10
	s_add_u32 s48, s46, s0
	s_addc_u32 s49, s47, 0
	global_load_dword v17, v0, s[48:49]
	s_branch .Lpd_n2_11

.Lpd_n2_11:
	s_add_i32 s0, s19, 10
	s_cmp_lt_u32 s0, s18
	s_cbranch_scc0 .Lpd_z2_12
	s_lshl_b32 s0, s0, 10
	s_add_u32 s48, s46, s0
	s_addc_u32 s49, s47, 0
	global_load_dword v18, v0, s[48:49]
	s_branch .Lpd_n2_12

.Lpd_n2_12:
	s_add_i32 s0, s19, 11
	s_cmp_lt_u32 s0, s18
	s_cbranch_scc0 .Lpd_z2_13
	s_lshl_b32 s0, s0, 10
	s_add_u32 s48, s46, s0
	s_addc_u32 s49, s47, 0
	global_load_dword v19, v0, s[48:49]
	s_branch .Lpd_n2_13

.Lpd_n2_13:
	s_add_i32 s0, s19, 12
	s_cmp_lt_u32 s0, s18
	s_cbranch_scc0 .Lpd_z2_14
	s_lshl_b32 s0, s0, 10
	s_add_u32 s48, s46, s0
	s_addc_u32 s49, s47, 0
	global_load_dword v20, v0, s[48:49]
	s_branch .Lpd_n2_14

.Lpd_n2_14:
	s_add_i32 s0, s19, 13
	s_cmp_lt_u32 s0, s18
	s_cbranch_scc0 .Lpd_z2_15
	s_lshl_b32 s0, s0, 10
	s_add_u32 s48, s46, s0
	s_addc_u32 s49, s47, 0
	global_load_dword v21, v0, s[48:49]
	s_branch .Lpd_n2_15

.Lpd_n2_15:
	s_add_i32 s0, s19, 14
	s_cmp_lt_u32 s0, s18
	s_cbranch_scc0 .Lpd_z2_16
	s_lshl_b32 s0, s0, 10
	s_add_u32 s48, s46, s0
	s_addc_u32 s49, s47, 0
	global_load_dword v22, v0, s[48:49]
	s_branch .Lpd_n2_16

.Lpd_n2_16:
	s_add_i32 s0, s19, 15
	s_cmp_lt_u32 s0, s18
	s_cbranch_scc0 .Lpd_z2_17
	s_lshl_b32 s0, s0, 10
	s_add_u32 s48, s46, s0
	s_addc_u32 s49, s47, 0
	global_load_dword v23, v0, s[48:49]
	s_branch .Lpd_n2_17
.Lpd_z2_17:
	global_load_dword v23, v0, s[50:51]
.Lpd_n2_17:
	s_add_i32 s0, s19, 16
	s_cmp_lt_u32 s0, s18
	s_cbranch_scc0 .Lpd_z2_18
	s_lshl_b32 s0, s0, 10
	s_add_u32 s48, s46, s0
	s_addc_u32 s49, s47, 0
	global_load_dword v24, v0, s[48:49]
	s_branch .Lpd_n2_18
.Lpd_z2_18:
	global_load_dword v24, v0, s[50:51]
.Lpd_n2_18:
	s_add_i32 s0, s19, 2
	s_min_u32 s0, s0, s18
	s_add_i32 s1, s19, -2
	s_max_i32 s1, s1, 0
	s_sub_i32 s0, s0, s1
	v_cvt_f32_i32_e32 v37, s0
	v_div_scale_f32 v38, s[0:1], v37, v37, 1.0
	v_rcp_f32_e32 v39, v38
	v_div_scale_f32 v41, vcc, 1.0, v37, 1.0
	v_fma_f32 v40, -v38, v39, 1.0
	v_fmac_f32_e32 v39, v40, v39
	v_mul_f32_e32 v42, v41, v39
	v_fma_f32 v43, -v38, v42, v41
	v_fmac_f32_e32 v42, v43, v39
	v_fma_f32 v38, -v38, v42, v41
	v_div_fmas_f32 v38, v38, v39, v42
	v_div_fixup_f32 v44, v38, v37, 1.0
	s_waitcnt vmcnt(15)
	v_lshlrev_b32_e32 v47, 16, v6
	v_and_b32_e32 v48, 0xffff0000, v6
	v_add_f32_e32 v45, 0, v47
	v_add_f32_e32 v46, 0, v48
	v_lshlrev_b32_e32 v47, 16, v7
	v_and_b32_e32 v48, 0xffff0000, v7
	v_add_f32_e32 v45, v45, v47
	v_add_f32_e32 v46, v46, v48
	v_lshlrev_b32_e32 v47, 16, v8
	v_and_b32_e32 v48, 0xffff0000, v8
	v_add_f32_e32 v45, v45, v47
	v_add_f32_e32 v46, v46, v48
	v_lshlrev_b32_e32 v47, 16, v9
	v_and_b32_e32 v48, 0xffff0000, v9
	v_add_f32_e32 v45, v45, v47
	v_add_f32_e32 v46, v46, v48
	v_lshlrev_b32_e32 v47, 16, v8
	v_and_b32_e32 v48, 0xffff0000, v8
	v_fma_f32 v45, v44, v45, -v47
	v_fma_f32 v46, v44, v46, -v48
	v_cvt_pk_bf16_f32 v45, v45, v46
	global_store_dword v0, v45, s[36:37]
	s_add_u32 s36, s36, 0x400
	s_addc_u32 s37, s37, 0
	s_add_i32 s0, s19, 3
	s_min_u32 s0, s0, s18
	s_add_i32 s1, s19, -1
	s_max_i32 s1, s1, 0
	s_sub_i32 s0, s0, s1
	v_cvt_f32_i32_e32 v37, s0
	v_div_scale_f32 v38, s[0:1], v37, v37, 1.0
	v_rcp_f32_e32 v39, v38
	v_div_scale_f32 v41, vcc, 1.0, v37, 1.0
	v_fma_f32 v40, -v38, v39, 1.0
	v_fmac_f32_e32 v39, v40, v39
	v_mul_f32_e32 v42, v41, v39
	v_fma_f32 v43, -v38, v42, v41
	v_fmac_f32_e32 v42, v43, v39
	v_fma_f32 v38, -v38, v42, v41
	v_div_fmas_f32 v38, v38, v39, v42
	v_div_fixup_f32 v44, v38, v37, 1.0
	s_waitcnt vmcnt(15)
	v_lshlrev_b32_e32 v47, 16, v7
	v_and_b32_e32 v48, 0xffff0000, v7
	v_add_f32_e32 v45, 0, v47
	v_add_f32_e32 v46, 0, v48
	v_lshlrev_b32_e32 v47, 16, v8
	v_and_b32_e32 v48, 0xffff0000, v8
	v_add_f32_e32 v45, v45, v47
	v_add_f32_e32 v46, v46, v48
	v_lshlrev_b32_e32 v47, 16, v9
	v_and_b32_e32 v48, 0xffff0000, v9
	v_add_f32_e32 v45, v45, v47
	v_add_f32_e32 v46, v46, v48
	v_lshlrev_b32_e32 v47, 16, v10
	v_and_b32_e32 v48, 0xffff0000, v10
	v_add_f32_e32 v45, v45, v47
	v_add_f32_e32 v46, v46, v48
	v_lshlrev_b32_e32 v47, 16, v9
	v_and_b32_e32 v48, 0xffff0000, v9
	v_fma_f32 v45, v44, v45, -v47
	v_fma_f32 v46, v44, v46, -v48
	v_cvt_pk_bf16_f32 v45, v45, v46
	global_store_dword v0, v45, s[36:37]
	s_add_u32 s36, s36, 0x400
	s_addc_u32 s37, s37, 0
	s_add_i32 s0, s19, 4
	s_min_u32 s0, s0, s18
	s_add_i32 s1, s19, 0
	s_max_i32 s1, s1, 0
	s_sub_i32 s0, s0, s1
	v_cvt_f32_i32_e32 v37, s0
	v_div_scale_f32 v38, s[0:1], v37, v37, 1.0
	v_rcp_f32_e32 v39, v38
	v_div_scale_f32 v41, vcc, 1.0, v37, 1.0
	v_fma_f32 v40, -v38, v39, 1.0
	v_fmac_f32_e32 v39, v40, v39
	v_mul_f32_e32 v42, v41, v39
	v_fma_f32 v43, -v38, v42, v41
	v_fmac_f32_e32 v42, v43, v39
	v_fma_f32 v38, -v38, v42, v41
	v_div_fmas_f32 v38, v38, v39, v42
	v_div_fixup_f32 v44, v38, v37, 1.0
	s_waitcnt vmcnt(15)
	v_lshlrev_b32_e32 v47, 16, v8
	v_and_b32_e32 v48, 0xffff0000, v8
	v_add_f32_e32 v45, 0, v47
	v_add_f32_e32 v46, 0, v48
	v_lshlrev_b32_e32 v47, 16, v9
	v_and_b32_e32 v48, 0xffff0000, v9
	v_add_f32_e32 v45, v45, v47
	v_add_f32_e32 v46, v46, v48
	v_lshlrev_b32_e32 v47, 16, v10
	v_and_b32_e32 v48, 0xffff0000, v10
	v_add_f32_e32 v45, v45, v47
	v_add_f32_e32 v46, v46, v48
	v_lshlrev_b32_e32 v47, 16, v11
	v_and_b32_e32 v48, 0xffff0000, v11
	v_add_f32_e32 v45, v45, v47
	v_add_f32_e32 v46, v46, v48
	v_lshlrev_b32_e32 v47, 16, v10
	v_and_b32_e32 v48, 0xffff0000, v10
	v_fma_f32 v45, v44, v45, -v47
	v_fma_f32 v46, v44, v46, -v48
	v_cvt_pk_bf16_f32 v45, v45, v46
	global_store_dword v0, v45, s[36:37]
	s_add_u32 s36, s36, 0x400
	s_addc_u32 s37, s37, 0
	s_add_i32 s0, s19, 5
	s_min_u32 s0, s0, s18
	s_add_i32 s1, s19, 1
	s_max_i32 s1, s1, 0
	s_sub_i32 s0, s0, s1
	v_cvt_f32_i32_e32 v37, s0
	v_div_scale_f32 v38, s[0:1], v37, v37, 1.0
	v_rcp_f32_e32 v39, v38
	v_div_scale_f32 v41, vcc, 1.0, v37, 1.0
	v_fma_f32 v40, -v38, v39, 1.0
	v_fmac_f32_e32 v39, v40, v39
	v_mul_f32_e32 v42, v41, v39
	v_fma_f32 v43, -v38, v42, v41
	v_fmac_f32_e32 v42, v43, v39
	v_fma_f32 v38, -v38, v42, v41
	v_div_fmas_f32 v38, v38, v39, v42
	v_div_fixup_f32 v44, v38, v37, 1.0
	s_waitcnt vmcnt(15)
	v_lshlrev_b32_e32 v47, 16, v9
	v_and_b32_e32 v48, 0xffff0000, v9
	v_add_f32_e32 v45, 0, v47
	v_add_f32_e32 v46, 0, v48
	v_lshlrev_b32_e32 v47, 16, v10
	v_and_b32_e32 v48, 0xffff0000, v10
	v_add_f32_e32 v45, v45, v47
	v_add_f32_e32 v46, v46, v48
	v_lshlrev_b32_e32 v47, 16, v11
	v_and_b32_e32 v48, 0xffff0000, v11
	v_add_f32_e32 v45, v45, v47
	v_add_f32_e32 v46, v46, v48
	v_lshlrev_b32_e32 v47, 16, v12
	v_and_b32_e32 v48, 0xffff0000, v12
	v_add_f32_e32 v45, v45, v47
	v_add_f32_e32 v46, v46, v48
	v_lshlrev_b32_e32 v47, 16, v11
	v_and_b32_e32 v48, 0xffff0000, v11
	v_fma_f32 v45, v44, v45, -v47
	v_fma_f32 v46, v44, v46, -v48
	v_cvt_pk_bf16_f32 v45, v45, v46
	global_store_dword v0, v45, s[36:37]
	s_add_u32 s36, s36, 0x400
	s_addc_u32 s37, s37, 0
	s_add_i32 s0, s19, 6
	s_min_u32 s0, s0, s18
	s_add_i32 s1, s19, 2
	s_max_i32 s1, s1, 0
	s_sub_i32 s0, s0, s1
	v_cvt_f32_i32_e32 v37, s0
	v_div_scale_f32 v38, s[0:1], v37, v37, 1.0
	v_rcp_f32_e32 v39, v38
	v_div_scale_f32 v41, vcc, 1.0, v37, 1.0
	v_fma_f32 v40, -v38, v39, 1.0
	v_fmac_f32_e32 v39, v40, v39
	v_mul_f32_e32 v42, v41, v39
	v_fma_f32 v43, -v38, v42, v41
	v_fmac_f32_e32 v42, v43, v39
	v_fma_f32 v38, -v38, v42, v41
	v_div_fmas_f32 v38, v38, v39, v42
	v_div_fixup_f32 v44, v38, v37, 1.0
	s_waitcnt vmcnt(15)
	v_lshlrev_b32_e32 v47, 16, v10
	v_and_b32_e32 v48, 0xffff0000, v10
	v_add_f32_e32 v45, 0, v47
	v_add_f32_e32 v46, 0, v48
	v_lshlrev_b32_e32 v47, 16, v11
	v_and_b32_e32 v48, 0xffff0000, v11
	v_add_f32_e32 v45, v45, v47
	v_add_f32_e32 v46, v46, v48
	v_lshlrev_b32_e32 v47, 16, v12
	v_and_b32_e32 v48, 0xffff0000, v12
	v_add_f32_e32 v45, v45, v47
	v_add_f32_e32 v46, v46, v48
	v_lshlrev_b32_e32 v47, 16, v13
	v_and_b32_e32 v48, 0xffff0000, v13
	v_add_f32_e32 v45, v45, v47
	v_add_f32_e32 v46, v46, v48
	v_lshlrev_b32_e32 v47, 16, v12
	v_and_b32_e32 v48, 0xffff0000, v12
	v_fma_f32 v45, v44, v45, -v47
	v_fma_f32 v46, v44, v46, -v48
	v_cvt_pk_bf16_f32 v45, v45, v46
	global_store_dword v0, v45, s[36:37]
	s_add_u32 s36, s36, 0x400
	s_addc_u32 s37, s37, 0
	s_add_i32 s0, s19, 7
	s_min_u32 s0, s0, s18
	s_add_i32 s1, s19, 3
	s_max_i32 s1, s1, 0
	s_sub_i32 s0, s0, s1
	v_cvt_f32_i32_e32 v37, s0
	v_div_scale_f32 v38, s[0:1], v37, v37, 1.0
	v_rcp_f32_e32 v39, v38
	v_div_scale_f32 v41, vcc, 1.0, v37, 1.0
	v_fma_f32 v40, -v38, v39, 1.0
	v_fmac_f32_e32 v39, v40, v39
	v_mul_f32_e32 v42, v41, v39
	v_fma_f32 v43, -v38, v42, v41
	v_fmac_f32_e32 v42, v43, v39
	v_fma_f32 v38, -v38, v42, v41
	v_div_fmas_f32 v38, v38, v39, v42
	v_div_fixup_f32 v44, v38, v37, 1.0
	s_waitcnt vmcnt(15)
	v_lshlrev_b32_e32 v47, 16, v11
	v_and_b32_e32 v48, 0xffff0000, v11
	v_add_f32_e32 v45, 0, v47
	v_add_f32_e32 v46, 0, v48
	v_lshlrev_b32_e32 v47, 16, v12
	v_and_b32_e32 v48, 0xffff0000, v12
	v_add_f32_e32 v45, v45, v47
	v_add_f32_e32 v46, v46, v48
	v_lshlrev_b32_e32 v47, 16, v13
	v_and_b32_e32 v48, 0xffff0000, v13
	v_add_f32_e32 v45, v45, v47
	v_add_f32_e32 v46, v46, v48
	v_lshlrev_b32_e32 v47, 16, v14
	v_and_b32_e32 v48, 0xffff0000, v14
	v_add_f32_e32 v45, v45, v47
	v_add_f32_e32 v46, v46, v48
	v_lshlrev_b32_e32 v47, 16, v13
	v_and_b32_e32 v48, 0xffff0000, v13
	v_fma_f32 v45, v44, v45, -v47
	v_fma_f32 v46, v44, v46, -v48
	v_cvt_pk_bf16_f32 v45, v45, v46
	global_store_dword v0, v45, s[36:37]
	s_add_u32 s36, s36, 0x400
	s_addc_u32 s37, s37, 0
	s_add_i32 s0, s19, 8
	s_min_u32 s0, s0, s18
	s_add_i32 s1, s19, 4
	s_max_i32 s1, s1, 0
	s_sub_i32 s0, s0, s1
	v_cvt_f32_i32_e32 v37, s0
	v_div_scale_f32 v38, s[0:1], v37, v37, 1.0
	v_rcp_f32_e32 v39, v38
	v_div_scale_f32 v41, vcc, 1.0, v37, 1.0
	v_fma_f32 v40, -v38, v39, 1.0
	v_fmac_f32_e32 v39, v40, v39
	v_mul_f32_e32 v42, v41, v39
	v_fma_f32 v43, -v38, v42, v41
	v_fmac_f32_e32 v42, v43, v39
	v_fma_f32 v38, -v38, v42, v41
	v_div_fmas_f32 v38, v38, v39, v42
	v_div_fixup_f32 v44, v38, v37, 1.0
	s_waitcnt vmcnt(15)
	v_lshlrev_b32_e32 v47, 16, v12
	v_and_b32_e32 v48, 0xffff0000, v12
	v_add_f32_e32 v45, 0, v47
	v_add_f32_e32 v46, 0, v48
	v_lshlrev_b32_e32 v47, 16, v13
	v_and_b32_e32 v48, 0xffff0000, v13
	v_add_f32_e32 v45, v45, v47
	v_add_f32_e32 v46, v46, v48
	v_lshlrev_b32_e32 v47, 16, v14
	v_and_b32_e32 v48, 0xffff0000, v14
	v_add_f32_e32 v45, v45, v47
	v_add_f32_e32 v46, v46, v48
	v_lshlrev_b32_e32 v47, 16, v15
	v_and_b32_e32 v48, 0xffff0000, v15
	v_add_f32_e32 v45, v45, v47
	v_add_f32_e32 v46, v46, v48
	v_lshlrev_b32_e32 v47, 16, v14
	v_and_b32_e32 v48, 0xffff0000, v14
	v_fma_f32 v45, v44, v45, -v47
	v_fma_f32 v46, v44, v46, -v48
	v_cvt_pk_bf16_f32 v45, v45, v46
	global_store_dword v0, v45, s[36:37]
	s_add_u32 s36, s36, 0x400
	s_addc_u32 s37, s37, 0
	s_add_i32 s0, s19, 9
	s_min_u32 s0, s0, s18
	s_add_i32 s1, s19, 5
	s_max_i32 s1, s1, 0
	s_sub_i32 s0, s0, s1
	v_cvt_f32_i32_e32 v37, s0
	v_div_scale_f32 v38, s[0:1], v37, v37, 1.0
	v_rcp_f32_e32 v39, v38
	v_div_scale_f32 v41, vcc, 1.0, v37, 1.0
	v_fma_f32 v40, -v38, v39, 1.0
	v_fmac_f32_e32 v39, v40, v39
	v_mul_f32_e32 v42, v41, v39
	v_fma_f32 v43, -v38, v42, v41
	v_fmac_f32_e32 v42, v43, v39
	v_fma_f32 v38, -v38, v42, v41
	v_div_fmas_f32 v38, v38, v39, v42
	v_div_fixup_f32 v44, v38, v37, 1.0
	s_waitcnt vmcnt(15)
	v_lshlrev_b32_e32 v47, 16, v13
	v_and_b32_e32 v48, 0xffff0000, v13
	v_add_f32_e32 v45, 0, v47
	v_add_f32_e32 v46, 0, v48
	v_lshlrev_b32_e32 v47, 16, v14
	v_and_b32_e32 v48, 0xffff0000, v14
	v_add_f32_e32 v45, v45, v47
	v_add_f32_e32 v46, v46, v48
	v_lshlrev_b32_e32 v47, 16, v15
	v_and_b32_e32 v48, 0xffff0000, v15
	v_add_f32_e32 v45, v45, v47
	v_add_f32_e32 v46, v46, v48
	v_lshlrev_b32_e32 v47, 16, v16
	v_and_b32_e32 v48, 0xffff0000, v16
	v_add_f32_e32 v45, v45, v47
	v_add_f32_e32 v46, v46, v48
	v_lshlrev_b32_e32 v47, 16, v15
	v_and_b32_e32 v48, 0xffff0000, v15
	v_fma_f32 v45, v44, v45, -v47
	v_fma_f32 v46, v44, v46, -v48
	v_cvt_pk_bf16_f32 v45, v45, v46
	global_store_dword v0, v45, s[36:37]
	s_add_u32 s36, s36, 0x400
	s_addc_u32 s37, s37, 0
	s_add_i32 s0, s19, 10
	s_min_u32 s0, s0, s18
	s_add_i32 s1, s19, 6
	s_max_i32 s1, s1, 0
	s_sub_i32 s0, s0, s1
	v_cvt_f32_i32_e32 v37, s0
	v_div_scale_f32 v38, s[0:1], v37, v37, 1.0
	v_rcp_f32_e32 v39, v38
	v_div_scale_f32 v41, vcc, 1.0, v37, 1.0
	v_fma_f32 v40, -v38, v39, 1.0
	v_fmac_f32_e32 v39, v40, v39
	v_mul_f32_e32 v42, v41, v39
	v_fma_f32 v43, -v38, v42, v41
	v_fmac_f32_e32 v42, v43, v39
	v_fma_f32 v38, -v38, v42, v41
	v_div_fmas_f32 v38, v38, v39, v42
	v_div_fixup_f32 v44, v38, v37, 1.0
	s_waitcnt vmcnt(15)
	v_lshlrev_b32_e32 v47, 16, v14
	v_and_b32_e32 v48, 0xffff0000, v14
	v_add_f32_e32 v45, 0, v47
	v_add_f32_e32 v46, 0, v48
	v_lshlrev_b32_e32 v47, 16, v15
	v_and_b32_e32 v48, 0xffff0000, v15
	v_add_f32_e32 v45, v45, v47
	v_add_f32_e32 v46, v46, v48
	v_lshlrev_b32_e32 v47, 16, v16
	v_and_b32_e32 v48, 0xffff0000, v16
	v_add_f32_e32 v45, v45, v47
	v_add_f32_e32 v46, v46, v48
	v_lshlrev_b32_e32 v47, 16, v17
	v_and_b32_e32 v48, 0xffff0000, v17
	v_add_f32_e32 v45, v45, v47
	v_add_f32_e32 v46, v46, v48
	v_lshlrev_b32_e32 v47, 16, v16
	v_and_b32_e32 v48, 0xffff0000, v16
	v_fma_f32 v45, v44, v45, -v47
	v_fma_f32 v46, v44, v46, -v48
	v_cvt_pk_bf16_f32 v45, v45, v46
	global_store_dword v0, v45, s[36:37]
	s_add_u32 s36, s36, 0x400
	s_addc_u32 s37, s37, 0
	s_add_i32 s0, s19, 11
	s_min_u32 s0, s0, s18
	s_add_i32 s1, s19, 7
	s_max_i32 s1, s1, 0
	s_sub_i32 s0, s0, s1
	v_cvt_f32_i32_e32 v37, s0
	v_div_scale_f32 v38, s[0:1], v37, v37, 1.0
	v_rcp_f32_e32 v39, v38
	v_div_scale_f32 v41, vcc, 1.0, v37, 1.0
	v_fma_f32 v40, -v38, v39, 1.0
	v_fmac_f32_e32 v39, v40, v39
	v_mul_f32_e32 v42, v41, v39
	v_fma_f32 v43, -v38, v42, v41
	v_fmac_f32_e32 v42, v43, v39
	v_fma_f32 v38, -v38, v42, v41
	v_div_fmas_f32 v38, v38, v39, v42
	v_div_fixup_f32 v44, v38, v37, 1.0
	s_waitcnt vmcnt(15)
	v_lshlrev_b32_e32 v47, 16, v15
	v_and_b32_e32 v48, 0xffff0000, v15
	v_add_f32_e32 v45, 0, v47
	v_add_f32_e32 v46, 0, v48
	v_lshlrev_b32_e32 v47, 16, v16
	v_and_b32_e32 v48, 0xffff0000, v16
	v_add_f32_e32 v45, v45, v47
	v_add_f32_e32 v46, v46, v48
	v_lshlrev_b32_e32 v47, 16, v17
	v_and_b32_e32 v48, 0xffff0000, v17
	v_add_f32_e32 v45, v45, v47
	v_add_f32_e32 v46, v46, v48
	v_lshlrev_b32_e32 v47, 16, v18
	v_and_b32_e32 v48, 0xffff0000, v18
	v_add_f32_e32 v45, v45, v47
	v_add_f32_e32 v46, v46, v48
	v_lshlrev_b32_e32 v47, 16, v17
	v_and_b32_e32 v48, 0xffff0000, v17
	v_fma_f32 v45, v44, v45, -v47
	v_fma_f32 v46, v44, v46, -v48
	v_cvt_pk_bf16_f32 v45, v45, v46
	global_store_dword v0, v45, s[36:37]
	s_add_u32 s36, s36, 0x400
	s_addc_u32 s37, s37, 0
	s_add_i32 s0, s19, 12
	s_min_u32 s0, s0, s18
	s_add_i32 s1, s19, 8
	s_max_i32 s1, s1, 0
	s_sub_i32 s0, s0, s1
	v_cvt_f32_i32_e32 v37, s0
	v_div_scale_f32 v38, s[0:1], v37, v37, 1.0
	v_rcp_f32_e32 v39, v38
	v_div_scale_f32 v41, vcc, 1.0, v37, 1.0
	v_fma_f32 v40, -v38, v39, 1.0
	v_fmac_f32_e32 v39, v40, v39
	v_mul_f32_e32 v42, v41, v39
	v_fma_f32 v43, -v38, v42, v41
	v_fmac_f32_e32 v42, v43, v39
	v_fma_f32 v38, -v38, v42, v41
	v_div_fmas_f32 v38, v38, v39, v42
	v_div_fixup_f32 v44, v38, v37, 1.0
	s_waitcnt vmcnt(15)
	v_lshlrev_b32_e32 v47, 16, v16
	v_and_b32_e32 v48, 0xffff0000, v16
	v_add_f32_e32 v45, 0, v47
	v_add_f32_e32 v46, 0, v48
	v_lshlrev_b32_e32 v47, 16, v17
	v_and_b32_e32 v48, 0xffff0000, v17
	v_add_f32_e32 v45, v45, v47
	v_add_f32_e32 v46, v46, v48
	v_lshlrev_b32_e32 v47, 16, v18
	v_and_b32_e32 v48, 0xffff0000, v18
	v_add_f32_e32 v45, v45, v47
	v_add_f32_e32 v46, v46, v48
	v_lshlrev_b32_e32 v47, 16, v19
	v_and_b32_e32 v48, 0xffff0000, v19
	v_add_f32_e32 v45, v45, v47
	v_add_f32_e32 v46, v46, v48
	v_lshlrev_b32_e32 v47, 16, v18
	v_and_b32_e32 v48, 0xffff0000, v18
	v_fma_f32 v45, v44, v45, -v47
	v_fma_f32 v46, v44, v46, -v48
	v_cvt_pk_bf16_f32 v45, v45, v46
	global_store_dword v0, v45, s[36:37]
	s_add_u32 s36, s36, 0x400
	s_addc_u32 s37, s37, 0
	s_add_i32 s0, s19, 13
	s_min_u32 s0, s0, s18
	s_add_i32 s1, s19, 9
	s_max_i32 s1, s1, 0
	s_sub_i32 s0, s0, s1
	v_cvt_f32_i32_e32 v37, s0
	v_div_scale_f32 v38, s[0:1], v37, v37, 1.0
	v_rcp_f32_e32 v39, v38
	v_div_scale_f32 v41, vcc, 1.0, v37, 1.0
	v_fma_f32 v40, -v38, v39, 1.0
	v_fmac_f32_e32 v39, v40, v39
	v_mul_f32_e32 v42, v41, v39
	v_fma_f32 v43, -v38, v42, v41
	v_fmac_f32_e32 v42, v43, v39
	v_fma_f32 v38, -v38, v42, v41
	v_div_fmas_f32 v38, v38, v39, v42
	v_div_fixup_f32 v44, v38, v37, 1.0
	s_waitcnt vmcnt(15)
	v_lshlrev_b32_e32 v47, 16, v17
	v_and_b32_e32 v48, 0xffff0000, v17
	v_add_f32_e32 v45, 0, v47
	v_add_f32_e32 v46, 0, v48
	v_lshlrev_b32_e32 v47, 16, v18
	v_and_b32_e32 v48, 0xffff0000, v18
	v_add_f32_e32 v45, v45, v47
	v_add_f32_e32 v46, v46, v48
	v_lshlrev_b32_e32 v47, 16, v19
	v_and_b32_e32 v48, 0xffff0000, v19
	v_add_f32_e32 v45, v45, v47
	v_add_f32_e32 v46, v46, v48
	v_lshlrev_b32_e32 v47, 16, v20
	v_and_b32_e32 v48, 0xffff0000, v20
	v_add_f32_e32 v45, v45, v47
	v_add_f32_e32 v46, v46, v48
	v_lshlrev_b32_e32 v47, 16, v19
	v_and_b32_e32 v48, 0xffff0000, v19
	v_fma_f32 v45, v44, v45, -v47
	v_fma_f32 v46, v44, v46, -v48
	v_cvt_pk_bf16_f32 v45, v45, v46
	global_store_dword v0, v45, s[36:37]
	s_add_u32 s36, s36, 0x400
	s_addc_u32 s37, s37, 0
	s_add_i32 s0, s19, 14
	s_min_u32 s0, s0, s18
	s_add_i32 s1, s19, 10
	s_max_i32 s1, s1, 0
	s_sub_i32 s0, s0, s1
	v_cvt_f32_i32_e32 v37, s0
	v_div_scale_f32 v38, s[0:1], v37, v37, 1.0
	v_rcp_f32_e32 v39, v38
	v_div_scale_f32 v41, vcc, 1.0, v37, 1.0
	v_fma_f32 v40, -v38, v39, 1.0
	v_fmac_f32_e32 v39, v40, v39
	v_mul_f32_e32 v42, v41, v39
	v_fma_f32 v43, -v38, v42, v41
	v_fmac_f32_e32 v42, v43, v39
	v_fma_f32 v38, -v38, v42, v41
	v_div_fmas_f32 v38, v38, v39, v42
	v_div_fixup_f32 v44, v38, v37, 1.0
	s_waitcnt vmcnt(15)
	v_lshlrev_b32_e32 v47, 16, v18
	v_and_b32_e32 v48, 0xffff0000, v18
	v_add_f32_e32 v45, 0, v47
	v_add_f32_e32 v46, 0, v48
	v_lshlrev_b32_e32 v47, 16, v19
	v_and_b32_e32 v48, 0xffff0000, v19
	v_add_f32_e32 v45, v45, v47
	v_add_f32_e32 v46, v46, v48
	v_lshlrev_b32_e32 v47, 16, v20
	v_and_b32_e32 v48, 0xffff0000, v20
	v_add_f32_e32 v45, v45, v47
	v_add_f32_e32 v46, v46, v48
	v_lshlrev_b32_e32 v47, 16, v21
	v_and_b32_e32 v48, 0xffff0000, v21
	v_add_f32_e32 v45, v45, v47
	v_add_f32_e32 v46, v46, v48
	v_lshlrev_b32_e32 v47, 16, v20
	v_and_b32_e32 v48, 0xffff0000, v20
	v_fma_f32 v45, v44, v45, -v47
	v_fma_f32 v46, v44, v46, -v48
	v_cvt_pk_bf16_f32 v45, v45, v46
	global_store_dword v0, v45, s[36:37]
	s_add_u32 s36, s36, 0x400
	s_addc_u32 s37, s37, 0
	s_add_i32 s0, s19, 15
	s_min_u32 s0, s0, s18
	s_add_i32 s1, s19, 11
	s_max_i32 s1, s1, 0
	s_sub_i32 s0, s0, s1
	v_cvt_f32_i32_e32 v37, s0
	v_div_scale_f32 v38, s[0:1], v37, v37, 1.0
	v_rcp_f32_e32 v39, v38
	v_div_scale_f32 v41, vcc, 1.0, v37, 1.0
	v_fma_f32 v40, -v38, v39, 1.0
	v_fmac_f32_e32 v39, v40, v39
	v_mul_f32_e32 v42, v41, v39
	v_fma_f32 v43, -v38, v42, v41
	v_fmac_f32_e32 v42, v43, v39
	v_fma_f32 v38, -v38, v42, v41
	v_div_fmas_f32 v38, v38, v39, v42
	v_div_fixup_f32 v44, v38, v37, 1.0
	s_waitcnt vmcnt(15)
	v_lshlrev_b32_e32 v47, 16, v19
	v_and_b32_e32 v48, 0xffff0000, v19
	v_add_f32_e32 v45, 0, v47
	v_add_f32_e32 v46, 0, v48
	v_lshlrev_b32_e32 v47, 16, v20
	v_and_b32_e32 v48, 0xffff0000, v20
	v_add_f32_e32 v45, v45, v47
	v_add_f32_e32 v46, v46, v48
	v_lshlrev_b32_e32 v47, 16, v21
	v_and_b32_e32 v48, 0xffff0000, v21
	v_add_f32_e32 v45, v45, v47
	v_add_f32_e32 v46, v46, v48
	v_lshlrev_b32_e32 v47, 16, v22
	v_and_b32_e32 v48, 0xffff0000, v22
	v_add_f32_e32 v45, v45, v47
	v_add_f32_e32 v46, v46, v48
	v_lshlrev_b32_e32 v47, 16, v21
	v_and_b32_e32 v48, 0xffff0000, v21
	v_fma_f32 v45, v44, v45, -v47
	v_fma_f32 v46, v44, v46, -v48
	v_cvt_pk_bf16_f32 v45, v45, v46
	global_store_dword v0, v45, s[36:37]
	s_add_u32 s36, s36, 0x400
	s_addc_u32 s37, s37, 0
	s_add_i32 s0, s19, 16
	s_min_u32 s0, s0, s18
	s_add_i32 s1, s19, 12
	s_max_i32 s1, s1, 0
	s_sub_i32 s0, s0, s1
	v_cvt_f32_i32_e32 v37, s0
	v_div_scale_f32 v38, s[0:1], v37, v37, 1.0
	v_rcp_f32_e32 v39, v38
	v_div_scale_f32 v41, vcc, 1.0, v37, 1.0
	v_fma_f32 v40, -v38, v39, 1.0
	v_fmac_f32_e32 v39, v40, v39
	v_mul_f32_e32 v42, v41, v39
	v_fma_f32 v43, -v38, v42, v41
	v_fmac_f32_e32 v42, v43, v39
	v_fma_f32 v38, -v38, v42, v41
	v_div_fmas_f32 v38, v38, v39, v42
	v_div_fixup_f32 v44, v38, v37, 1.0
	s_waitcnt vmcnt(15)
	v_lshlrev_b32_e32 v47, 16, v20
	v_and_b32_e32 v48, 0xffff0000, v20
	v_add_f32_e32 v45, 0, v47
	v_add_f32_e32 v46, 0, v48
	v_lshlrev_b32_e32 v47, 16, v21
	v_and_b32_e32 v48, 0xffff0000, v21
	v_add_f32_e32 v45, v45, v47
	v_add_f32_e32 v46, v46, v48
	v_lshlrev_b32_e32 v47, 16, v22
	v_and_b32_e32 v48, 0xffff0000, v22
	v_add_f32_e32 v45, v45, v47
	v_add_f32_e32 v46, v46, v48
	v_lshlrev_b32_e32 v47, 16, v23
	v_and_b32_e32 v48, 0xffff0000, v23
	v_add_f32_e32 v45, v45, v47
	v_add_f32_e32 v46, v46, v48
	v_lshlrev_b32_e32 v47, 16, v22
	v_and_b32_e32 v48, 0xffff0000, v22
	v_fma_f32 v45, v44, v45, -v47
	v_fma_f32 v46, v44, v46, -v48
	v_cvt_pk_bf16_f32 v45, v45, v46
	global_store_dword v0, v45, s[36:37]
	s_add_u32 s36, s36, 0x400
	s_addc_u32 s37, s37, 0
	s_add_i32 s0, s19, 17
	s_min_u32 s0, s0, s18
	s_add_i32 s1, s19, 13
	s_max_i32 s1, s1, 0
	s_sub_i32 s0, s0, s1
	v_cvt_f32_i32_e32 v37, s0
	v_div_scale_f32 v38, s[0:1], v37, v37, 1.0
	v_rcp_f32_e32 v39, v38
	v_div_scale_f32 v41, vcc, 1.0, v37, 1.0
	v_fma_f32 v40, -v38, v39, 1.0
	v_fmac_f32_e32 v39, v40, v39
	v_mul_f32_e32 v42, v41, v39
	v_fma_f32 v43, -v38, v42, v41
	v_fmac_f32_e32 v42, v43, v39
	v_fma_f32 v38, -v38, v42, v41
	v_div_fmas_f32 v38, v38, v39, v42
	v_div_fixup_f32 v44, v38, v37, 1.0
	s_waitcnt vmcnt(15)
	v_lshlrev_b32_e32 v47, 16, v21
	v_and_b32_e32 v48, 0xffff0000, v21
	v_add_f32_e32 v45, 0, v47
	v_add_f32_e32 v46, 0, v48
	v_lshlrev_b32_e32 v47, 16, v22
	v_and_b32_e32 v48, 0xffff0000, v22
	v_add_f32_e32 v45, v45, v47
	v_add_f32_e32 v46, v46, v48
	v_lshlrev_b32_e32 v47, 16, v23
	v_and_b32_e32 v48, 0xffff0000, v23
	v_add_f32_e32 v45, v45, v47
	v_add_f32_e32 v46, v46, v48
	v_lshlrev_b32_e32 v47, 16, v24
	v_and_b32_e32 v48, 0xffff0000, v24
	v_add_f32_e32 v45, v45, v47
	v_add_f32_e32 v46, v46, v48
	v_lshlrev_b32_e32 v47, 16, v23
	v_and_b32_e32 v48, 0xffff0000, v23
	v_fma_f32 v45, v44, v45, -v47
	v_fma_f32 v46, v44, v46, -v48
	v_cvt_pk_bf16_f32 v45, v45, v46
	global_store_dword v0, v45, s[36:37]
	s_branch .Lpd_done
.Lpd_hw4:
	s_add_i32 s0, s19, -4
	s_cmp_lt_u32 s0, s18
	s_cbranch_scc0 .Lpd_z4_0
	s_lshl_b32 s0, s0, 10
	s_add_u32 s48, s46, s0
	s_addc_u32 s49, s47, 0
	global_load_dword v6, v0, s[48:49]
	s_branch .Lpd_n4_0

.Lpd_n4_0:
	s_add_i32 s0, s19, -3
	s_cmp_lt_u32 s0, s18
	s_cbranch_scc0 .Lpd_z4_1
	s_lshl_b32 s0, s0, 10
	s_add_u32 s48, s46, s0
	s_addc_u32 s49, s47, 0
	global_load_dword v7, v0, s[48:49]
	s_branch .Lpd_n4_1

.Lpd_n4_1:
	s_add_i32 s0, s19, -2
	s_cmp_lt_u32 s0, s18
	s_cbranch_scc0 .Lpd_z4_2
	s_lshl_b32 s0, s0, 10
	s_add_u32 s48, s46, s0
	s_addc_u32 s49, s47, 0
	global_load_dword v8, v0, s[48:49]
	s_branch .Lpd_n4_2

.Lpd_n4_2:
	s_add_i32 s0, s19, -1
	s_cmp_lt_u32 s0, s18
	s_cbranch_scc0 .Lpd_z4_3
	s_lshl_b32 s0, s0, 10
	s_add_u32 s48, s46, s0
	s_addc_u32 s49, s47, 0
	global_load_dword v9, v0, s[48:49]
	s_branch .Lpd_n4_3

.Lpd_n4_3:
	s_lshl_b32 s0, s19, 10
	s_add_u32 s48, s46, s0
	s_addc_u32 s49, s47, 0
	global_load_dword v10, v0, s[48:49]
	s_add_i32 s0, s19, 1
	s_cmp_lt_u32 s0, s18
	s_cbranch_scc0 .Lpd_z4_5
	s_lshl_b32 s0, s0, 10
	s_add_u32 s48, s46, s0
	s_addc_u32 s49, s47, 0
	global_load_dword v11, v0, s[48:49]
	s_branch .Lpd_n4_5

.Lpd_n4_5:
	s_add_i32 s0, s19, 2
	s_cmp_lt_u32 s0, s18
	s_cbranch_scc0 .Lpd_z4_6
	s_lshl_b32 s0, s0, 10
	s_add_u32 s48, s46, s0
	s_addc_u32 s49, s47, 0
	global_load_dword v12, v0, s[48:49]
	s_branch .Lpd_n4_6

.Lpd_n4_6:
	s_add_i32 s0, s19, 3
	s_cmp_lt_u32 s0, s18
	s_cbranch_scc0 .Lpd_z4_7
	s_lshl_b32 s0, s0, 10
	s_add_u32 s48, s46, s0
	s_addc_u32 s49, s47, 0
	global_load_dword v13, v0, s[48:49]
	s_branch .Lpd_n4_7

.Lpd_n4_7:
	s_add_i32 s0, s19, 4
	s_cmp_lt_u32 s0, s18
	s_cbranch_scc0 .Lpd_z4_8
	s_lshl_b32 s0, s0, 10
	s_add_u32 s48, s46, s0
	s_addc_u32 s49, s47, 0
	global_load_dword v14, v0, s[48:49]
	s_branch .Lpd_n4_8

.Lpd_n4_8:
	s_add_i32 s0, s19, 5
	s_cmp_lt_u32 s0, s18
	s_cbranch_scc0 .Lpd_z4_9
	s_lshl_b32 s0, s0, 10
	s_add_u32 s48, s46, s0
	s_addc_u32 s49, s47, 0
	global_load_dword v15, v0, s[48:49]
	s_branch .Lpd_n4_9

.Lpd_n4_9:
	s_add_i32 s0, s19, 6
	s_cmp_lt_u32 s0, s18
	s_cbranch_scc0 .Lpd_z4_10
	s_lshl_b32 s0, s0, 10
	s_add_u32 s48, s46, s0
	s_addc_u32 s49, s47, 0
	global_load_dword v16, v0, s[48:49]
	s_branch .Lpd_n4_10

.Lpd_n4_10:
	s_add_i32 s0, s19, 7
	s_cmp_lt_u32 s0, s18
	s_cbranch_scc0 .Lpd_z4_11
	s_lshl_b32 s0, s0, 10
	s_add_u32 s48, s46, s0
	s_addc_u32 s49, s47, 0
	global_load_dword v17, v0, s[48:49]
	s_branch .Lpd_n4_11

.Lpd_n4_11:
	s_add_i32 s0, s19, 8
	s_cmp_lt_u32 s0, s18
	s_cbranch_scc0 .Lpd_z4_12
	s_lshl_b32 s0, s0, 10
	s_add_u32 s48, s46, s0
	s_addc_u32 s49, s47, 0
	global_load_dword v18, v0, s[48:49]
	s_branch .Lpd_n4_12

.Lpd_n4_12:
	s_add_i32 s0, s19, 9
	s_cmp_lt_u32 s0, s18
	s_cbranch_scc0 .Lpd_z4_13
	s_lshl_b32 s0, s0, 10
	s_add_u32 s48, s46, s0
	s_addc_u32 s49, s47, 0
	global_load_dword v19, v0, s[48:49]
	s_branch .Lpd_n4_13

.Lpd_n4_13:
	s_add_i32 s0, s19, 10
	s_cmp_lt_u32 s0, s18
	s_cbranch_scc0 .Lpd_z4_14
	s_lshl_b32 s0, s0, 10
	s_add_u32 s48, s46, s0
	s_addc_u32 s49, s47, 0
	global_load_dword v20, v0, s[48:49]
	s_branch .Lpd_n4_14

.Lpd_n4_14:
	s_add_i32 s0, s19, 11
	s_cmp_lt_u32 s0, s18
	s_cbranch_scc0 .Lpd_z4_15
	s_lshl_b32 s0, s0, 10
	s_add_u32 s48, s46, s0
	s_addc_u32 s49, s47, 0
	global_load_dword v21, v0, s[48:49]
	s_branch .Lpd_n4_15

.Lpd_n4_15:
	s_add_i32 s0, s19, 12
	s_cmp_lt_u32 s0, s18
	s_cbranch_scc0 .Lpd_z4_16
	s_lshl_b32 s0, s0, 10
	s_add_u32 s48, s46, s0
	s_addc_u32 s49, s47, 0
	global_load_dword v22, v0, s[48:49]
	s_branch .Lpd_n4_16

.Lpd_n4_16:
	s_add_i32 s0, s19, 13
	s_cmp_lt_u32 s0, s18
	s_cbranch_scc0 .Lpd_z4_17
	s_lshl_b32 s0, s0, 10
	s_add_u32 s48, s46, s0
	s_addc_u32 s49, s47, 0
	global_load_dword v23, v0, s[48:49]
	s_branch .Lpd_n4_17

.Lpd_n4_17:
	s_add_i32 s0, s19, 14
	s_cmp_lt_u32 s0, s18
	s_cbranch_scc0 .Lpd_z4_18
	s_lshl_b32 s0, s0, 10
	s_add_u32 s48, s46, s0
	s_addc_u32 s49, s47, 0
	global_load_dword v24, v0, s[48:49]
	s_branch .Lpd_n4_18

.Lpd_n4_18:
	s_add_i32 s0, s19, 15
	s_cmp_lt_u32 s0, s18
	s_cbranch_scc0 .Lpd_z4_19
	s_lshl_b32 s0, s0, 10
	s_add_u32 s48, s46, s0
	s_addc_u32 s49, s47, 0
	global_load_dword v25, v0, s[48:49]
	s_branch .Lpd_n4_19
.Lpd_z4_19:
	global_load_dword v25, v0, s[50:51]
.Lpd_n4_19:
	s_add_i32 s0, s19, 16
	s_cmp_lt_u32 s0, s18
	s_cbranch_scc0 .Lpd_z4_20
	s_lshl_b32 s0, s0, 10
	s_add_u32 s48, s46, s0
	s_addc_u32 s49, s47, 0
	global_load_dword v26, v0, s[48:49]
	s_branch .Lpd_n4_20
.Lpd_z4_20:
	global_load_dword v26, v0, s[50:51]
.Lpd_n4_20:
	s_add_i32 s0, s19, 17
	s_cmp_lt_u32 s0, s18
	s_cbranch_scc0 .Lpd_z4_21
	s_lshl_b32 s0, s0, 10
	s_add_u32 s48, s46, s0
	s_addc_u32 s49, s47, 0
	global_load_dword v27, v0, s[48:49]
	s_branch .Lpd_n4_21
.Lpd_z4_21:
	global_load_dword v27, v0, s[50:51]
.Lpd_n4_21:
	s_add_i32 s0, s19, 18
	s_cmp_lt_u32 s0, s18
	s_cbranch_scc0 .Lpd_z4_22
	s_lshl_b32 s0, s0, 10
	s_add_u32 s48, s46, s0
	s_addc_u32 s49, s47, 0
	global_load_dword v28, v0, s[48:49]
	s_branch .Lpd_n4_22
.Lpd_z4_22:
	global_load_dword v28, v0, s[50:51]
.Lpd_n4_22:
	s_add_i32 s0, s19, 4
	s_min_u32 s0, s0, s18
	s_add_i32 s1, s19, -4
	s_max_i32 s1, s1, 0
	s_sub_i32 s0, s0, s1
	v_cvt_f32_i32_e32 v37, s0
	v_div_scale_f32 v38, s[0:1], v37, v37, 1.0
	v_rcp_f32_e32 v39, v38
	v_div_scale_f32 v41, vcc, 1.0, v37, 1.0
	v_fma_f32 v40, -v38, v39, 1.0
	v_fmac_f32_e32 v39, v40, v39
	v_mul_f32_e32 v42, v41, v39
	v_fma_f32 v43, -v38, v42, v41
	v_fmac_f32_e32 v42, v43, v39
	v_fma_f32 v38, -v38, v42, v41
	v_div_fmas_f32 v38, v38, v39, v42
	v_div_fixup_f32 v44, v38, v37, 1.0
	s_waitcnt vmcnt(15)
	v_lshlrev_b32_e32 v47, 16, v6
	v_and_b32_e32 v48, 0xffff0000, v6
	v_add_f32_e32 v45, 0, v47
	v_add_f32_e32 v46, 0, v48
	v_lshlrev_b32_e32 v47, 16, v7
	v_and_b32_e32 v48, 0xffff0000, v7
	v_add_f32_e32 v45, v45, v47
	v_add_f32_e32 v46, v46, v48
	v_lshlrev_b32_e32 v47, 16, v8
	v_and_b32_e32 v48, 0xffff0000, v8
	v_add_f32_e32 v45, v45, v47
	v_add_f32_e32 v46, v46, v48
	v_lshlrev_b32_e32 v47, 16, v9
	v_and_b32_e32 v48, 0xffff0000, v9
	v_add_f32_e32 v45, v45, v47
	v_add_f32_e32 v46, v46, v48
	v_lshlrev_b32_e32 v47, 16, v10
	v_and_b32_e32 v48, 0xffff0000, v10
	v_add_f32_e32 v45, v45, v47
	v_add_f32_e32 v46, v46, v48
	v_lshlrev_b32_e32 v47, 16, v11
	v_and_b32_e32 v48, 0xffff0000, v11
	v_add_f32_e32 v45, v45, v47
	v_add_f32_e32 v46, v46, v48
	v_lshlrev_b32_e32 v47, 16, v12
	v_and_b32_e32 v48, 0xffff0000, v12
	v_add_f32_e32 v45, v45, v47
	v_add_f32_e32 v46, v46, v48
	v_lshlrev_b32_e32 v47, 16, v13
	v_and_b32_e32 v48, 0xffff0000, v13
	v_add_f32_e32 v45, v45, v47
	v_add_f32_e32 v46, v46, v48
	v_lshlrev_b32_e32 v47, 16, v10
	v_and_b32_e32 v48, 0xffff0000, v10
	v_fma_f32 v45, v44, v45, -v47
	v_fma_f32 v46, v44, v46, -v48
	v_cvt_pk_bf16_f32 v45, v45, v46
	global_store_dword v0, v45, s[36:37]
	s_add_u32 s36, s36, 0x400
	s_addc_u32 s37, s37, 0
	s_add_i32 s0, s19, 5
	s_min_u32 s0, s0, s18
	s_add_i32 s1, s19, -3
	s_max_i32 s1, s1, 0
	s_sub_i32 s0, s0, s1
	v_cvt_f32_i32_e32 v37, s0
	v_div_scale_f32 v38, s[0:1], v37, v37, 1.0
	v_rcp_f32_e32 v39, v38
	v_div_scale_f32 v41, vcc, 1.0, v37, 1.0
	v_fma_f32 v40, -v38, v39, 1.0
	v_fmac_f32_e32 v39, v40, v39
	v_mul_f32_e32 v42, v41, v39
	v_fma_f32 v43, -v38, v42, v41
	v_fmac_f32_e32 v42, v43, v39
	v_fma_f32 v38, -v38, v42, v41
	v_div_fmas_f32 v38, v38, v39, v42
	v_div_fixup_f32 v44, v38, v37, 1.0
	s_waitcnt vmcnt(15)
	v_lshlrev_b32_e32 v47, 16, v7
	v_and_b32_e32 v48, 0xffff0000, v7
	v_add_f32_e32 v45, 0, v47
	v_add_f32_e32 v46, 0, v48
	v_lshlrev_b32_e32 v47, 16, v8
	v_and_b32_e32 v48, 0xffff0000, v8
	v_add_f32_e32 v45, v45, v47
	v_add_f32_e32 v46, v46, v48
	v_lshlrev_b32_e32 v47, 16, v9
	v_and_b32_e32 v48, 0xffff0000, v9
	v_add_f32_e32 v45, v45, v47
	v_add_f32_e32 v46, v46, v48
	v_lshlrev_b32_e32 v47, 16, v10
	v_and_b32_e32 v48, 0xffff0000, v10
	v_add_f32_e32 v45, v45, v47
	v_add_f32_e32 v46, v46, v48
	v_lshlrev_b32_e32 v47, 16, v11
	v_and_b32_e32 v48, 0xffff0000, v11
	v_add_f32_e32 v45, v45, v47
	v_add_f32_e32 v46, v46, v48
	v_lshlrev_b32_e32 v47, 16, v12
	v_and_b32_e32 v48, 0xffff0000, v12
	v_add_f32_e32 v45, v45, v47
	v_add_f32_e32 v46, v46, v48
	v_lshlrev_b32_e32 v47, 16, v13
	v_and_b32_e32 v48, 0xffff0000, v13
	v_add_f32_e32 v45, v45, v47
	v_add_f32_e32 v46, v46, v48
	v_lshlrev_b32_e32 v47, 16, v14
	v_and_b32_e32 v48, 0xffff0000, v14
	v_add_f32_e32 v45, v45, v47
	v_add_f32_e32 v46, v46, v48
	v_lshlrev_b32_e32 v47, 16, v11
	v_and_b32_e32 v48, 0xffff0000, v11
	v_fma_f32 v45, v44, v45, -v47
	v_fma_f32 v46, v44, v46, -v48
	v_cvt_pk_bf16_f32 v45, v45, v46
	global_store_dword v0, v45, s[36:37]
	s_add_u32 s36, s36, 0x400
	s_addc_u32 s37, s37, 0
	s_add_i32 s0, s19, 6
	s_min_u32 s0, s0, s18
	s_add_i32 s1, s19, -2
	s_max_i32 s1, s1, 0
	s_sub_i32 s0, s0, s1
	v_cvt_f32_i32_e32 v37, s0
	v_div_scale_f32 v38, s[0:1], v37, v37, 1.0
	v_rcp_f32_e32 v39, v38
	v_div_scale_f32 v41, vcc, 1.0, v37, 1.0
	v_fma_f32 v40, -v38, v39, 1.0
	v_fmac_f32_e32 v39, v40, v39
	v_mul_f32_e32 v42, v41, v39
	v_fma_f32 v43, -v38, v42, v41
	v_fmac_f32_e32 v42, v43, v39
	v_fma_f32 v38, -v38, v42, v41
	v_div_fmas_f32 v38, v38, v39, v42
	v_div_fixup_f32 v44, v38, v37, 1.0
	s_waitcnt vmcnt(15)
	v_lshlrev_b32_e32 v47, 16, v8
	v_and_b32_e32 v48, 0xffff0000, v8
	v_add_f32_e32 v45, 0, v47
	v_add_f32_e32 v46, 0, v48
	v_lshlrev_b32_e32 v47, 16, v9
	v_and_b32_e32 v48, 0xffff0000, v9
	v_add_f32_e32 v45, v45, v47
	v_add_f32_e32 v46, v46, v48
	v_lshlrev_b32_e32 v47, 16, v10
	v_and_b32_e32 v48, 0xffff0000, v10
	v_add_f32_e32 v45, v45, v47
	v_add_f32_e32 v46, v46, v48
	v_lshlrev_b32_e32 v47, 16, v11
	v_and_b32_e32 v48, 0xffff0000, v11
	v_add_f32_e32 v45, v45, v47
	v_add_f32_e32 v46, v46, v48
	v_lshlrev_b32_e32 v47, 16, v12
	v_and_b32_e32 v48, 0xffff0000, v12
	v_add_f32_e32 v45, v45, v47
	v_add_f32_e32 v46, v46, v48
	v_lshlrev_b32_e32 v47, 16, v13
	v_and_b32_e32 v48, 0xffff0000, v13
	v_add_f32_e32 v45, v45, v47
	v_add_f32_e32 v46, v46, v48
	v_lshlrev_b32_e32 v47, 16, v14
	v_and_b32_e32 v48, 0xffff0000, v14
	v_add_f32_e32 v45, v45, v47
	v_add_f32_e32 v46, v46, v48
	v_lshlrev_b32_e32 v47, 16, v15
	v_and_b32_e32 v48, 0xffff0000, v15
	v_add_f32_e32 v45, v45, v47
	v_add_f32_e32 v46, v46, v48
	v_lshlrev_b32_e32 v47, 16, v12
	v_and_b32_e32 v48, 0xffff0000, v12
	v_fma_f32 v45, v44, v45, -v47
	v_fma_f32 v46, v44, v46, -v48
	v_cvt_pk_bf16_f32 v45, v45, v46
	global_store_dword v0, v45, s[36:37]
	s_add_u32 s36, s36, 0x400
	s_addc_u32 s37, s37, 0
	s_add_i32 s0, s19, 7
	s_min_u32 s0, s0, s18
	s_add_i32 s1, s19, -1
	s_max_i32 s1, s1, 0
	s_sub_i32 s0, s0, s1
	v_cvt_f32_i32_e32 v37, s0
	v_div_scale_f32 v38, s[0:1], v37, v37, 1.0
	v_rcp_f32_e32 v39, v38
	v_div_scale_f32 v41, vcc, 1.0, v37, 1.0
	v_fma_f32 v40, -v38, v39, 1.0
	v_fmac_f32_e32 v39, v40, v39
	v_mul_f32_e32 v42, v41, v39
	v_fma_f32 v43, -v38, v42, v41
	v_fmac_f32_e32 v42, v43, v39
	v_fma_f32 v38, -v38, v42, v41
	v_div_fmas_f32 v38, v38, v39, v42
	v_div_fixup_f32 v44, v38, v37, 1.0
	s_waitcnt vmcnt(15)
	v_lshlrev_b32_e32 v47, 16, v9
	v_and_b32_e32 v48, 0xffff0000, v9
	v_add_f32_e32 v45, 0, v47
	v_add_f32_e32 v46, 0, v48
	v_lshlrev_b32_e32 v47, 16, v10
	v_and_b32_e32 v48, 0xffff0000, v10
	v_add_f32_e32 v45, v45, v47
	v_add_f32_e32 v46, v46, v48
	v_lshlrev_b32_e32 v47, 16, v11
	v_and_b32_e32 v48, 0xffff0000, v11
	v_add_f32_e32 v45, v45, v47
	v_add_f32_e32 v46, v46, v48
	v_lshlrev_b32_e32 v47, 16, v12
	v_and_b32_e32 v48, 0xffff0000, v12
	v_add_f32_e32 v45, v45, v47
	v_add_f32_e32 v46, v46, v48
	v_lshlrev_b32_e32 v47, 16, v13
	v_and_b32_e32 v48, 0xffff0000, v13
	v_add_f32_e32 v45, v45, v47
	v_add_f32_e32 v46, v46, v48
	v_lshlrev_b32_e32 v47, 16, v14
	v_and_b32_e32 v48, 0xffff0000, v14
	v_add_f32_e32 v45, v45, v47
	v_add_f32_e32 v46, v46, v48
	v_lshlrev_b32_e32 v47, 16, v15
	v_and_b32_e32 v48, 0xffff0000, v15
	v_add_f32_e32 v45, v45, v47
	v_add_f32_e32 v46, v46, v48
	v_lshlrev_b32_e32 v47, 16, v16
	v_and_b32_e32 v48, 0xffff0000, v16
	v_add_f32_e32 v45, v45, v47
	v_add_f32_e32 v46, v46, v48
	v_lshlrev_b32_e32 v47, 16, v13
	v_and_b32_e32 v48, 0xffff0000, v13
	v_fma_f32 v45, v44, v45, -v47
	v_fma_f32 v46, v44, v46, -v48
	v_cvt_pk_bf16_f32 v45, v45, v46
	global_store_dword v0, v45, s[36:37]
	s_add_u32 s36, s36, 0x400
	s_addc_u32 s37, s37, 0
	s_add_i32 s0, s19, 8
	s_min_u32 s0, s0, s18
	s_add_i32 s1, s19, 0
	s_max_i32 s1, s1, 0
	s_sub_i32 s0, s0, s1
	v_cvt_f32_i32_e32 v37, s0
	v_div_scale_f32 v38, s[0:1], v37, v37, 1.0
	v_rcp_f32_e32 v39, v38
	v_div_scale_f32 v41, vcc, 1.0, v37, 1.0
	v_fma_f32 v40, -v38, v39, 1.0
	v_fmac_f32_e32 v39, v40, v39
	v_mul_f32_e32 v42, v41, v39
	v_fma_f32 v43, -v38, v42, v41
	v_fmac_f32_e32 v42, v43, v39
	v_fma_f32 v38, -v38, v42, v41
	v_div_fmas_f32 v38, v38, v39, v42
	v_div_fixup_f32 v44, v38, v37, 1.0
	s_waitcnt vmcnt(15)
	v_lshlrev_b32_e32 v47, 16, v10
	v_and_b32_e32 v48, 0xffff0000, v10
	v_add_f32_e32 v45, 0, v47
	v_add_f32_e32 v46, 0, v48
	v_lshlrev_b32_e32 v47, 16, v11
	v_and_b32_e32 v48, 0xffff0000, v11
	v_add_f32_e32 v45, v45, v47
	v_add_f32_e32 v46, v46, v48
	v_lshlrev_b32_e32 v47, 16, v12
	v_and_b32_e32 v48, 0xffff0000, v12
	v_add_f32_e32 v45, v45, v47
	v_add_f32_e32 v46, v46, v48
	v_lshlrev_b32_e32 v47, 16, v13
	v_and_b32_e32 v48, 0xffff0000, v13
	v_add_f32_e32 v45, v45, v47
	v_add_f32_e32 v46, v46, v48
	v_lshlrev_b32_e32 v47, 16, v14
	v_and_b32_e32 v48, 0xffff0000, v14
	v_add_f32_e32 v45, v45, v47
	v_add_f32_e32 v46, v46, v48
	v_lshlrev_b32_e32 v47, 16, v15
	v_and_b32_e32 v48, 0xffff0000, v15
	v_add_f32_e32 v45, v45, v47
	v_add_f32_e32 v46, v46, v48
	v_lshlrev_b32_e32 v47, 16, v16
	v_and_b32_e32 v48, 0xffff0000, v16
	v_add_f32_e32 v45, v45, v47
	v_add_f32_e32 v46, v46, v48
	v_lshlrev_b32_e32 v47, 16, v17
	v_and_b32_e32 v48, 0xffff0000, v17
	v_add_f32_e32 v45, v45, v47
	v_add_f32_e32 v46, v46, v48
	v_lshlrev_b32_e32 v47, 16, v14
	v_and_b32_e32 v48, 0xffff0000, v14
	v_fma_f32 v45, v44, v45, -v47
	v_fma_f32 v46, v44, v46, -v48
	v_cvt_pk_bf16_f32 v45, v45, v46
	global_store_dword v0, v45, s[36:37]
	s_add_u32 s36, s36, 0x400
	s_addc_u32 s37, s37, 0
	s_add_i32 s0, s19, 9
	s_min_u32 s0, s0, s18
	s_add_i32 s1, s19, 1
	s_max_i32 s1, s1, 0
	s_sub_i32 s0, s0, s1
	v_cvt_f32_i32_e32 v37, s0
	v_div_scale_f32 v38, s[0:1], v37, v37, 1.0
	v_rcp_f32_e32 v39, v38
	v_div_scale_f32 v41, vcc, 1.0, v37, 1.0
	v_fma_f32 v40, -v38, v39, 1.0
	v_fmac_f32_e32 v39, v40, v39
	v_mul_f32_e32 v42, v41, v39
	v_fma_f32 v43, -v38, v42, v41
	v_fmac_f32_e32 v42, v43, v39
	v_fma_f32 v38, -v38, v42, v41
	v_div_fmas_f32 v38, v38, v39, v42
	v_div_fixup_f32 v44, v38, v37, 1.0
	s_waitcnt vmcnt(15)
	v_lshlrev_b32_e32 v47, 16, v11
	v_and_b32_e32 v48, 0xffff0000, v11
	v_add_f32_e32 v45, 0, v47
	v_add_f32_e32 v46, 0, v48
	v_lshlrev_b32_e32 v47, 16, v12
	v_and_b32_e32 v48, 0xffff0000, v12
	v_add_f32_e32 v45, v45, v47
	v_add_f32_e32 v46, v46, v48
	v_lshlrev_b32_e32 v47, 16, v13
	v_and_b32_e32 v48, 0xffff0000, v13
	v_add_f32_e32 v45, v45, v47
	v_add_f32_e32 v46, v46, v48
	v_lshlrev_b32_e32 v47, 16, v14
	v_and_b32_e32 v48, 0xffff0000, v14
	v_add_f32_e32 v45, v45, v47
	v_add_f32_e32 v46, v46, v48
	v_lshlrev_b32_e32 v47, 16, v15
	v_and_b32_e32 v48, 0xffff0000, v15
	v_add_f32_e32 v45, v45, v47
	v_add_f32_e32 v46, v46, v48
	v_lshlrev_b32_e32 v47, 16, v16
	v_and_b32_e32 v48, 0xffff0000, v16
	v_add_f32_e32 v45, v45, v47
	v_add_f32_e32 v46, v46, v48
	v_lshlrev_b32_e32 v47, 16, v17
	v_and_b32_e32 v48, 0xffff0000, v17
	v_add_f32_e32 v45, v45, v47
	v_add_f32_e32 v46, v46, v48
	v_lshlrev_b32_e32 v47, 16, v18
	v_and_b32_e32 v48, 0xffff0000, v18
	v_add_f32_e32 v45, v45, v47
	v_add_f32_e32 v46, v46, v48
	v_lshlrev_b32_e32 v47, 16, v15
	v_and_b32_e32 v48, 0xffff0000, v15
	v_fma_f32 v45, v44, v45, -v47
	v_fma_f32 v46, v44, v46, -v48
	v_cvt_pk_bf16_f32 v45, v45, v46
	global_store_dword v0, v45, s[36:37]
	s_add_u32 s36, s36, 0x400
	s_addc_u32 s37, s37, 0
	s_add_i32 s0, s19, 10
	s_min_u32 s0, s0, s18
	s_add_i32 s1, s19, 2
	s_max_i32 s1, s1, 0
	s_sub_i32 s0, s0, s1
	v_cvt_f32_i32_e32 v37, s0
	v_div_scale_f32 v38, s[0:1], v37, v37, 1.0
	v_rcp_f32_e32 v39, v38
	v_div_scale_f32 v41, vcc, 1.0, v37, 1.0
	v_fma_f32 v40, -v38, v39, 1.0
	v_fmac_f32_e32 v39, v40, v39
	v_mul_f32_e32 v42, v41, v39
	v_fma_f32 v43, -v38, v42, v41
	v_fmac_f32_e32 v42, v43, v39
	v_fma_f32 v38, -v38, v42, v41
	v_div_fmas_f32 v38, v38, v39, v42
	v_div_fixup_f32 v44, v38, v37, 1.0
	s_waitcnt vmcnt(15)
	v_lshlrev_b32_e32 v47, 16, v12
	v_and_b32_e32 v48, 0xffff0000, v12
	v_add_f32_e32 v45, 0, v47
	v_add_f32_e32 v46, 0, v48
	v_lshlrev_b32_e32 v47, 16, v13
	v_and_b32_e32 v48, 0xffff0000, v13
	v_add_f32_e32 v45, v45, v47
	v_add_f32_e32 v46, v46, v48
	v_lshlrev_b32_e32 v47, 16, v14
	v_and_b32_e32 v48, 0xffff0000, v14
	v_add_f32_e32 v45, v45, v47
	v_add_f32_e32 v46, v46, v48
	v_lshlrev_b32_e32 v47, 16, v15
	v_and_b32_e32 v48, 0xffff0000, v15
	v_add_f32_e32 v45, v45, v47
	v_add_f32_e32 v46, v46, v48
	v_lshlrev_b32_e32 v47, 16, v16
	v_and_b32_e32 v48, 0xffff0000, v16
	v_add_f32_e32 v45, v45, v47
	v_add_f32_e32 v46, v46, v48
	v_lshlrev_b32_e32 v47, 16, v17
	v_and_b32_e32 v48, 0xffff0000, v17
	v_add_f32_e32 v45, v45, v47
	v_add_f32_e32 v46, v46, v48
	v_lshlrev_b32_e32 v47, 16, v18
	v_and_b32_e32 v48, 0xffff0000, v18
	v_add_f32_e32 v45, v45, v47
	v_add_f32_e32 v46, v46, v48
	v_lshlrev_b32_e32 v47, 16, v19
	v_and_b32_e32 v48, 0xffff0000, v19
	v_add_f32_e32 v45, v45, v47
	v_add_f32_e32 v46, v46, v48
	v_lshlrev_b32_e32 v47, 16, v16
	v_and_b32_e32 v48, 0xffff0000, v16
	v_fma_f32 v45, v44, v45, -v47
	v_fma_f32 v46, v44, v46, -v48
	v_cvt_pk_bf16_f32 v45, v45, v46
	global_store_dword v0, v45, s[36:37]
	s_add_u32 s36, s36, 0x400
	s_addc_u32 s37, s37, 0
	s_add_i32 s0, s19, 11
	s_min_u32 s0, s0, s18
	s_add_i32 s1, s19, 3
	s_max_i32 s1, s1, 0
	s_sub_i32 s0, s0, s1
	v_cvt_f32_i32_e32 v37, s0
	v_div_scale_f32 v38, s[0:1], v37, v37, 1.0
	v_rcp_f32_e32 v39, v38
	v_div_scale_f32 v41, vcc, 1.0, v37, 1.0
	v_fma_f32 v40, -v38, v39, 1.0
	v_fmac_f32_e32 v39, v40, v39
	v_mul_f32_e32 v42, v41, v39
	v_fma_f32 v43, -v38, v42, v41
	v_fmac_f32_e32 v42, v43, v39
	v_fma_f32 v38, -v38, v42, v41
	v_div_fmas_f32 v38, v38, v39, v42
	v_div_fixup_f32 v44, v38, v37, 1.0
	s_waitcnt vmcnt(15)
	v_lshlrev_b32_e32 v47, 16, v13
	v_and_b32_e32 v48, 0xffff0000, v13
	v_add_f32_e32 v45, 0, v47
	v_add_f32_e32 v46, 0, v48
	v_lshlrev_b32_e32 v47, 16, v14
	v_and_b32_e32 v48, 0xffff0000, v14
	v_add_f32_e32 v45, v45, v47
	v_add_f32_e32 v46, v46, v48
	v_lshlrev_b32_e32 v47, 16, v15
	v_and_b32_e32 v48, 0xffff0000, v15
	v_add_f32_e32 v45, v45, v47
	v_add_f32_e32 v46, v46, v48
	v_lshlrev_b32_e32 v47, 16, v16
	v_and_b32_e32 v48, 0xffff0000, v16
	v_add_f32_e32 v45, v45, v47
	v_add_f32_e32 v46, v46, v48
	v_lshlrev_b32_e32 v47, 16, v17
	v_and_b32_e32 v48, 0xffff0000, v17
	v_add_f32_e32 v45, v45, v47
	v_add_f32_e32 v46, v46, v48
	v_lshlrev_b32_e32 v47, 16, v18
	v_and_b32_e32 v48, 0xffff0000, v18
	v_add_f32_e32 v45, v45, v47
	v_add_f32_e32 v46, v46, v48
	v_lshlrev_b32_e32 v47, 16, v19
	v_and_b32_e32 v48, 0xffff0000, v19
	v_add_f32_e32 v45, v45, v47
	v_add_f32_e32 v46, v46, v48
	v_lshlrev_b32_e32 v47, 16, v20
	v_and_b32_e32 v48, 0xffff0000, v20
	v_add_f32_e32 v45, v45, v47
	v_add_f32_e32 v46, v46, v48
	v_lshlrev_b32_e32 v47, 16, v17
	v_and_b32_e32 v48, 0xffff0000, v17
	v_fma_f32 v45, v44, v45, -v47
	v_fma_f32 v46, v44, v46, -v48
	v_cvt_pk_bf16_f32 v45, v45, v46
	global_store_dword v0, v45, s[36:37]
	s_add_u32 s36, s36, 0x400
	s_addc_u32 s37, s37, 0
	s_add_i32 s0, s19, 12
	s_min_u32 s0, s0, s18
	s_add_i32 s1, s19, 4
	s_max_i32 s1, s1, 0
	s_sub_i32 s0, s0, s1
	v_cvt_f32_i32_e32 v37, s0
	v_div_scale_f32 v38, s[0:1], v37, v37, 1.0
	v_rcp_f32_e32 v39, v38
	v_div_scale_f32 v41, vcc, 1.0, v37, 1.0
	v_fma_f32 v40, -v38, v39, 1.0
	v_fmac_f32_e32 v39, v40, v39
	v_mul_f32_e32 v42, v41, v39
	v_fma_f32 v43, -v38, v42, v41
	v_fmac_f32_e32 v42, v43, v39
	v_fma_f32 v38, -v38, v42, v41
	v_div_fmas_f32 v38, v38, v39, v42
	v_div_fixup_f32 v44, v38, v37, 1.0
	s_waitcnt vmcnt(15)
	v_lshlrev_b32_e32 v47, 16, v14
	v_and_b32_e32 v48, 0xffff0000, v14
	v_add_f32_e32 v45, 0, v47
	v_add_f32_e32 v46, 0, v48
	v_lshlrev_b32_e32 v47, 16, v15
	v_and_b32_e32 v48, 0xffff0000, v15
	v_add_f32_e32 v45, v45, v47
	v_add_f32_e32 v46, v46, v48
	v_lshlrev_b32_e32 v47, 16, v16
	v_and_b32_e32 v48, 0xffff0000, v16
	v_add_f32_e32 v45, v45, v47
	v_add_f32_e32 v46, v46, v48
	v_lshlrev_b32_e32 v47, 16, v17
	v_and_b32_e32 v48, 0xffff0000, v17
	v_add_f32_e32 v45, v45, v47
	v_add_f32_e32 v46, v46, v48
	v_lshlrev_b32_e32 v47, 16, v18
	v_and_b32_e32 v48, 0xffff0000, v18
	v_add_f32_e32 v45, v45, v47
	v_add_f32_e32 v46, v46, v48
	v_lshlrev_b32_e32 v47, 16, v19
	v_and_b32_e32 v48, 0xffff0000, v19
	v_add_f32_e32 v45, v45, v47
	v_add_f32_e32 v46, v46, v48
	v_lshlrev_b32_e32 v47, 16, v20
	v_and_b32_e32 v48, 0xffff0000, v20
	v_add_f32_e32 v45, v45, v47
	v_add_f32_e32 v46, v46, v48
	v_lshlrev_b32_e32 v47, 16, v21
	v_and_b32_e32 v48, 0xffff0000, v21
	v_add_f32_e32 v45, v45, v47
	v_add_f32_e32 v46, v46, v48
	v_lshlrev_b32_e32 v47, 16, v18
	v_and_b32_e32 v48, 0xffff0000, v18
	v_fma_f32 v45, v44, v45, -v47
	v_fma_f32 v46, v44, v46, -v48
	v_cvt_pk_bf16_f32 v45, v45, v46
	global_store_dword v0, v45, s[36:37]
	s_add_u32 s36, s36, 0x400
	s_addc_u32 s37, s37, 0
	s_add_i32 s0, s19, 13
	s_min_u32 s0, s0, s18
	s_add_i32 s1, s19, 5
	s_max_i32 s1, s1, 0
	s_sub_i32 s0, s0, s1
	v_cvt_f32_i32_e32 v37, s0
	v_div_scale_f32 v38, s[0:1], v37, v37, 1.0
	v_rcp_f32_e32 v39, v38
	v_div_scale_f32 v41, vcc, 1.0, v37, 1.0
	v_fma_f32 v40, -v38, v39, 1.0
	v_fmac_f32_e32 v39, v40, v39
	v_mul_f32_e32 v42, v41, v39
	v_fma_f32 v43, -v38, v42, v41
	v_fmac_f32_e32 v42, v43, v39
	v_fma_f32 v38, -v38, v42, v41
	v_div_fmas_f32 v38, v38, v39, v42
	v_div_fixup_f32 v44, v38, v37, 1.0
	s_waitcnt vmcnt(15)
	v_lshlrev_b32_e32 v47, 16, v15
	v_and_b32_e32 v48, 0xffff0000, v15
	v_add_f32_e32 v45, 0, v47
	v_add_f32_e32 v46, 0, v48
	v_lshlrev_b32_e32 v47, 16, v16
	v_and_b32_e32 v48, 0xffff0000, v16
	v_add_f32_e32 v45, v45, v47
	v_add_f32_e32 v46, v46, v48
	v_lshlrev_b32_e32 v47, 16, v17
	v_and_b32_e32 v48, 0xffff0000, v17
	v_add_f32_e32 v45, v45, v47
	v_add_f32_e32 v46, v46, v48
	v_lshlrev_b32_e32 v47, 16, v18
	v_and_b32_e32 v48, 0xffff0000, v18
	v_add_f32_e32 v45, v45, v47
	v_add_f32_e32 v46, v46, v48
	v_lshlrev_b32_e32 v47, 16, v19
	v_and_b32_e32 v48, 0xffff0000, v19
	v_add_f32_e32 v45, v45, v47
	v_add_f32_e32 v46, v46, v48
	v_lshlrev_b32_e32 v47, 16, v20
	v_and_b32_e32 v48, 0xffff0000, v20
	v_add_f32_e32 v45, v45, v47
	v_add_f32_e32 v46, v46, v48
	v_lshlrev_b32_e32 v47, 16, v21
	v_and_b32_e32 v48, 0xffff0000, v21
	v_add_f32_e32 v45, v45, v47
	v_add_f32_e32 v46, v46, v48
	v_lshlrev_b32_e32 v47, 16, v22
	v_and_b32_e32 v48, 0xffff0000, v22
	v_add_f32_e32 v45, v45, v47
	v_add_f32_e32 v46, v46, v48
	v_lshlrev_b32_e32 v47, 16, v19
	v_and_b32_e32 v48, 0xffff0000, v19
	v_fma_f32 v45, v44, v45, -v47
	v_fma_f32 v46, v44, v46, -v48
	v_cvt_pk_bf16_f32 v45, v45, v46
	global_store_dword v0, v45, s[36:37]
	s_add_u32 s36, s36, 0x400
	s_addc_u32 s37, s37, 0
	s_add_i32 s0, s19, 14
	s_min_u32 s0, s0, s18
	s_add_i32 s1, s19, 6
	s_max_i32 s1, s1, 0
	s_sub_i32 s0, s0, s1
	v_cvt_f32_i32_e32 v37, s0
	v_div_scale_f32 v38, s[0:1], v37, v37, 1.0
	v_rcp_f32_e32 v39, v38
	v_div_scale_f32 v41, vcc, 1.0, v37, 1.0
	v_fma_f32 v40, -v38, v39, 1.0
	v_fmac_f32_e32 v39, v40, v39
	v_mul_f32_e32 v42, v41, v39
	v_fma_f32 v43, -v38, v42, v41
	v_fmac_f32_e32 v42, v43, v39
	v_fma_f32 v38, -v38, v42, v41
	v_div_fmas_f32 v38, v38, v39, v42
	v_div_fixup_f32 v44, v38, v37, 1.0
	s_waitcnt vmcnt(15)
	v_lshlrev_b32_e32 v47, 16, v16
	v_and_b32_e32 v48, 0xffff0000, v16
	v_add_f32_e32 v45, 0, v47
	v_add_f32_e32 v46, 0, v48
	v_lshlrev_b32_e32 v47, 16, v17
	v_and_b32_e32 v48, 0xffff0000, v17
	v_add_f32_e32 v45, v45, v47
	v_add_f32_e32 v46, v46, v48
	v_lshlrev_b32_e32 v47, 16, v18
	v_and_b32_e32 v48, 0xffff0000, v18
	v_add_f32_e32 v45, v45, v47
	v_add_f32_e32 v46, v46, v48
	v_lshlrev_b32_e32 v47, 16, v19
	v_and_b32_e32 v48, 0xffff0000, v19
	v_add_f32_e32 v45, v45, v47
	v_add_f32_e32 v46, v46, v48
	v_lshlrev_b32_e32 v47, 16, v20
	v_and_b32_e32 v48, 0xffff0000, v20
	v_add_f32_e32 v45, v45, v47
	v_add_f32_e32 v46, v46, v48
	v_lshlrev_b32_e32 v47, 16, v21
	v_and_b32_e32 v48, 0xffff0000, v21
	v_add_f32_e32 v45, v45, v47
	v_add_f32_e32 v46, v46, v48
	v_lshlrev_b32_e32 v47, 16, v22
	v_and_b32_e32 v48, 0xffff0000, v22
	v_add_f32_e32 v45, v45, v47
	v_add_f32_e32 v46, v46, v48
	v_lshlrev_b32_e32 v47, 16, v23
	v_and_b32_e32 v48, 0xffff0000, v23
	v_add_f32_e32 v45, v45, v47
	v_add_f32_e32 v46, v46, v48
	v_lshlrev_b32_e32 v47, 16, v20
	v_and_b32_e32 v48, 0xffff0000, v20
	v_fma_f32 v45, v44, v45, -v47
	v_fma_f32 v46, v44, v46, -v48
	v_cvt_pk_bf16_f32 v45, v45, v46
	global_store_dword v0, v45, s[36:37]
	s_add_u32 s36, s36, 0x400
	s_addc_u32 s37, s37, 0
	s_add_i32 s0, s19, 15
	s_min_u32 s0, s0, s18
	s_add_i32 s1, s19, 7
	s_max_i32 s1, s1, 0
	s_sub_i32 s0, s0, s1
	v_cvt_f32_i32_e32 v37, s0
	v_div_scale_f32 v38, s[0:1], v37, v37, 1.0
	v_rcp_f32_e32 v39, v38
	v_div_scale_f32 v41, vcc, 1.0, v37, 1.0
	v_fma_f32 v40, -v38, v39, 1.0
	v_fmac_f32_e32 v39, v40, v39
	v_mul_f32_e32 v42, v41, v39
	v_fma_f32 v43, -v38, v42, v41
	v_fmac_f32_e32 v42, v43, v39
	v_fma_f32 v38, -v38, v42, v41
	v_div_fmas_f32 v38, v38, v39, v42
	v_div_fixup_f32 v44, v38, v37, 1.0
	s_waitcnt vmcnt(15)
	v_lshlrev_b32_e32 v47, 16, v17
	v_and_b32_e32 v48, 0xffff0000, v17
	v_add_f32_e32 v45, 0, v47
	v_add_f32_e32 v46, 0, v48
	v_lshlrev_b32_e32 v47, 16, v18
	v_and_b32_e32 v48, 0xffff0000, v18
	v_add_f32_e32 v45, v45, v47
	v_add_f32_e32 v46, v46, v48
	v_lshlrev_b32_e32 v47, 16, v19
	v_and_b32_e32 v48, 0xffff0000, v19
	v_add_f32_e32 v45, v45, v47
	v_add_f32_e32 v46, v46, v48
	v_lshlrev_b32_e32 v47, 16, v20
	v_and_b32_e32 v48, 0xffff0000, v20
	v_add_f32_e32 v45, v45, v47
	v_add_f32_e32 v46, v46, v48
	v_lshlrev_b32_e32 v47, 16, v21
	v_and_b32_e32 v48, 0xffff0000, v21
	v_add_f32_e32 v45, v45, v47
	v_add_f32_e32 v46, v46, v48
	v_lshlrev_b32_e32 v47, 16, v22
	v_and_b32_e32 v48, 0xffff0000, v22
	v_add_f32_e32 v45, v45, v47
	v_add_f32_e32 v46, v46, v48
	v_lshlrev_b32_e32 v47, 16, v23
	v_and_b32_e32 v48, 0xffff0000, v23
	v_add_f32_e32 v45, v45, v47
	v_add_f32_e32 v46, v46, v48
	v_lshlrev_b32_e32 v47, 16, v24
	v_and_b32_e32 v48, 0xffff0000, v24
	v_add_f32_e32 v45, v45, v47
	v_add_f32_e32 v46, v46, v48
	v_lshlrev_b32_e32 v47, 16, v21
	v_and_b32_e32 v48, 0xffff0000, v21
	v_fma_f32 v45, v44, v45, -v47
	v_fma_f32 v46, v44, v46, -v48
	v_cvt_pk_bf16_f32 v45, v45, v46
	global_store_dword v0, v45, s[36:37]
	s_add_u32 s36, s36, 0x400
	s_addc_u32 s37, s37, 0
	s_add_i32 s0, s19, 16
	s_min_u32 s0, s0, s18
	s_add_i32 s1, s19, 8
	s_max_i32 s1, s1, 0
	s_sub_i32 s0, s0, s1
	v_cvt_f32_i32_e32 v37, s0
	v_div_scale_f32 v38, s[0:1], v37, v37, 1.0
	v_rcp_f32_e32 v39, v38
	v_div_scale_f32 v41, vcc, 1.0, v37, 1.0
	v_fma_f32 v40, -v38, v39, 1.0
	v_fmac_f32_e32 v39, v40, v39
	v_mul_f32_e32 v42, v41, v39
	v_fma_f32 v43, -v38, v42, v41
	v_fmac_f32_e32 v42, v43, v39
	v_fma_f32 v38, -v38, v42, v41
	v_div_fmas_f32 v38, v38, v39, v42
	v_div_fixup_f32 v44, v38, v37, 1.0
	s_waitcnt vmcnt(15)
	v_lshlrev_b32_e32 v47, 16, v18
	v_and_b32_e32 v48, 0xffff0000, v18
	v_add_f32_e32 v45, 0, v47
	v_add_f32_e32 v46, 0, v48
	v_lshlrev_b32_e32 v47, 16, v19
	v_and_b32_e32 v48, 0xffff0000, v19
	v_add_f32_e32 v45, v45, v47
	v_add_f32_e32 v46, v46, v48
	v_lshlrev_b32_e32 v47, 16, v20
	v_and_b32_e32 v48, 0xffff0000, v20
	v_add_f32_e32 v45, v45, v47
	v_add_f32_e32 v46, v46, v48
	v_lshlrev_b32_e32 v47, 16, v21
	v_and_b32_e32 v48, 0xffff0000, v21
	v_add_f32_e32 v45, v45, v47
	v_add_f32_e32 v46, v46, v48
	v_lshlrev_b32_e32 v47, 16, v22
	v_and_b32_e32 v48, 0xffff0000, v22
	v_add_f32_e32 v45, v45, v47
	v_add_f32_e32 v46, v46, v48
	v_lshlrev_b32_e32 v47, 16, v23
	v_and_b32_e32 v48, 0xffff0000, v23
	v_add_f32_e32 v45, v45, v47
	v_add_f32_e32 v46, v46, v48
	v_lshlrev_b32_e32 v47, 16, v24
	v_and_b32_e32 v48, 0xffff0000, v24
	v_add_f32_e32 v45, v45, v47
	v_add_f32_e32 v46, v46, v48
	v_lshlrev_b32_e32 v47, 16, v25
	v_and_b32_e32 v48, 0xffff0000, v25
	v_add_f32_e32 v45, v45, v47
	v_add_f32_e32 v46, v46, v48
	v_lshlrev_b32_e32 v47, 16, v22
	v_and_b32_e32 v48, 0xffff0000, v22
	v_fma_f32 v45, v44, v45, -v47
	v_fma_f32 v46, v44, v46, -v48
	v_cvt_pk_bf16_f32 v45, v45, v46
	global_store_dword v0, v45, s[36:37]
	s_add_u32 s36, s36, 0x400
	s_addc_u32 s37, s37, 0
	s_add_i32 s0, s19, 17
	s_min_u32 s0, s0, s18
	s_add_i32 s1, s19, 9
	s_max_i32 s1, s1, 0
	s_sub_i32 s0, s0, s1
	v_cvt_f32_i32_e32 v37, s0
	v_div_scale_f32 v38, s[0:1], v37, v37, 1.0
	v_rcp_f32_e32 v39, v38
	v_div_scale_f32 v41, vcc, 1.0, v37, 1.0
	v_fma_f32 v40, -v38, v39, 1.0
	v_fmac_f32_e32 v39, v40, v39
	v_mul_f32_e32 v42, v41, v39
	v_fma_f32 v43, -v38, v42, v41
	v_fmac_f32_e32 v42, v43, v39
	v_fma_f32 v38, -v38, v42, v41
	v_div_fmas_f32 v38, v38, v39, v42
	v_div_fixup_f32 v44, v38, v37, 1.0
	s_waitcnt vmcnt(15)
	v_lshlrev_b32_e32 v47, 16, v19
	v_and_b32_e32 v48, 0xffff0000, v19
	v_add_f32_e32 v45, 0, v47
	v_add_f32_e32 v46, 0, v48
	v_lshlrev_b32_e32 v47, 16, v20
	v_and_b32_e32 v48, 0xffff0000, v20
	v_add_f32_e32 v45, v45, v47
	v_add_f32_e32 v46, v46, v48
	v_lshlrev_b32_e32 v47, 16, v21
	v_and_b32_e32 v48, 0xffff0000, v21
	v_add_f32_e32 v45, v45, v47
	v_add_f32_e32 v46, v46, v48
	v_lshlrev_b32_e32 v47, 16, v22
	v_and_b32_e32 v48, 0xffff0000, v22
	v_add_f32_e32 v45, v45, v47
	v_add_f32_e32 v46, v46, v48
	v_lshlrev_b32_e32 v47, 16, v23
	v_and_b32_e32 v48, 0xffff0000, v23
	v_add_f32_e32 v45, v45, v47
	v_add_f32_e32 v46, v46, v48
	v_lshlrev_b32_e32 v47, 16, v24
	v_and_b32_e32 v48, 0xffff0000, v24
	v_add_f32_e32 v45, v45, v47
	v_add_f32_e32 v46, v46, v48
	v_lshlrev_b32_e32 v47, 16, v25
	v_and_b32_e32 v48, 0xffff0000, v25
	v_add_f32_e32 v45, v45, v47
	v_add_f32_e32 v46, v46, v48
	v_lshlrev_b32_e32 v47, 16, v26
	v_and_b32_e32 v48, 0xffff0000, v26
	v_add_f32_e32 v45, v45, v47
	v_add_f32_e32 v46, v46, v48
	v_lshlrev_b32_e32 v47, 16, v23
	v_and_b32_e32 v48, 0xffff0000, v23
	v_fma_f32 v45, v44, v45, -v47
	v_fma_f32 v46, v44, v46, -v48
	v_cvt_pk_bf16_f32 v45, v45, v46
	global_store_dword v0, v45, s[36:37]
	s_add_u32 s36, s36, 0x400
	s_addc_u32 s37, s37, 0
	s_add_i32 s0, s19, 18
	s_min_u32 s0, s0, s18
	s_add_i32 s1, s19, 10
	s_max_i32 s1, s1, 0
	s_sub_i32 s0, s0, s1
	v_cvt_f32_i32_e32 v37, s0
	v_div_scale_f32 v38, s[0:1], v37, v37, 1.0
	v_rcp_f32_e32 v39, v38
	v_div_scale_f32 v41, vcc, 1.0, v37, 1.0
	v_fma_f32 v40, -v38, v39, 1.0
	v_fmac_f32_e32 v39, v40, v39
	v_mul_f32_e32 v42, v41, v39
	v_fma_f32 v43, -v38, v42, v41
	v_fmac_f32_e32 v42, v43, v39
	v_fma_f32 v38, -v38, v42, v41
	v_div_fmas_f32 v38, v38, v39, v42
	v_div_fixup_f32 v44, v38, v37, 1.0
	s_waitcnt vmcnt(15)
	v_lshlrev_b32_e32 v47, 16, v20
	v_and_b32_e32 v48, 0xffff0000, v20
	v_add_f32_e32 v45, 0, v47
	v_add_f32_e32 v46, 0, v48
	v_lshlrev_b32_e32 v47, 16, v21
	v_and_b32_e32 v48, 0xffff0000, v21
	v_add_f32_e32 v45, v45, v47
	v_add_f32_e32 v46, v46, v48
	v_lshlrev_b32_e32 v47, 16, v22
	v_and_b32_e32 v48, 0xffff0000, v22
	v_add_f32_e32 v45, v45, v47
	v_add_f32_e32 v46, v46, v48
	v_lshlrev_b32_e32 v47, 16, v23
	v_and_b32_e32 v48, 0xffff0000, v23
	v_add_f32_e32 v45, v45, v47
	v_add_f32_e32 v46, v46, v48
	v_lshlrev_b32_e32 v47, 16, v24
	v_and_b32_e32 v48, 0xffff0000, v24
	v_add_f32_e32 v45, v45, v47
	v_add_f32_e32 v46, v46, v48
	v_lshlrev_b32_e32 v47, 16, v25
	v_and_b32_e32 v48, 0xffff0000, v25
	v_add_f32_e32 v45, v45, v47
	v_add_f32_e32 v46, v46, v48
	v_lshlrev_b32_e32 v47, 16, v26
	v_and_b32_e32 v48, 0xffff0000, v26
	v_add_f32_e32 v45, v45, v47
	v_add_f32_e32 v46, v46, v48
	v_lshlrev_b32_e32 v47, 16, v27
	v_and_b32_e32 v48, 0xffff0000, v27
	v_add_f32_e32 v45, v45, v47
	v_add_f32_e32 v46, v46, v48
	v_lshlrev_b32_e32 v47, 16, v24
	v_and_b32_e32 v48, 0xffff0000, v24
	v_fma_f32 v45, v44, v45, -v47
	v_fma_f32 v46, v44, v46, -v48
	v_cvt_pk_bf16_f32 v45, v45, v46
	global_store_dword v0, v45, s[36:37]
	s_add_u32 s36, s36, 0x400
	s_addc_u32 s37, s37, 0
	s_add_i32 s0, s19, 19
	s_min_u32 s0, s0, s18
	s_add_i32 s1, s19, 11
	s_max_i32 s1, s1, 0
	s_sub_i32 s0, s0, s1
	v_cvt_f32_i32_e32 v37, s0
	v_div_scale_f32 v38, s[0:1], v37, v37, 1.0
	v_rcp_f32_e32 v39, v38
	v_div_scale_f32 v41, vcc, 1.0, v37, 1.0
	v_fma_f32 v40, -v38, v39, 1.0
	v_fmac_f32_e32 v39, v40, v39
	v_mul_f32_e32 v42, v41, v39
	v_fma_f32 v43, -v38, v42, v41
	v_fmac_f32_e32 v42, v43, v39
	v_fma_f32 v38, -v38, v42, v41
	v_div_fmas_f32 v38, v38, v39, v42
	v_div_fixup_f32 v44, v38, v37, 1.0
	s_waitcnt vmcnt(15)
	v_lshlrev_b32_e32 v47, 16, v21
	v_and_b32_e32 v48, 0xffff0000, v21
	v_add_f32_e32 v45, 0, v47
	v_add_f32_e32 v46, 0, v48
	v_lshlrev_b32_e32 v47, 16, v22
	v_and_b32_e32 v48, 0xffff0000, v22
	v_add_f32_e32 v45, v45, v47
	v_add_f32_e32 v46, v46, v48
	v_lshlrev_b32_e32 v47, 16, v23
	v_and_b32_e32 v48, 0xffff0000, v23
	v_add_f32_e32 v45, v45, v47
	v_add_f32_e32 v46, v46, v48
	v_lshlrev_b32_e32 v47, 16, v24
	v_and_b32_e32 v48, 0xffff0000, v24
	v_add_f32_e32 v45, v45, v47
	v_add_f32_e32 v46, v46, v48
	v_lshlrev_b32_e32 v47, 16, v25
	v_and_b32_e32 v48, 0xffff0000, v25
	v_add_f32_e32 v45, v45, v47
	v_add_f32_e32 v46, v46, v48
	v_lshlrev_b32_e32 v47, 16, v26
	v_and_b32_e32 v48, 0xffff0000, v26
	v_add_f32_e32 v45, v45, v47
	v_add_f32_e32 v46, v46, v48
	v_lshlrev_b32_e32 v47, 16, v27
	v_and_b32_e32 v48, 0xffff0000, v27
	v_add_f32_e32 v45, v45, v47
	v_add_f32_e32 v46, v46, v48
	v_lshlrev_b32_e32 v47, 16, v28
	v_and_b32_e32 v48, 0xffff0000, v28
	v_add_f32_e32 v45, v45, v47
	v_add_f32_e32 v46, v46, v48
	v_lshlrev_b32_e32 v47, 16, v25
	v_and_b32_e32 v48, 0xffff0000, v25
	v_fma_f32 v45, v44, v45, -v47
	v_fma_f32 v46, v44, v46, -v48
	v_cvt_pk_bf16_f32 v45, v45, v46
	global_store_dword v0, v45, s[36:37]
	s_branch .Lpd_done
.Lpd_hw8:
	s_add_i32 s0, s19, -8
	s_cmp_lt_u32 s0, s18
	s_cbranch_scc0 .Lpd_z8_0
	s_lshl_b32 s0, s0, 10
	s_add_u32 s48, s46, s0
	s_addc_u32 s49, s47, 0
	global_load_dword v6, v0, s[48:49]
	s_branch .Lpd_n8_0

.Lpd_n8_0:
	s_add_i32 s0, s19, -7
	s_cmp_lt_u32 s0, s18
	s_cbranch_scc0 .Lpd_z8_1
	s_lshl_b32 s0, s0, 10
	s_add_u32 s48, s46, s0
	s_addc_u32 s49, s47, 0
	global_load_dword v7, v0, s[48:49]
	s_branch .Lpd_n8_1

.Lpd_n8_1:
	s_add_i32 s0, s19, -6
	s_cmp_lt_u32 s0, s18
	s_cbranch_scc0 .Lpd_z8_2
	s_lshl_b32 s0, s0, 10
	s_add_u32 s48, s46, s0
	s_addc_u32 s49, s47, 0
	global_load_dword v8, v0, s[48:49]
	s_branch .Lpd_n8_2

.Lpd_n8_2:
	s_add_i32 s0, s19, -5
	s_cmp_lt_u32 s0, s18
	s_cbranch_scc0 .Lpd_z8_3
	s_lshl_b32 s0, s0, 10
	s_add_u32 s48, s46, s0
	s_addc_u32 s49, s47, 0
	global_load_dword v9, v0, s[48:49]
	s_branch .Lpd_n8_3

.Lpd_n8_3:
	s_add_i32 s0, s19, -4
	s_cmp_lt_u32 s0, s18
	s_cbranch_scc0 .Lpd_z8_4
	s_lshl_b32 s0, s0, 10
	s_add_u32 s48, s46, s0
	s_addc_u32 s49, s47, 0
	global_load_dword v10, v0, s[48:49]
	s_branch .Lpd_n8_4

.Lpd_n8_4:
	s_add_i32 s0, s19, -3
	s_cmp_lt_u32 s0, s18
	s_cbranch_scc0 .Lpd_z8_5
	s_lshl_b32 s0, s0, 10
	s_add_u32 s48, s46, s0
	s_addc_u32 s49, s47, 0
	global_load_dword v11, v0, s[48:49]
	s_branch .Lpd_n8_5

.Lpd_n8_5:
	s_add_i32 s0, s19, -2
	s_cmp_lt_u32 s0, s18
	s_cbranch_scc0 .Lpd_z8_6
	s_lshl_b32 s0, s0, 10
	s_add_u32 s48, s46, s0
	s_addc_u32 s49, s47, 0
	global_load_dword v12, v0, s[48:49]
	s_branch .Lpd_n8_6

.Lpd_n8_6:
	s_add_i32 s0, s19, -1
	s_cmp_lt_u32 s0, s18
	s_cbranch_scc0 .Lpd_z8_7
	s_lshl_b32 s0, s0, 10
	s_add_u32 s48, s46, s0
	s_addc_u32 s49, s47, 0
	global_load_dword v13, v0, s[48:49]
	s_branch .Lpd_n8_7

.Lpd_n8_7:
	s_lshl_b32 s0, s19, 10
	s_add_u32 s48, s46, s0
	s_addc_u32 s49, s47, 0
	global_load_dword v14, v0, s[48:49]
	s_add_i32 s0, s19, 1
	s_cmp_lt_u32 s0, s18
	s_cbranch_scc0 .Lpd_z8_9
	s_lshl_b32 s0, s0, 10
	s_add_u32 s48, s46, s0
	s_addc_u32 s49, s47, 0
	global_load_dword v15, v0, s[48:49]
	s_branch .Lpd_n8_9

.Lpd_n8_9:
	s_add_i32 s0, s19, 2
	s_cmp_lt_u32 s0, s18
	s_cbranch_scc0 .Lpd_z8_10
	s_lshl_b32 s0, s0, 10
	s_add_u32 s48, s46, s0
	s_addc_u32 s49, s47, 0
	global_load_dword v16, v0, s[48:49]
	s_branch .Lpd_n8_10

.Lpd_n8_10:
	s_add_i32 s0, s19, 3
	s_cmp_lt_u32 s0, s18
	s_cbranch_scc0 .Lpd_z8_11
	s_lshl_b32 s0, s0, 10
	s_add_u32 s48, s46, s0
	s_addc_u32 s49, s47, 0
	global_load_dword v17, v0, s[48:49]
	s_branch .Lpd_n8_11

.Lpd_n8_11:
	s_add_i32 s0, s19, 4
	s_cmp_lt_u32 s0, s18
	s_cbranch_scc0 .Lpd_z8_12
	s_lshl_b32 s0, s0, 10
	s_add_u32 s48, s46, s0
	s_addc_u32 s49, s47, 0
	global_load_dword v18, v0, s[48:49]
	s_branch .Lpd_n8_12

.Lpd_n8_12:
	s_add_i32 s0, s19, 5
	s_cmp_lt_u32 s0, s18
	s_cbranch_scc0 .Lpd_z8_13
	s_lshl_b32 s0, s0, 10
	s_add_u32 s48, s46, s0
	s_addc_u32 s49, s47, 0
	global_load_dword v19, v0, s[48:49]
	s_branch .Lpd_n8_13

.Lpd_n8_13:
	s_add_i32 s0, s19, 6
	s_cmp_lt_u32 s0, s18
	s_cbranch_scc0 .Lpd_z8_14
	s_lshl_b32 s0, s0, 10
	s_add_u32 s48, s46, s0
	s_addc_u32 s49, s47, 0
	global_load_dword v20, v0, s[48:49]
	s_branch .Lpd_n8_14

.Lpd_n8_14:
	s_add_i32 s0, s19, 7
	s_cmp_lt_u32 s0, s18
	s_cbranch_scc0 .Lpd_z8_15
	s_lshl_b32 s0, s0, 10
	s_add_u32 s48, s46, s0
	s_addc_u32 s49, s47, 0
	global_load_dword v21, v0, s[48:49]
	s_branch .Lpd_n8_15

.Lpd_n8_15:
	s_add_i32 s0, s19, 8
	s_cmp_lt_u32 s0, s18
	s_cbranch_scc0 .Lpd_z8_16
	s_lshl_b32 s0, s0, 10
	s_add_u32 s48, s46, s0
	s_addc_u32 s49, s47, 0
	global_load_dword v22, v0, s[48:49]
	s_branch .Lpd_n8_16

.Lpd_n8_16:
	s_add_i32 s0, s19, 9
	s_cmp_lt_u32 s0, s18
	s_cbranch_scc0 .Lpd_z8_17
	s_lshl_b32 s0, s0, 10
	s_add_u32 s48, s46, s0
	s_addc_u32 s49, s47, 0
	global_load_dword v23, v0, s[48:49]
	s_branch .Lpd_n8_17

.Lpd_n8_17:
	s_add_i32 s0, s19, 10
	s_cmp_lt_u32 s0, s18
	s_cbranch_scc0 .Lpd_z8_18
	s_lshl_b32 s0, s0, 10
	s_add_u32 s48, s46, s0
	s_addc_u32 s49, s47, 0
	global_load_dword v24, v0, s[48:49]
	s_branch .Lpd_n8_18

.Lpd_n8_18:
	s_add_i32 s0, s19, 11
	s_cmp_lt_u32 s0, s18
	s_cbranch_scc0 .Lpd_z8_19
	s_lshl_b32 s0, s0, 10
	s_add_u32 s48, s46, s0
	s_addc_u32 s49, s47, 0
	global_load_dword v25, v0, s[48:49]
	s_branch .Lpd_n8_19

.Lpd_n8_19:
	s_add_i32 s0, s19, 12
	s_cmp_lt_u32 s0, s18
	s_cbranch_scc0 .Lpd_z8_20
	s_lshl_b32 s0, s0, 10
	s_add_u32 s48, s46, s0
	s_addc_u32 s49, s47, 0
	global_load_dword v26, v0, s[48:49]
	s_branch .Lpd_n8_20

.Lpd_n8_20:
	s_add_i32 s0, s19, 13
	s_cmp_lt_u32 s0, s18
	s_cbranch_scc0 .Lpd_z8_21
	s_lshl_b32 s0, s0, 10
	s_add_u32 s48, s46, s0
	s_addc_u32 s49, s47, 0
	global_load_dword v27, v0, s[48:49]
	s_branch .Lpd_n8_21

.Lpd_n8_21:
	s_add_i32 s0, s19, 14
	s_cmp_lt_u32 s0, s18
	s_cbranch_scc0 .Lpd_z8_22
	s_lshl_b32 s0, s0, 10
	s_add_u32 s48, s46, s0
	s_addc_u32 s49, s47, 0
	global_load_dword v28, v0, s[48:49]
	s_branch .Lpd_n8_22

.Lpd_n8_22:
	s_add_i32 s0, s19, 15
	s_cmp_lt_u32 s0, s18
	s_cbranch_scc0 .Lpd_z8_23
	s_lshl_b32 s0, s0, 10
	s_add_u32 s48, s46, s0
	s_addc_u32 s49, s47, 0
	global_load_dword v29, v0, s[48:49]
	s_branch .Lpd_n8_23
.Lpd_z8_23:
	global_load_dword v29, v0, s[50:51]
.Lpd_n8_23:
	s_add_i32 s0, s19, 16
	s_cmp_lt_u32 s0, s18
	s_cbranch_scc0 .Lpd_z8_24
	s_lshl_b32 s0, s0, 10
	s_add_u32 s48, s46, s0
	s_addc_u32 s49, s47, 0
	global_load_dword v30, v0, s[48:49]
	s_branch .Lpd_n8_24
.Lpd_z8_24:
	global_load_dword v30, v0, s[50:51]
.Lpd_n8_24:
	s_add_i32 s0, s19, 17
	s_cmp_lt_u32 s0, s18
	s_cbranch_scc0 .Lpd_z8_25
	s_lshl_b32 s0, s0, 10
	s_add_u32 s48, s46, s0
	s_addc_u32 s49, s47, 0
	global_load_dword v31, v0, s[48:49]
	s_branch .Lpd_n8_25
.Lpd_z8_25:
	global_load_dword v31, v0, s[50:51]
.Lpd_n8_25:
	s_add_i32 s0, s19, 18
	s_cmp_lt_u32 s0, s18
	s_cbranch_scc0 .Lpd_z8_26
	s_lshl_b32 s0, s0, 10
	s_add_u32 s48, s46, s0
	s_addc_u32 s49, s47, 0
	global_load_dword v32, v0, s[48:49]
	s_branch .Lpd_n8_26
.Lpd_z8_26:
	global_load_dword v32, v0, s[50:51]
.Lpd_n8_26:
	s_add_i32 s0, s19, 19
	s_cmp_lt_u32 s0, s18
	s_cbranch_scc0 .Lpd_z8_27
	s_lshl_b32 s0, s0, 10
	s_add_u32 s48, s46, s0
	s_addc_u32 s49, s47, 0
	global_load_dword v33, v0, s[48:49]
	s_branch .Lpd_n8_27
.Lpd_z8_27:
	global_load_dword v33, v0, s[50:51]
.Lpd_n8_27:
	s_add_i32 s0, s19, 20
	s_cmp_lt_u32 s0, s18
	s_cbranch_scc0 .Lpd_z8_28
	s_lshl_b32 s0, s0, 10
	s_add_u32 s48, s46, s0
	s_addc_u32 s49, s47, 0
	global_load_dword v34, v0, s[48:49]
	s_branch .Lpd_n8_28
.Lpd_z8_28:
	global_load_dword v34, v0, s[50:51]
.Lpd_n8_28:
	s_add_i32 s0, s19, 21
	s_cmp_lt_u32 s0, s18
	s_cbranch_scc0 .Lpd_z8_29
	s_lshl_b32 s0, s0, 10
	s_add_u32 s48, s46, s0
	s_addc_u32 s49, s47, 0
	global_load_dword v35, v0, s[48:49]
	s_branch .Lpd_n8_29
.Lpd_z8_29:
	global_load_dword v35, v0, s[50:51]
.Lpd_n8_29:
	s_add_i32 s0, s19, 22
	s_cmp_lt_u32 s0, s18
	s_cbranch_scc0 .Lpd_z8_30
	s_lshl_b32 s0, s0, 10
	s_add_u32 s48, s46, s0
	s_addc_u32 s49, s47, 0
	global_load_dword v36, v0, s[48:49]
	s_branch .Lpd_n8_30
.Lpd_z8_30:
	global_load_dword v36, v0, s[50:51]
.Lpd_n8_30:
	s_add_i32 s0, s19, 8
	s_min_u32 s0, s0, s18
	s_add_i32 s1, s19, -8
	s_max_i32 s1, s1, 0
	s_sub_i32 s0, s0, s1
	v_cvt_f32_i32_e32 v37, s0
	v_div_scale_f32 v38, s[0:1], v37, v37, 1.0
	v_rcp_f32_e32 v39, v38
	v_div_scale_f32 v41, vcc, 1.0, v37, 1.0
	v_fma_f32 v40, -v38, v39, 1.0
	v_fmac_f32_e32 v39, v40, v39
	v_mul_f32_e32 v42, v41, v39
	v_fma_f32 v43, -v38, v42, v41
	v_fmac_f32_e32 v42, v43, v39
	v_fma_f32 v38, -v38, v42, v41
	v_div_fmas_f32 v38, v38, v39, v42
	v_div_fixup_f32 v44, v38, v37, 1.0
	s_waitcnt vmcnt(15)
	v_lshlrev_b32_e32 v47, 16, v6
	v_and_b32_e32 v48, 0xffff0000, v6
	v_add_f32_e32 v45, 0, v47
	v_add_f32_e32 v46, 0, v48
	v_lshlrev_b32_e32 v47, 16, v7
	v_and_b32_e32 v48, 0xffff0000, v7
	v_add_f32_e32 v45, v45, v47
	v_add_f32_e32 v46, v46, v48
	v_lshlrev_b32_e32 v47, 16, v8
	v_and_b32_e32 v48, 0xffff0000, v8
	v_add_f32_e32 v45, v45, v47
	v_add_f32_e32 v46, v46, v48
	v_lshlrev_b32_e32 v47, 16, v9
	v_and_b32_e32 v48, 0xffff0000, v9
	v_add_f32_e32 v45, v45, v47
	v_add_f32_e32 v46, v46, v48
	v_lshlrev_b32_e32 v47, 16, v10
	v_and_b32_e32 v48, 0xffff0000, v10
	v_add_f32_e32 v45, v45, v47
	v_add_f32_e32 v46, v46, v48
	v_lshlrev_b32_e32 v47, 16, v11
	v_and_b32_e32 v48, 0xffff0000, v11
	v_add_f32_e32 v45, v45, v47
	v_add_f32_e32 v46, v46, v48
	v_lshlrev_b32_e32 v47, 16, v12
	v_and_b32_e32 v48, 0xffff0000, v12
	v_add_f32_e32 v45, v45, v47
	v_add_f32_e32 v46, v46, v48
	v_lshlrev_b32_e32 v47, 16, v13
	v_and_b32_e32 v48, 0xffff0000, v13
	v_add_f32_e32 v45, v45, v47
	v_add_f32_e32 v46, v46, v48
	v_lshlrev_b32_e32 v47, 16, v14
	v_and_b32_e32 v48, 0xffff0000, v14
	v_add_f32_e32 v45, v45, v47
	v_add_f32_e32 v46, v46, v48
	v_lshlrev_b32_e32 v47, 16, v15
	v_and_b32_e32 v48, 0xffff0000, v15
	v_add_f32_e32 v45, v45, v47
	v_add_f32_e32 v46, v46, v48
	v_lshlrev_b32_e32 v47, 16, v16
	v_and_b32_e32 v48, 0xffff0000, v16
	v_add_f32_e32 v45, v45, v47
	v_add_f32_e32 v46, v46, v48
	v_lshlrev_b32_e32 v47, 16, v17
	v_and_b32_e32 v48, 0xffff0000, v17
	v_add_f32_e32 v45, v45, v47
	v_add_f32_e32 v46, v46, v48
	v_lshlrev_b32_e32 v47, 16, v18
	v_and_b32_e32 v48, 0xffff0000, v18
	v_add_f32_e32 v45, v45, v47
	v_add_f32_e32 v46, v46, v48
	v_lshlrev_b32_e32 v47, 16, v19
	v_and_b32_e32 v48, 0xffff0000, v19
	v_add_f32_e32 v45, v45, v47
	v_add_f32_e32 v46, v46, v48
	v_lshlrev_b32_e32 v47, 16, v20
	v_and_b32_e32 v48, 0xffff0000, v20
	v_add_f32_e32 v45, v45, v47
	v_add_f32_e32 v46, v46, v48
	v_lshlrev_b32_e32 v47, 16, v21
	v_and_b32_e32 v48, 0xffff0000, v21
	v_add_f32_e32 v45, v45, v47
	v_add_f32_e32 v46, v46, v48
	v_lshlrev_b32_e32 v47, 16, v14
	v_and_b32_e32 v48, 0xffff0000, v14
	v_fma_f32 v45, v44, v45, -v47
	v_fma_f32 v46, v44, v46, -v48
	v_cvt_pk_bf16_f32 v45, v45, v46
	global_store_dword v0, v45, s[36:37]
	s_add_u32 s36, s36, 0x400
	s_addc_u32 s37, s37, 0
	s_add_i32 s0, s19, 9
	s_min_u32 s0, s0, s18
	s_add_i32 s1, s19, -7
	s_max_i32 s1, s1, 0
	s_sub_i32 s0, s0, s1
	v_cvt_f32_i32_e32 v37, s0
	v_div_scale_f32 v38, s[0:1], v37, v37, 1.0
	v_rcp_f32_e32 v39, v38
	v_div_scale_f32 v41, vcc, 1.0, v37, 1.0
	v_fma_f32 v40, -v38, v39, 1.0
	v_fmac_f32_e32 v39, v40, v39
	v_mul_f32_e32 v42, v41, v39
	v_fma_f32 v43, -v38, v42, v41
	v_fmac_f32_e32 v42, v43, v39
	v_fma_f32 v38, -v38, v42, v41
	v_div_fmas_f32 v38, v38, v39, v42
	v_div_fixup_f32 v44, v38, v37, 1.0
	s_waitcnt vmcnt(15)
	v_lshlrev_b32_e32 v47, 16, v7
	v_and_b32_e32 v48, 0xffff0000, v7
	v_add_f32_e32 v45, 0, v47
	v_add_f32_e32 v46, 0, v48
	v_lshlrev_b32_e32 v47, 16, v8
	v_and_b32_e32 v48, 0xffff0000, v8
	v_add_f32_e32 v45, v45, v47
	v_add_f32_e32 v46, v46, v48
	v_lshlrev_b32_e32 v47, 16, v9
	v_and_b32_e32 v48, 0xffff0000, v9
	v_add_f32_e32 v45, v45, v47
	v_add_f32_e32 v46, v46, v48
	v_lshlrev_b32_e32 v47, 16, v10
	v_and_b32_e32 v48, 0xffff0000, v10
	v_add_f32_e32 v45, v45, v47
	v_add_f32_e32 v46, v46, v48
	v_lshlrev_b32_e32 v47, 16, v11
	v_and_b32_e32 v48, 0xffff0000, v11
	v_add_f32_e32 v45, v45, v47
	v_add_f32_e32 v46, v46, v48
	v_lshlrev_b32_e32 v47, 16, v12
	v_and_b32_e32 v48, 0xffff0000, v12
	v_add_f32_e32 v45, v45, v47
	v_add_f32_e32 v46, v46, v48
	v_lshlrev_b32_e32 v47, 16, v13
	v_and_b32_e32 v48, 0xffff0000, v13
	v_add_f32_e32 v45, v45, v47
	v_add_f32_e32 v46, v46, v48
	v_lshlrev_b32_e32 v47, 16, v14
	v_and_b32_e32 v48, 0xffff0000, v14
	v_add_f32_e32 v45, v45, v47
	v_add_f32_e32 v46, v46, v48
	v_lshlrev_b32_e32 v47, 16, v15
	v_and_b32_e32 v48, 0xffff0000, v15
	v_add_f32_e32 v45, v45, v47
	v_add_f32_e32 v46, v46, v48
	v_lshlrev_b32_e32 v47, 16, v16
	v_and_b32_e32 v48, 0xffff0000, v16
	v_add_f32_e32 v45, v45, v47
	v_add_f32_e32 v46, v46, v48
	v_lshlrev_b32_e32 v47, 16, v17
	v_and_b32_e32 v48, 0xffff0000, v17
	v_add_f32_e32 v45, v45, v47
	v_add_f32_e32 v46, v46, v48
	v_lshlrev_b32_e32 v47, 16, v18
	v_and_b32_e32 v48, 0xffff0000, v18
	v_add_f32_e32 v45, v45, v47
	v_add_f32_e32 v46, v46, v48
	v_lshlrev_b32_e32 v47, 16, v19
	v_and_b32_e32 v48, 0xffff0000, v19
	v_add_f32_e32 v45, v45, v47
	v_add_f32_e32 v46, v46, v48
	v_lshlrev_b32_e32 v47, 16, v20
	v_and_b32_e32 v48, 0xffff0000, v20
	v_add_f32_e32 v45, v45, v47
	v_add_f32_e32 v46, v46, v48
	v_lshlrev_b32_e32 v47, 16, v21
	v_and_b32_e32 v48, 0xffff0000, v21
	v_add_f32_e32 v45, v45, v47
	v_add_f32_e32 v46, v46, v48
	v_lshlrev_b32_e32 v47, 16, v22
	v_and_b32_e32 v48, 0xffff0000, v22
	v_add_f32_e32 v45, v45, v47
	v_add_f32_e32 v46, v46, v48
	v_lshlrev_b32_e32 v47, 16, v15
	v_and_b32_e32 v48, 0xffff0000, v15
	v_fma_f32 v45, v44, v45, -v47
	v_fma_f32 v46, v44, v46, -v48
	v_cvt_pk_bf16_f32 v45, v45, v46
	global_store_dword v0, v45, s[36:37]
	s_add_u32 s36, s36, 0x400
	s_addc_u32 s37, s37, 0
	s_add_i32 s0, s19, 10
	s_min_u32 s0, s0, s18
	s_add_i32 s1, s19, -6
	s_max_i32 s1, s1, 0
	s_sub_i32 s0, s0, s1
	v_cvt_f32_i32_e32 v37, s0
	v_div_scale_f32 v38, s[0:1], v37, v37, 1.0
	v_rcp_f32_e32 v39, v38
	v_div_scale_f32 v41, vcc, 1.0, v37, 1.0
	v_fma_f32 v40, -v38, v39, 1.0
	v_fmac_f32_e32 v39, v40, v39
	v_mul_f32_e32 v42, v41, v39
	v_fma_f32 v43, -v38, v42, v41
	v_fmac_f32_e32 v42, v43, v39
	v_fma_f32 v38, -v38, v42, v41
	v_div_fmas_f32 v38, v38, v39, v42
	v_div_fixup_f32 v44, v38, v37, 1.0
	s_waitcnt vmcnt(15)
	v_lshlrev_b32_e32 v47, 16, v8
	v_and_b32_e32 v48, 0xffff0000, v8
	v_add_f32_e32 v45, 0, v47
	v_add_f32_e32 v46, 0, v48
	v_lshlrev_b32_e32 v47, 16, v9
	v_and_b32_e32 v48, 0xffff0000, v9
	v_add_f32_e32 v45, v45, v47
	v_add_f32_e32 v46, v46, v48
	v_lshlrev_b32_e32 v47, 16, v10
	v_and_b32_e32 v48, 0xffff0000, v10
	v_add_f32_e32 v45, v45, v47
	v_add_f32_e32 v46, v46, v48
	v_lshlrev_b32_e32 v47, 16, v11
	v_and_b32_e32 v48, 0xffff0000, v11
	v_add_f32_e32 v45, v45, v47
	v_add_f32_e32 v46, v46, v48
	v_lshlrev_b32_e32 v47, 16, v12
	v_and_b32_e32 v48, 0xffff0000, v12
	v_add_f32_e32 v45, v45, v47
	v_add_f32_e32 v46, v46, v48
	v_lshlrev_b32_e32 v47, 16, v13
	v_and_b32_e32 v48, 0xffff0000, v13
	v_add_f32_e32 v45, v45, v47
	v_add_f32_e32 v46, v46, v48
	v_lshlrev_b32_e32 v47, 16, v14
	v_and_b32_e32 v48, 0xffff0000, v14
	v_add_f32_e32 v45, v45, v47
	v_add_f32_e32 v46, v46, v48
	v_lshlrev_b32_e32 v47, 16, v15
	v_and_b32_e32 v48, 0xffff0000, v15
	v_add_f32_e32 v45, v45, v47
	v_add_f32_e32 v46, v46, v48
	v_lshlrev_b32_e32 v47, 16, v16
	v_and_b32_e32 v48, 0xffff0000, v16
	v_add_f32_e32 v45, v45, v47
	v_add_f32_e32 v46, v46, v48
	v_lshlrev_b32_e32 v47, 16, v17
	v_and_b32_e32 v48, 0xffff0000, v17
	v_add_f32_e32 v45, v45, v47
	v_add_f32_e32 v46, v46, v48
	v_lshlrev_b32_e32 v47, 16, v18
	v_and_b32_e32 v48, 0xffff0000, v18
	v_add_f32_e32 v45, v45, v47
	v_add_f32_e32 v46, v46, v48
	v_lshlrev_b32_e32 v47, 16, v19
	v_and_b32_e32 v48, 0xffff0000, v19
	v_add_f32_e32 v45, v45, v47
	v_add_f32_e32 v46, v46, v48
	v_lshlrev_b32_e32 v47, 16, v20
	v_and_b32_e32 v48, 0xffff0000, v20
	v_add_f32_e32 v45, v45, v47
	v_add_f32_e32 v46, v46, v48
	v_lshlrev_b32_e32 v47, 16, v21
	v_and_b32_e32 v48, 0xffff0000, v21
	v_add_f32_e32 v45, v45, v47
	v_add_f32_e32 v46, v46, v48
	v_lshlrev_b32_e32 v47, 16, v22
	v_and_b32_e32 v48, 0xffff0000, v22
	v_add_f32_e32 v45, v45, v47
	v_add_f32_e32 v46, v46, v48
	v_lshlrev_b32_e32 v47, 16, v23
	v_and_b32_e32 v48, 0xffff0000, v23
	v_add_f32_e32 v45, v45, v47
	v_add_f32_e32 v46, v46, v48
	v_lshlrev_b32_e32 v47, 16, v16
	v_and_b32_e32 v48, 0xffff0000, v16
	v_fma_f32 v45, v44, v45, -v47
	v_fma_f32 v46, v44, v46, -v48
	v_cvt_pk_bf16_f32 v45, v45, v46
	global_store_dword v0, v45, s[36:37]
	s_add_u32 s36, s36, 0x400
	s_addc_u32 s37, s37, 0
	s_add_i32 s0, s19, 11
	s_min_u32 s0, s0, s18
	s_add_i32 s1, s19, -5
	s_max_i32 s1, s1, 0
	s_sub_i32 s0, s0, s1
	v_cvt_f32_i32_e32 v37, s0
	v_div_scale_f32 v38, s[0:1], v37, v37, 1.0
	v_rcp_f32_e32 v39, v38
	v_div_scale_f32 v41, vcc, 1.0, v37, 1.0
	v_fma_f32 v40, -v38, v39, 1.0
	v_fmac_f32_e32 v39, v40, v39
	v_mul_f32_e32 v42, v41, v39
	v_fma_f32 v43, -v38, v42, v41
	v_fmac_f32_e32 v42, v43, v39
	v_fma_f32 v38, -v38, v42, v41
	v_div_fmas_f32 v38, v38, v39, v42
	v_div_fixup_f32 v44, v38, v37, 1.0
	s_waitcnt vmcnt(15)
	v_lshlrev_b32_e32 v47, 16, v9
	v_and_b32_e32 v48, 0xffff0000, v9
	v_add_f32_e32 v45, 0, v47
	v_add_f32_e32 v46, 0, v48
	v_lshlrev_b32_e32 v47, 16, v10
	v_and_b32_e32 v48, 0xffff0000, v10
	v_add_f32_e32 v45, v45, v47
	v_add_f32_e32 v46, v46, v48
	v_lshlrev_b32_e32 v47, 16, v11
	v_and_b32_e32 v48, 0xffff0000, v11
	v_add_f32_e32 v45, v45, v47
	v_add_f32_e32 v46, v46, v48
	v_lshlrev_b32_e32 v47, 16, v12
	v_and_b32_e32 v48, 0xffff0000, v12
	v_add_f32_e32 v45, v45, v47
	v_add_f32_e32 v46, v46, v48
	v_lshlrev_b32_e32 v47, 16, v13
	v_and_b32_e32 v48, 0xffff0000, v13
	v_add_f32_e32 v45, v45, v47
	v_add_f32_e32 v46, v46, v48
	v_lshlrev_b32_e32 v47, 16, v14
	v_and_b32_e32 v48, 0xffff0000, v14
	v_add_f32_e32 v45, v45, v47
	v_add_f32_e32 v46, v46, v48
	v_lshlrev_b32_e32 v47, 16, v15
	v_and_b32_e32 v48, 0xffff0000, v15
	v_add_f32_e32 v45, v45, v47
	v_add_f32_e32 v46, v46, v48
	v_lshlrev_b32_e32 v47, 16, v16
	v_and_b32_e32 v48, 0xffff0000, v16
	v_add_f32_e32 v45, v45, v47
	v_add_f32_e32 v46, v46, v48
	v_lshlrev_b32_e32 v47, 16, v17
	v_and_b32_e32 v48, 0xffff0000, v17
	v_add_f32_e32 v45, v45, v47
	v_add_f32_e32 v46, v46, v48
	v_lshlrev_b32_e32 v47, 16, v18
	v_and_b32_e32 v48, 0xffff0000, v18
	v_add_f32_e32 v45, v45, v47
	v_add_f32_e32 v46, v46, v48
	v_lshlrev_b32_e32 v47, 16, v19
	v_and_b32_e32 v48, 0xffff0000, v19
	v_add_f32_e32 v45, v45, v47
	v_add_f32_e32 v46, v46, v48
	v_lshlrev_b32_e32 v47, 16, v20
	v_and_b32_e32 v48, 0xffff0000, v20
	v_add_f32_e32 v45, v45, v47
	v_add_f32_e32 v46, v46, v48
	v_lshlrev_b32_e32 v47, 16, v21
	v_and_b32_e32 v48, 0xffff0000, v21
	v_add_f32_e32 v45, v45, v47
	v_add_f32_e32 v46, v46, v48
	v_lshlrev_b32_e32 v47, 16, v22
	v_and_b32_e32 v48, 0xffff0000, v22
	v_add_f32_e32 v45, v45, v47
	v_add_f32_e32 v46, v46, v48
	v_lshlrev_b32_e32 v47, 16, v23
	v_and_b32_e32 v48, 0xffff0000, v23
	v_add_f32_e32 v45, v45, v47
	v_add_f32_e32 v46, v46, v48
	v_lshlrev_b32_e32 v47, 16, v24
	v_and_b32_e32 v48, 0xffff0000, v24
	v_add_f32_e32 v45, v45, v47
	v_add_f32_e32 v46, v46, v48
	v_lshlrev_b32_e32 v47, 16, v17
	v_and_b32_e32 v48, 0xffff0000, v17
	v_fma_f32 v45, v44, v45, -v47
	v_fma_f32 v46, v44, v46, -v48
	v_cvt_pk_bf16_f32 v45, v45, v46
	global_store_dword v0, v45, s[36:37]
	s_add_u32 s36, s36, 0x400
	s_addc_u32 s37, s37, 0
	s_add_i32 s0, s19, 12
	s_min_u32 s0, s0, s18
	s_add_i32 s1, s19, -4
	s_max_i32 s1, s1, 0
	s_sub_i32 s0, s0, s1
	v_cvt_f32_i32_e32 v37, s0
	v_div_scale_f32 v38, s[0:1], v37, v37, 1.0
	v_rcp_f32_e32 v39, v38
	v_div_scale_f32 v41, vcc, 1.0, v37, 1.0
	v_fma_f32 v40, -v38, v39, 1.0
	v_fmac_f32_e32 v39, v40, v39
	v_mul_f32_e32 v42, v41, v39
	v_fma_f32 v43, -v38, v42, v41
	v_fmac_f32_e32 v42, v43, v39
	v_fma_f32 v38, -v38, v42, v41
	v_div_fmas_f32 v38, v38, v39, v42
	v_div_fixup_f32 v44, v38, v37, 1.0
	s_waitcnt vmcnt(15)
	v_lshlrev_b32_e32 v47, 16, v10
	v_and_b32_e32 v48, 0xffff0000, v10
	v_add_f32_e32 v45, 0, v47
	v_add_f32_e32 v46, 0, v48
	v_lshlrev_b32_e32 v47, 16, v11
	v_and_b32_e32 v48, 0xffff0000, v11
	v_add_f32_e32 v45, v45, v47
	v_add_f32_e32 v46, v46, v48
	v_lshlrev_b32_e32 v47, 16, v12
	v_and_b32_e32 v48, 0xffff0000, v12
	v_add_f32_e32 v45, v45, v47
	v_add_f32_e32 v46, v46, v48
	v_lshlrev_b32_e32 v47, 16, v13
	v_and_b32_e32 v48, 0xffff0000, v13
	v_add_f32_e32 v45, v45, v47
	v_add_f32_e32 v46, v46, v48
	v_lshlrev_b32_e32 v47, 16, v14
	v_and_b32_e32 v48, 0xffff0000, v14
	v_add_f32_e32 v45, v45, v47
	v_add_f32_e32 v46, v46, v48
	v_lshlrev_b32_e32 v47, 16, v15
	v_and_b32_e32 v48, 0xffff0000, v15
	v_add_f32_e32 v45, v45, v47
	v_add_f32_e32 v46, v46, v48
	v_lshlrev_b32_e32 v47, 16, v16
	v_and_b32_e32 v48, 0xffff0000, v16
	v_add_f32_e32 v45, v45, v47
	v_add_f32_e32 v46, v46, v48
	v_lshlrev_b32_e32 v47, 16, v17
	v_and_b32_e32 v48, 0xffff0000, v17
	v_add_f32_e32 v45, v45, v47
	v_add_f32_e32 v46, v46, v48
	v_lshlrev_b32_e32 v47, 16, v18
	v_and_b32_e32 v48, 0xffff0000, v18
	v_add_f32_e32 v45, v45, v47
	v_add_f32_e32 v46, v46, v48
	v_lshlrev_b32_e32 v47, 16, v19
	v_and_b32_e32 v48, 0xffff0000, v19
	v_add_f32_e32 v45, v45, v47
	v_add_f32_e32 v46, v46, v48
	v_lshlrev_b32_e32 v47, 16, v20
	v_and_b32_e32 v48, 0xffff0000, v20
	v_add_f32_e32 v45, v45, v47
	v_add_f32_e32 v46, v46, v48
	v_lshlrev_b32_e32 v47, 16, v21
	v_and_b32_e32 v48, 0xffff0000, v21
	v_add_f32_e32 v45, v45, v47
	v_add_f32_e32 v46, v46, v48
	v_lshlrev_b32_e32 v47, 16, v22
	v_and_b32_e32 v48, 0xffff0000, v22
	v_add_f32_e32 v45, v45, v47
	v_add_f32_e32 v46, v46, v48
	v_lshlrev_b32_e32 v47, 16, v23
	v_and_b32_e32 v48, 0xffff0000, v23
	v_add_f32_e32 v45, v45, v47
	v_add_f32_e32 v46, v46, v48
	v_lshlrev_b32_e32 v47, 16, v24
	v_and_b32_e32 v48, 0xffff0000, v24
	v_add_f32_e32 v45, v45, v47
	v_add_f32_e32 v46, v46, v48
	v_lshlrev_b32_e32 v47, 16, v25
	v_and_b32_e32 v48, 0xffff0000, v25
	v_add_f32_e32 v45, v45, v47
	v_add_f32_e32 v46, v46, v48
	v_lshlrev_b32_e32 v47, 16, v18
	v_and_b32_e32 v48, 0xffff0000, v18
	v_fma_f32 v45, v44, v45, -v47
	v_fma_f32 v46, v44, v46, -v48
	v_cvt_pk_bf16_f32 v45, v45, v46
	global_store_dword v0, v45, s[36:37]
	s_add_u32 s36, s36, 0x400
	s_addc_u32 s37, s37, 0
	s_add_i32 s0, s19, 13
	s_min_u32 s0, s0, s18
	s_add_i32 s1, s19, -3
	s_max_i32 s1, s1, 0
	s_sub_i32 s0, s0, s1
	v_cvt_f32_i32_e32 v37, s0
	v_div_scale_f32 v38, s[0:1], v37, v37, 1.0
	v_rcp_f32_e32 v39, v38
	v_div_scale_f32 v41, vcc, 1.0, v37, 1.0
	v_fma_f32 v40, -v38, v39, 1.0
	v_fmac_f32_e32 v39, v40, v39
	v_mul_f32_e32 v42, v41, v39
	v_fma_f32 v43, -v38, v42, v41
	v_fmac_f32_e32 v42, v43, v39
	v_fma_f32 v38, -v38, v42, v41
	v_div_fmas_f32 v38, v38, v39, v42
	v_div_fixup_f32 v44, v38, v37, 1.0
	s_waitcnt vmcnt(15)
	v_lshlrev_b32_e32 v47, 16, v11
	v_and_b32_e32 v48, 0xffff0000, v11
	v_add_f32_e32 v45, 0, v47
	v_add_f32_e32 v46, 0, v48
	v_lshlrev_b32_e32 v47, 16, v12
	v_and_b32_e32 v48, 0xffff0000, v12
	v_add_f32_e32 v45, v45, v47
	v_add_f32_e32 v46, v46, v48
	v_lshlrev_b32_e32 v47, 16, v13
	v_and_b32_e32 v48, 0xffff0000, v13
	v_add_f32_e32 v45, v45, v47
	v_add_f32_e32 v46, v46, v48
	v_lshlrev_b32_e32 v47, 16, v14
	v_and_b32_e32 v48, 0xffff0000, v14
	v_add_f32_e32 v45, v45, v47
	v_add_f32_e32 v46, v46, v48
	v_lshlrev_b32_e32 v47, 16, v15
	v_and_b32_e32 v48, 0xffff0000, v15
	v_add_f32_e32 v45, v45, v47
	v_add_f32_e32 v46, v46, v48
	v_lshlrev_b32_e32 v47, 16, v16
	v_and_b32_e32 v48, 0xffff0000, v16
	v_add_f32_e32 v45, v45, v47
	v_add_f32_e32 v46, v46, v48
	v_lshlrev_b32_e32 v47, 16, v17
	v_and_b32_e32 v48, 0xffff0000, v17
	v_add_f32_e32 v45, v45, v47
	v_add_f32_e32 v46, v46, v48
	v_lshlrev_b32_e32 v47, 16, v18
	v_and_b32_e32 v48, 0xffff0000, v18
	v_add_f32_e32 v45, v45, v47
	v_add_f32_e32 v46, v46, v48
	v_lshlrev_b32_e32 v47, 16, v19
	v_and_b32_e32 v48, 0xffff0000, v19
	v_add_f32_e32 v45, v45, v47
	v_add_f32_e32 v46, v46, v48
	v_lshlrev_b32_e32 v47, 16, v20
	v_and_b32_e32 v48, 0xffff0000, v20
	v_add_f32_e32 v45, v45, v47
	v_add_f32_e32 v46, v46, v48
	v_lshlrev_b32_e32 v47, 16, v21
	v_and_b32_e32 v48, 0xffff0000, v21
	v_add_f32_e32 v45, v45, v47
	v_add_f32_e32 v46, v46, v48
	v_lshlrev_b32_e32 v47, 16, v22
	v_and_b32_e32 v48, 0xffff0000, v22
	v_add_f32_e32 v45, v45, v47
	v_add_f32_e32 v46, v46, v48
	v_lshlrev_b32_e32 v47, 16, v23
	v_and_b32_e32 v48, 0xffff0000, v23
	v_add_f32_e32 v45, v45, v47
	v_add_f32_e32 v46, v46, v48
	v_lshlrev_b32_e32 v47, 16, v24
	v_and_b32_e32 v48, 0xffff0000, v24
	v_add_f32_e32 v45, v45, v47
	v_add_f32_e32 v46, v46, v48
	v_lshlrev_b32_e32 v47, 16, v25
	v_and_b32_e32 v48, 0xffff0000, v25
	v_add_f32_e32 v45, v45, v47
	v_add_f32_e32 v46, v46, v48
	v_lshlrev_b32_e32 v47, 16, v26
	v_and_b32_e32 v48, 0xffff0000, v26
	v_add_f32_e32 v45, v45, v47
	v_add_f32_e32 v46, v46, v48
	v_lshlrev_b32_e32 v47, 16, v19
	v_and_b32_e32 v48, 0xffff0000, v19
	v_fma_f32 v45, v44, v45, -v47
	v_fma_f32 v46, v44, v46, -v48
	v_cvt_pk_bf16_f32 v45, v45, v46
	global_store_dword v0, v45, s[36:37]
	s_add_u32 s36, s36, 0x400
	s_addc_u32 s37, s37, 0
	s_add_i32 s0, s19, 14
	s_min_u32 s0, s0, s18
	s_add_i32 s1, s19, -2
	s_max_i32 s1, s1, 0
	s_sub_i32 s0, s0, s1
	v_cvt_f32_i32_e32 v37, s0
	v_div_scale_f32 v38, s[0:1], v37, v37, 1.0
	v_rcp_f32_e32 v39, v38
	v_div_scale_f32 v41, vcc, 1.0, v37, 1.0
	v_fma_f32 v40, -v38, v39, 1.0
	v_fmac_f32_e32 v39, v40, v39
	v_mul_f32_e32 v42, v41, v39
	v_fma_f32 v43, -v38, v42, v41
	v_fmac_f32_e32 v42, v43, v39
	v_fma_f32 v38, -v38, v42, v41
	v_div_fmas_f32 v38, v38, v39, v42
	v_div_fixup_f32 v44, v38, v37, 1.0
	s_waitcnt vmcnt(15)
	v_lshlrev_b32_e32 v47, 16, v12
	v_and_b32_e32 v48, 0xffff0000, v12
	v_add_f32_e32 v45, 0, v47
	v_add_f32_e32 v46, 0, v48
	v_lshlrev_b32_e32 v47, 16, v13
	v_and_b32_e32 v48, 0xffff0000, v13
	v_add_f32_e32 v45, v45, v47
	v_add_f32_e32 v46, v46, v48
	v_lshlrev_b32_e32 v47, 16, v14
	v_and_b32_e32 v48, 0xffff0000, v14
	v_add_f32_e32 v45, v45, v47
	v_add_f32_e32 v46, v46, v48
	v_lshlrev_b32_e32 v47, 16, v15
	v_and_b32_e32 v48, 0xffff0000, v15
	v_add_f32_e32 v45, v45, v47
	v_add_f32_e32 v46, v46, v48
	v_lshlrev_b32_e32 v47, 16, v16
	v_and_b32_e32 v48, 0xffff0000, v16
	v_add_f32_e32 v45, v45, v47
	v_add_f32_e32 v46, v46, v48
	v_lshlrev_b32_e32 v47, 16, v17
	v_and_b32_e32 v48, 0xffff0000, v17
	v_add_f32_e32 v45, v45, v47
	v_add_f32_e32 v46, v46, v48
	v_lshlrev_b32_e32 v47, 16, v18
	v_and_b32_e32 v48, 0xffff0000, v18
	v_add_f32_e32 v45, v45, v47
	v_add_f32_e32 v46, v46, v48
	v_lshlrev_b32_e32 v47, 16, v19
	v_and_b32_e32 v48, 0xffff0000, v19
	v_add_f32_e32 v45, v45, v47
	v_add_f32_e32 v46, v46, v48
	v_lshlrev_b32_e32 v47, 16, v20
	v_and_b32_e32 v48, 0xffff0000, v20
	v_add_f32_e32 v45, v45, v47
	v_add_f32_e32 v46, v46, v48
	v_lshlrev_b32_e32 v47, 16, v21
	v_and_b32_e32 v48, 0xffff0000, v21
	v_add_f32_e32 v45, v45, v47
	v_add_f32_e32 v46, v46, v48
	v_lshlrev_b32_e32 v47, 16, v22
	v_and_b32_e32 v48, 0xffff0000, v22
	v_add_f32_e32 v45, v45, v47
	v_add_f32_e32 v46, v46, v48
	v_lshlrev_b32_e32 v47, 16, v23
	v_and_b32_e32 v48, 0xffff0000, v23
	v_add_f32_e32 v45, v45, v47
	v_add_f32_e32 v46, v46, v48
	v_lshlrev_b32_e32 v47, 16, v24
	v_and_b32_e32 v48, 0xffff0000, v24
	v_add_f32_e32 v45, v45, v47
	v_add_f32_e32 v46, v46, v48
	v_lshlrev_b32_e32 v47, 16, v25
	v_and_b32_e32 v48, 0xffff0000, v25
	v_add_f32_e32 v45, v45, v47
	v_add_f32_e32 v46, v46, v48
	v_lshlrev_b32_e32 v47, 16, v26
	v_and_b32_e32 v48, 0xffff0000, v26
	v_add_f32_e32 v45, v45, v47
	v_add_f32_e32 v46, v46, v48
	v_lshlrev_b32_e32 v47, 16, v27
	v_and_b32_e32 v48, 0xffff0000, v27
	v_add_f32_e32 v45, v45, v47
	v_add_f32_e32 v46, v46, v48
	v_lshlrev_b32_e32 v47, 16, v20
	v_and_b32_e32 v48, 0xffff0000, v20
	v_fma_f32 v45, v44, v45, -v47
	v_fma_f32 v46, v44, v46, -v48
	v_cvt_pk_bf16_f32 v45, v45, v46
	global_store_dword v0, v45, s[36:37]
	s_add_u32 s36, s36, 0x400
	s_addc_u32 s37, s37, 0
	s_add_i32 s0, s19, 15
	s_min_u32 s0, s0, s18
	s_add_i32 s1, s19, -1
	s_max_i32 s1, s1, 0
	s_sub_i32 s0, s0, s1
	v_cvt_f32_i32_e32 v37, s0
	v_div_scale_f32 v38, s[0:1], v37, v37, 1.0
	v_rcp_f32_e32 v39, v38
	v_div_scale_f32 v41, vcc, 1.0, v37, 1.0
	v_fma_f32 v40, -v38, v39, 1.0
	v_fmac_f32_e32 v39, v40, v39
	v_mul_f32_e32 v42, v41, v39
	v_fma_f32 v43, -v38, v42, v41
	v_fmac_f32_e32 v42, v43, v39
	v_fma_f32 v38, -v38, v42, v41
	v_div_fmas_f32 v38, v38, v39, v42
	v_div_fixup_f32 v44, v38, v37, 1.0
	s_waitcnt vmcnt(15)
	v_lshlrev_b32_e32 v47, 16, v13
	v_and_b32_e32 v48, 0xffff0000, v13
	v_add_f32_e32 v45, 0, v47
	v_add_f32_e32 v46, 0, v48
	v_lshlrev_b32_e32 v47, 16, v14
	v_and_b32_e32 v48, 0xffff0000, v14
	v_add_f32_e32 v45, v45, v47
	v_add_f32_e32 v46, v46, v48
	v_lshlrev_b32_e32 v47, 16, v15
	v_and_b32_e32 v48, 0xffff0000, v15
	v_add_f32_e32 v45, v45, v47
	v_add_f32_e32 v46, v46, v48
	v_lshlrev_b32_e32 v47, 16, v16
	v_and_b32_e32 v48, 0xffff0000, v16
	v_add_f32_e32 v45, v45, v47
	v_add_f32_e32 v46, v46, v48
	v_lshlrev_b32_e32 v47, 16, v17
	v_and_b32_e32 v48, 0xffff0000, v17
	v_add_f32_e32 v45, v45, v47
	v_add_f32_e32 v46, v46, v48
	v_lshlrev_b32_e32 v47, 16, v18
	v_and_b32_e32 v48, 0xffff0000, v18
	v_add_f32_e32 v45, v45, v47
	v_add_f32_e32 v46, v46, v48
	v_lshlrev_b32_e32 v47, 16, v19
	v_and_b32_e32 v48, 0xffff0000, v19
	v_add_f32_e32 v45, v45, v47
	v_add_f32_e32 v46, v46, v48
	v_lshlrev_b32_e32 v47, 16, v20
	v_and_b32_e32 v48, 0xffff0000, v20
	v_add_f32_e32 v45, v45, v47
	v_add_f32_e32 v46, v46, v48
	v_lshlrev_b32_e32 v47, 16, v21
	v_and_b32_e32 v48, 0xffff0000, v21
	v_add_f32_e32 v45, v45, v47
	v_add_f32_e32 v46, v46, v48
	v_lshlrev_b32_e32 v47, 16, v22
	v_and_b32_e32 v48, 0xffff0000, v22
	v_add_f32_e32 v45, v45, v47
	v_add_f32_e32 v46, v46, v48
	v_lshlrev_b32_e32 v47, 16, v23
	v_and_b32_e32 v48, 0xffff0000, v23
	v_add_f32_e32 v45, v45, v47
	v_add_f32_e32 v46, v46, v48
	v_lshlrev_b32_e32 v47, 16, v24
	v_and_b32_e32 v48, 0xffff0000, v24
	v_add_f32_e32 v45, v45, v47
	v_add_f32_e32 v46, v46, v48
	v_lshlrev_b32_e32 v47, 16, v25
	v_and_b32_e32 v48, 0xffff0000, v25
	v_add_f32_e32 v45, v45, v47
	v_add_f32_e32 v46, v46, v48
	v_lshlrev_b32_e32 v47, 16, v26
	v_and_b32_e32 v48, 0xffff0000, v26
	v_add_f32_e32 v45, v45, v47
	v_add_f32_e32 v46, v46, v48
	v_lshlrev_b32_e32 v47, 16, v27
	v_and_b32_e32 v48, 0xffff0000, v27
	v_add_f32_e32 v45, v45, v47
	v_add_f32_e32 v46, v46, v48
	v_lshlrev_b32_e32 v47, 16, v28
	v_and_b32_e32 v48, 0xffff0000, v28
	v_add_f32_e32 v45, v45, v47
	v_add_f32_e32 v46, v46, v48
	v_lshlrev_b32_e32 v47, 16, v21
	v_and_b32_e32 v48, 0xffff0000, v21
	v_fma_f32 v45, v44, v45, -v47
	v_fma_f32 v46, v44, v46, -v48
	v_cvt_pk_bf16_f32 v45, v45, v46
	global_store_dword v0, v45, s[36:37]
	s_add_u32 s36, s36, 0x400
	s_addc_u32 s37, s37, 0
	s_add_i32 s0, s19, 16
	s_min_u32 s0, s0, s18
	s_add_i32 s1, s19, 0
	s_max_i32 s1, s1, 0
	s_sub_i32 s0, s0, s1
	v_cvt_f32_i32_e32 v37, s0
	v_div_scale_f32 v38, s[0:1], v37, v37, 1.0
	v_rcp_f32_e32 v39, v38
	v_div_scale_f32 v41, vcc, 1.0, v37, 1.0
	v_fma_f32 v40, -v38, v39, 1.0
	v_fmac_f32_e32 v39, v40, v39
	v_mul_f32_e32 v42, v41, v39
	v_fma_f32 v43, -v38, v42, v41
	v_fmac_f32_e32 v42, v43, v39
	v_fma_f32 v38, -v38, v42, v41
	v_div_fmas_f32 v38, v38, v39, v42
	v_div_fixup_f32 v44, v38, v37, 1.0
	s_waitcnt vmcnt(15)
	v_lshlrev_b32_e32 v47, 16, v14
	v_and_b32_e32 v48, 0xffff0000, v14
	v_add_f32_e32 v45, 0, v47
	v_add_f32_e32 v46, 0, v48
	v_lshlrev_b32_e32 v47, 16, v15
	v_and_b32_e32 v48, 0xffff0000, v15
	v_add_f32_e32 v45, v45, v47
	v_add_f32_e32 v46, v46, v48
	v_lshlrev_b32_e32 v47, 16, v16
	v_and_b32_e32 v48, 0xffff0000, v16
	v_add_f32_e32 v45, v45, v47
	v_add_f32_e32 v46, v46, v48
	v_lshlrev_b32_e32 v47, 16, v17
	v_and_b32_e32 v48, 0xffff0000, v17
	v_add_f32_e32 v45, v45, v47
	v_add_f32_e32 v46, v46, v48
	v_lshlrev_b32_e32 v47, 16, v18
	v_and_b32_e32 v48, 0xffff0000, v18
	v_add_f32_e32 v45, v45, v47
	v_add_f32_e32 v46, v46, v48
	v_lshlrev_b32_e32 v47, 16, v19
	v_and_b32_e32 v48, 0xffff0000, v19
	v_add_f32_e32 v45, v45, v47
	v_add_f32_e32 v46, v46, v48
	v_lshlrev_b32_e32 v47, 16, v20
	v_and_b32_e32 v48, 0xffff0000, v20
	v_add_f32_e32 v45, v45, v47
	v_add_f32_e32 v46, v46, v48
	v_lshlrev_b32_e32 v47, 16, v21
	v_and_b32_e32 v48, 0xffff0000, v21
	v_add_f32_e32 v45, v45, v47
	v_add_f32_e32 v46, v46, v48
	v_lshlrev_b32_e32 v47, 16, v22
	v_and_b32_e32 v48, 0xffff0000, v22
	v_add_f32_e32 v45, v45, v47
	v_add_f32_e32 v46, v46, v48
	v_lshlrev_b32_e32 v47, 16, v23
	v_and_b32_e32 v48, 0xffff0000, v23
	v_add_f32_e32 v45, v45, v47
	v_add_f32_e32 v46, v46, v48
	v_lshlrev_b32_e32 v47, 16, v24
	v_and_b32_e32 v48, 0xffff0000, v24
	v_add_f32_e32 v45, v45, v47
	v_add_f32_e32 v46, v46, v48
	v_lshlrev_b32_e32 v47, 16, v25
	v_and_b32_e32 v48, 0xffff0000, v25
	v_add_f32_e32 v45, v45, v47
	v_add_f32_e32 v46, v46, v48
	v_lshlrev_b32_e32 v47, 16, v26
	v_and_b32_e32 v48, 0xffff0000, v26
	v_add_f32_e32 v45, v45, v47
	v_add_f32_e32 v46, v46, v48
	v_lshlrev_b32_e32 v47, 16, v27
	v_and_b32_e32 v48, 0xffff0000, v27
	v_add_f32_e32 v45, v45, v47
	v_add_f32_e32 v46, v46, v48
	v_lshlrev_b32_e32 v47, 16, v28
	v_and_b32_e32 v48, 0xffff0000, v28
	v_add_f32_e32 v45, v45, v47
	v_add_f32_e32 v46, v46, v48
	v_lshlrev_b32_e32 v47, 16, v29
	v_and_b32_e32 v48, 0xffff0000, v29
	v_add_f32_e32 v45, v45, v47
	v_add_f32_e32 v46, v46, v48
	v_lshlrev_b32_e32 v47, 16, v22
	v_and_b32_e32 v48, 0xffff0000, v22
	v_fma_f32 v45, v44, v45, -v47
	v_fma_f32 v46, v44, v46, -v48
	v_cvt_pk_bf16_f32 v45, v45, v46
	global_store_dword v0, v45, s[36:37]
	s_add_u32 s36, s36, 0x400
	s_addc_u32 s37, s37, 0
	s_add_i32 s0, s19, 17
	s_min_u32 s0, s0, s18
	s_add_i32 s1, s19, 1
	s_max_i32 s1, s1, 0
	s_sub_i32 s0, s0, s1
	v_cvt_f32_i32_e32 v37, s0
	v_div_scale_f32 v38, s[0:1], v37, v37, 1.0
	v_rcp_f32_e32 v39, v38
	v_div_scale_f32 v41, vcc, 1.0, v37, 1.0
	v_fma_f32 v40, -v38, v39, 1.0
	v_fmac_f32_e32 v39, v40, v39
	v_mul_f32_e32 v42, v41, v39
	v_fma_f32 v43, -v38, v42, v41
	v_fmac_f32_e32 v42, v43, v39
	v_fma_f32 v38, -v38, v42, v41
	v_div_fmas_f32 v38, v38, v39, v42
	v_div_fixup_f32 v44, v38, v37, 1.0
	s_waitcnt vmcnt(15)
	v_lshlrev_b32_e32 v47, 16, v15
	v_and_b32_e32 v48, 0xffff0000, v15
	v_add_f32_e32 v45, 0, v47
	v_add_f32_e32 v46, 0, v48
	v_lshlrev_b32_e32 v47, 16, v16
	v_and_b32_e32 v48, 0xffff0000, v16
	v_add_f32_e32 v45, v45, v47
	v_add_f32_e32 v46, v46, v48
	v_lshlrev_b32_e32 v47, 16, v17
	v_and_b32_e32 v48, 0xffff0000, v17
	v_add_f32_e32 v45, v45, v47
	v_add_f32_e32 v46, v46, v48
	v_lshlrev_b32_e32 v47, 16, v18
	v_and_b32_e32 v48, 0xffff0000, v18
	v_add_f32_e32 v45, v45, v47
	v_add_f32_e32 v46, v46, v48
	v_lshlrev_b32_e32 v47, 16, v19
	v_and_b32_e32 v48, 0xffff0000, v19
	v_add_f32_e32 v45, v45, v47
	v_add_f32_e32 v46, v46, v48
	v_lshlrev_b32_e32 v47, 16, v20
	v_and_b32_e32 v48, 0xffff0000, v20
	v_add_f32_e32 v45, v45, v47
	v_add_f32_e32 v46, v46, v48
	v_lshlrev_b32_e32 v47, 16, v21
	v_and_b32_e32 v48, 0xffff0000, v21
	v_add_f32_e32 v45, v45, v47
	v_add_f32_e32 v46, v46, v48
	v_lshlrev_b32_e32 v47, 16, v22
	v_and_b32_e32 v48, 0xffff0000, v22
	v_add_f32_e32 v45, v45, v47
	v_add_f32_e32 v46, v46, v48
	v_lshlrev_b32_e32 v47, 16, v23
	v_and_b32_e32 v48, 0xffff0000, v23
	v_add_f32_e32 v45, v45, v47
	v_add_f32_e32 v46, v46, v48
	v_lshlrev_b32_e32 v47, 16, v24
	v_and_b32_e32 v48, 0xffff0000, v24
	v_add_f32_e32 v45, v45, v47
	v_add_f32_e32 v46, v46, v48
	v_lshlrev_b32_e32 v47, 16, v25
	v_and_b32_e32 v48, 0xffff0000, v25
	v_add_f32_e32 v45, v45, v47
	v_add_f32_e32 v46, v46, v48
	v_lshlrev_b32_e32 v47, 16, v26
	v_and_b32_e32 v48, 0xffff0000, v26
	v_add_f32_e32 v45, v45, v47
	v_add_f32_e32 v46, v46, v48
	v_lshlrev_b32_e32 v47, 16, v27
	v_and_b32_e32 v48, 0xffff0000, v27
	v_add_f32_e32 v45, v45, v47
	v_add_f32_e32 v46, v46, v48
	v_lshlrev_b32_e32 v47, 16, v28
	v_and_b32_e32 v48, 0xffff0000, v28
	v_add_f32_e32 v45, v45, v47
	v_add_f32_e32 v46, v46, v48
	v_lshlrev_b32_e32 v47, 16, v29
	v_and_b32_e32 v48, 0xffff0000, v29
	v_add_f32_e32 v45, v45, v47
	v_add_f32_e32 v46, v46, v48
	v_lshlrev_b32_e32 v47, 16, v30
	v_and_b32_e32 v48, 0xffff0000, v30
	v_add_f32_e32 v45, v45, v47
	v_add_f32_e32 v46, v46, v48
	v_lshlrev_b32_e32 v47, 16, v23
	v_and_b32_e32 v48, 0xffff0000, v23
	v_fma_f32 v45, v44, v45, -v47
	v_fma_f32 v46, v44, v46, -v48
	v_cvt_pk_bf16_f32 v45, v45, v46
	global_store_dword v0, v45, s[36:37]
	s_add_u32 s36, s36, 0x400
	s_addc_u32 s37, s37, 0
	s_add_i32 s0, s19, 18
	s_min_u32 s0, s0, s18
	s_add_i32 s1, s19, 2
	s_max_i32 s1, s1, 0
	s_sub_i32 s0, s0, s1
	v_cvt_f32_i32_e32 v37, s0
	v_div_scale_f32 v38, s[0:1], v37, v37, 1.0
	v_rcp_f32_e32 v39, v38
	v_div_scale_f32 v41, vcc, 1.0, v37, 1.0
	v_fma_f32 v40, -v38, v39, 1.0
	v_fmac_f32_e32 v39, v40, v39
	v_mul_f32_e32 v42, v41, v39
	v_fma_f32 v43, -v38, v42, v41
	v_fmac_f32_e32 v42, v43, v39
	v_fma_f32 v38, -v38, v42, v41
	v_div_fmas_f32 v38, v38, v39, v42
	v_div_fixup_f32 v44, v38, v37, 1.0
	s_waitcnt vmcnt(15)
	v_lshlrev_b32_e32 v47, 16, v16
	v_and_b32_e32 v48, 0xffff0000, v16
	v_add_f32_e32 v45, 0, v47
	v_add_f32_e32 v46, 0, v48
	v_lshlrev_b32_e32 v47, 16, v17
	v_and_b32_e32 v48, 0xffff0000, v17
	v_add_f32_e32 v45, v45, v47
	v_add_f32_e32 v46, v46, v48
	v_lshlrev_b32_e32 v47, 16, v18
	v_and_b32_e32 v48, 0xffff0000, v18
	v_add_f32_e32 v45, v45, v47
	v_add_f32_e32 v46, v46, v48
	v_lshlrev_b32_e32 v47, 16, v19
	v_and_b32_e32 v48, 0xffff0000, v19
	v_add_f32_e32 v45, v45, v47
	v_add_f32_e32 v46, v46, v48
	v_lshlrev_b32_e32 v47, 16, v20
	v_and_b32_e32 v48, 0xffff0000, v20
	v_add_f32_e32 v45, v45, v47
	v_add_f32_e32 v46, v46, v48
	v_lshlrev_b32_e32 v47, 16, v21
	v_and_b32_e32 v48, 0xffff0000, v21
	v_add_f32_e32 v45, v45, v47
	v_add_f32_e32 v46, v46, v48
	v_lshlrev_b32_e32 v47, 16, v22
	v_and_b32_e32 v48, 0xffff0000, v22
	v_add_f32_e32 v45, v45, v47
	v_add_f32_e32 v46, v46, v48
	v_lshlrev_b32_e32 v47, 16, v23
	v_and_b32_e32 v48, 0xffff0000, v23
	v_add_f32_e32 v45, v45, v47
	v_add_f32_e32 v46, v46, v48
	v_lshlrev_b32_e32 v47, 16, v24
	v_and_b32_e32 v48, 0xffff0000, v24
	v_add_f32_e32 v45, v45, v47
	v_add_f32_e32 v46, v46, v48
	v_lshlrev_b32_e32 v47, 16, v25
	v_and_b32_e32 v48, 0xffff0000, v25
	v_add_f32_e32 v45, v45, v47
	v_add_f32_e32 v46, v46, v48
	v_lshlrev_b32_e32 v47, 16, v26
	v_and_b32_e32 v48, 0xffff0000, v26
	v_add_f32_e32 v45, v45, v47
	v_add_f32_e32 v46, v46, v48
	v_lshlrev_b32_e32 v47, 16, v27
	v_and_b32_e32 v48, 0xffff0000, v27
	v_add_f32_e32 v45, v45, v47
	v_add_f32_e32 v46, v46, v48
	v_lshlrev_b32_e32 v47, 16, v28
	v_and_b32_e32 v48, 0xffff0000, v28
	v_add_f32_e32 v45, v45, v47
	v_add_f32_e32 v46, v46, v48
	v_lshlrev_b32_e32 v47, 16, v29
	v_and_b32_e32 v48, 0xffff0000, v29
	v_add_f32_e32 v45, v45, v47
	v_add_f32_e32 v46, v46, v48
	v_lshlrev_b32_e32 v47, 16, v30
	v_and_b32_e32 v48, 0xffff0000, v30
	v_add_f32_e32 v45, v45, v47
	v_add_f32_e32 v46, v46, v48
	v_lshlrev_b32_e32 v47, 16, v31
	v_and_b32_e32 v48, 0xffff0000, v31
	v_add_f32_e32 v45, v45, v47
	v_add_f32_e32 v46, v46, v48
	v_lshlrev_b32_e32 v47, 16, v24
	v_and_b32_e32 v48, 0xffff0000, v24
	v_fma_f32 v45, v44, v45, -v47
	v_fma_f32 v46, v44, v46, -v48
	v_cvt_pk_bf16_f32 v45, v45, v46
	global_store_dword v0, v45, s[36:37]
	s_add_u32 s36, s36, 0x400
	s_addc_u32 s37, s37, 0
	s_add_i32 s0, s19, 19
	s_min_u32 s0, s0, s18
	s_add_i32 s1, s19, 3
	s_max_i32 s1, s1, 0
	s_sub_i32 s0, s0, s1
	v_cvt_f32_i32_e32 v37, s0
	v_div_scale_f32 v38, s[0:1], v37, v37, 1.0
	v_rcp_f32_e32 v39, v38
	v_div_scale_f32 v41, vcc, 1.0, v37, 1.0
	v_fma_f32 v40, -v38, v39, 1.0
	v_fmac_f32_e32 v39, v40, v39
	v_mul_f32_e32 v42, v41, v39
	v_fma_f32 v43, -v38, v42, v41
	v_fmac_f32_e32 v42, v43, v39
	v_fma_f32 v38, -v38, v42, v41
	v_div_fmas_f32 v38, v38, v39, v42
	v_div_fixup_f32 v44, v38, v37, 1.0
	s_waitcnt vmcnt(15)
	v_lshlrev_b32_e32 v47, 16, v17
	v_and_b32_e32 v48, 0xffff0000, v17
	v_add_f32_e32 v45, 0, v47
	v_add_f32_e32 v46, 0, v48
	v_lshlrev_b32_e32 v47, 16, v18
	v_and_b32_e32 v48, 0xffff0000, v18
	v_add_f32_e32 v45, v45, v47
	v_add_f32_e32 v46, v46, v48
	v_lshlrev_b32_e32 v47, 16, v19
	v_and_b32_e32 v48, 0xffff0000, v19
	v_add_f32_e32 v45, v45, v47
	v_add_f32_e32 v46, v46, v48
	v_lshlrev_b32_e32 v47, 16, v20
	v_and_b32_e32 v48, 0xffff0000, v20
	v_add_f32_e32 v45, v45, v47
	v_add_f32_e32 v46, v46, v48
	v_lshlrev_b32_e32 v47, 16, v21
	v_and_b32_e32 v48, 0xffff0000, v21
	v_add_f32_e32 v45, v45, v47
	v_add_f32_e32 v46, v46, v48
	v_lshlrev_b32_e32 v47, 16, v22
	v_and_b32_e32 v48, 0xffff0000, v22
	v_add_f32_e32 v45, v45, v47
	v_add_f32_e32 v46, v46, v48
	v_lshlrev_b32_e32 v47, 16, v23
	v_and_b32_e32 v48, 0xffff0000, v23
	v_add_f32_e32 v45, v45, v47
	v_add_f32_e32 v46, v46, v48
	v_lshlrev_b32_e32 v47, 16, v24
	v_and_b32_e32 v48, 0xffff0000, v24
	v_add_f32_e32 v45, v45, v47
	v_add_f32_e32 v46, v46, v48
	v_lshlrev_b32_e32 v47, 16, v25
	v_and_b32_e32 v48, 0xffff0000, v25
	v_add_f32_e32 v45, v45, v47
	v_add_f32_e32 v46, v46, v48
	v_lshlrev_b32_e32 v47, 16, v26
	v_and_b32_e32 v48, 0xffff0000, v26
	v_add_f32_e32 v45, v45, v47
	v_add_f32_e32 v46, v46, v48
	v_lshlrev_b32_e32 v47, 16, v27
	v_and_b32_e32 v48, 0xffff0000, v27
	v_add_f32_e32 v45, v45, v47
	v_add_f32_e32 v46, v46, v48
	v_lshlrev_b32_e32 v47, 16, v28
	v_and_b32_e32 v48, 0xffff0000, v28
	v_add_f32_e32 v45, v45, v47
	v_add_f32_e32 v46, v46, v48
	v_lshlrev_b32_e32 v47, 16, v29
	v_and_b32_e32 v48, 0xffff0000, v29
	v_add_f32_e32 v45, v45, v47
	v_add_f32_e32 v46, v46, v48
	v_lshlrev_b32_e32 v47, 16, v30
	v_and_b32_e32 v48, 0xffff0000, v30
	v_add_f32_e32 v45, v45, v47
	v_add_f32_e32 v46, v46, v48
	v_lshlrev_b32_e32 v47, 16, v31
	v_and_b32_e32 v48, 0xffff0000, v31
	v_add_f32_e32 v45, v45, v47
	v_add_f32_e32 v46, v46, v48
	v_lshlrev_b32_e32 v47, 16, v32
	v_and_b32_e32 v48, 0xffff0000, v32
	v_add_f32_e32 v45, v45, v47
	v_add_f32_e32 v46, v46, v48
	v_lshlrev_b32_e32 v47, 16, v25
	v_and_b32_e32 v48, 0xffff0000, v25
	v_fma_f32 v45, v44, v45, -v47
	v_fma_f32 v46, v44, v46, -v48
	v_cvt_pk_bf16_f32 v45, v45, v46
	global_store_dword v0, v45, s[36:37]
	s_add_u32 s36, s36, 0x400
	s_addc_u32 s37, s37, 0
	s_add_i32 s0, s19, 20
	s_min_u32 s0, s0, s18
	s_add_i32 s1, s19, 4
	s_max_i32 s1, s1, 0
	s_sub_i32 s0, s0, s1
	v_cvt_f32_i32_e32 v37, s0
	v_div_scale_f32 v38, s[0:1], v37, v37, 1.0
	v_rcp_f32_e32 v39, v38
	v_div_scale_f32 v41, vcc, 1.0, v37, 1.0
	v_fma_f32 v40, -v38, v39, 1.0
	v_fmac_f32_e32 v39, v40, v39
	v_mul_f32_e32 v42, v41, v39
	v_fma_f32 v43, -v38, v42, v41
	v_fmac_f32_e32 v42, v43, v39
	v_fma_f32 v38, -v38, v42, v41
	v_div_fmas_f32 v38, v38, v39, v42
	v_div_fixup_f32 v44, v38, v37, 1.0
	s_waitcnt vmcnt(15)
	v_lshlrev_b32_e32 v47, 16, v18
	v_and_b32_e32 v48, 0xffff0000, v18
	v_add_f32_e32 v45, 0, v47
	v_add_f32_e32 v46, 0, v48
	v_lshlrev_b32_e32 v47, 16, v19
	v_and_b32_e32 v48, 0xffff0000, v19
	v_add_f32_e32 v45, v45, v47
	v_add_f32_e32 v46, v46, v48
	v_lshlrev_b32_e32 v47, 16, v20
	v_and_b32_e32 v48, 0xffff0000, v20
	v_add_f32_e32 v45, v45, v47
	v_add_f32_e32 v46, v46, v48
	v_lshlrev_b32_e32 v47, 16, v21
	v_and_b32_e32 v48, 0xffff0000, v21
	v_add_f32_e32 v45, v45, v47
	v_add_f32_e32 v46, v46, v48
	v_lshlrev_b32_e32 v47, 16, v22
	v_and_b32_e32 v48, 0xffff0000, v22
	v_add_f32_e32 v45, v45, v47
	v_add_f32_e32 v46, v46, v48
	v_lshlrev_b32_e32 v47, 16, v23
	v_and_b32_e32 v48, 0xffff0000, v23
	v_add_f32_e32 v45, v45, v47
	v_add_f32_e32 v46, v46, v48
	v_lshlrev_b32_e32 v47, 16, v24
	v_and_b32_e32 v48, 0xffff0000, v24
	v_add_f32_e32 v45, v45, v47
	v_add_f32_e32 v46, v46, v48
	v_lshlrev_b32_e32 v47, 16, v25
	v_and_b32_e32 v48, 0xffff0000, v25
	v_add_f32_e32 v45, v45, v47
	v_add_f32_e32 v46, v46, v48
	v_lshlrev_b32_e32 v47, 16, v26
	v_and_b32_e32 v48, 0xffff0000, v26
	v_add_f32_e32 v45, v45, v47
	v_add_f32_e32 v46, v46, v48
	v_lshlrev_b32_e32 v47, 16, v27
	v_and_b32_e32 v48, 0xffff0000, v27
	v_add_f32_e32 v45, v45, v47
	v_add_f32_e32 v46, v46, v48
	v_lshlrev_b32_e32 v47, 16, v28
	v_and_b32_e32 v48, 0xffff0000, v28
	v_add_f32_e32 v45, v45, v47
	v_add_f32_e32 v46, v46, v48
	v_lshlrev_b32_e32 v47, 16, v29
	v_and_b32_e32 v48, 0xffff0000, v29
	v_add_f32_e32 v45, v45, v47
	v_add_f32_e32 v46, v46, v48
	v_lshlrev_b32_e32 v47, 16, v30
	v_and_b32_e32 v48, 0xffff0000, v30
	v_add_f32_e32 v45, v45, v47
	v_add_f32_e32 v46, v46, v48
	v_lshlrev_b32_e32 v47, 16, v31
	v_and_b32_e32 v48, 0xffff0000, v31
	v_add_f32_e32 v45, v45, v47
	v_add_f32_e32 v46, v46, v48
	v_lshlrev_b32_e32 v47, 16, v32
	v_and_b32_e32 v48, 0xffff0000, v32
	v_add_f32_e32 v45, v45, v47
	v_add_f32_e32 v46, v46, v48
	v_lshlrev_b32_e32 v47, 16, v33
	v_and_b32_e32 v48, 0xffff0000, v33
	v_add_f32_e32 v45, v45, v47
	v_add_f32_e32 v46, v46, v48
	v_lshlrev_b32_e32 v47, 16, v26
	v_and_b32_e32 v48, 0xffff0000, v26
	v_fma_f32 v45, v44, v45, -v47
	v_fma_f32 v46, v44, v46, -v48
	v_cvt_pk_bf16_f32 v45, v45, v46
	global_store_dword v0, v45, s[36:37]
	s_add_u32 s36, s36, 0x400
	s_addc_u32 s37, s37, 0
	s_add_i32 s0, s19, 21
	s_min_u32 s0, s0, s18
	s_add_i32 s1, s19, 5
	s_max_i32 s1, s1, 0
	s_sub_i32 s0, s0, s1
	v_cvt_f32_i32_e32 v37, s0
	v_div_scale_f32 v38, s[0:1], v37, v37, 1.0
	v_rcp_f32_e32 v39, v38
	v_div_scale_f32 v41, vcc, 1.0, v37, 1.0
	v_fma_f32 v40, -v38, v39, 1.0
	v_fmac_f32_e32 v39, v40, v39
	v_mul_f32_e32 v42, v41, v39
	v_fma_f32 v43, -v38, v42, v41
	v_fmac_f32_e32 v42, v43, v39
	v_fma_f32 v38, -v38, v42, v41
	v_div_fmas_f32 v38, v38, v39, v42
	v_div_fixup_f32 v44, v38, v37, 1.0
	s_waitcnt vmcnt(15)
	v_lshlrev_b32_e32 v47, 16, v19
	v_and_b32_e32 v48, 0xffff0000, v19
	v_add_f32_e32 v45, 0, v47
	v_add_f32_e32 v46, 0, v48
	v_lshlrev_b32_e32 v47, 16, v20
	v_and_b32_e32 v48, 0xffff0000, v20
	v_add_f32_e32 v45, v45, v47
	v_add_f32_e32 v46, v46, v48
	v_lshlrev_b32_e32 v47, 16, v21
	v_and_b32_e32 v48, 0xffff0000, v21
	v_add_f32_e32 v45, v45, v47
	v_add_f32_e32 v46, v46, v48
	v_lshlrev_b32_e32 v47, 16, v22
	v_and_b32_e32 v48, 0xffff0000, v22
	v_add_f32_e32 v45, v45, v47
	v_add_f32_e32 v46, v46, v48
	v_lshlrev_b32_e32 v47, 16, v23
	v_and_b32_e32 v48, 0xffff0000, v23
	v_add_f32_e32 v45, v45, v47
	v_add_f32_e32 v46, v46, v48
	v_lshlrev_b32_e32 v47, 16, v24
	v_and_b32_e32 v48, 0xffff0000, v24
	v_add_f32_e32 v45, v45, v47
	v_add_f32_e32 v46, v46, v48
	v_lshlrev_b32_e32 v47, 16, v25
	v_and_b32_e32 v48, 0xffff0000, v25
	v_add_f32_e32 v45, v45, v47
	v_add_f32_e32 v46, v46, v48
	v_lshlrev_b32_e32 v47, 16, v26
	v_and_b32_e32 v48, 0xffff0000, v26
	v_add_f32_e32 v45, v45, v47
	v_add_f32_e32 v46, v46, v48
	v_lshlrev_b32_e32 v47, 16, v27
	v_and_b32_e32 v48, 0xffff0000, v27
	v_add_f32_e32 v45, v45, v47
	v_add_f32_e32 v46, v46, v48
	v_lshlrev_b32_e32 v47, 16, v28
	v_and_b32_e32 v48, 0xffff0000, v28
	v_add_f32_e32 v45, v45, v47
	v_add_f32_e32 v46, v46, v48
	v_lshlrev_b32_e32 v47, 16, v29
	v_and_b32_e32 v48, 0xffff0000, v29
	v_add_f32_e32 v45, v45, v47
	v_add_f32_e32 v46, v46, v48
	v_lshlrev_b32_e32 v47, 16, v30
	v_and_b32_e32 v48, 0xffff0000, v30
	v_add_f32_e32 v45, v45, v47
	v_add_f32_e32 v46, v46, v48
	v_lshlrev_b32_e32 v47, 16, v31
	v_and_b32_e32 v48, 0xffff0000, v31
	v_add_f32_e32 v45, v45, v47
	v_add_f32_e32 v46, v46, v48
	v_lshlrev_b32_e32 v47, 16, v32
	v_and_b32_e32 v48, 0xffff0000, v32
	v_add_f32_e32 v45, v45, v47
	v_add_f32_e32 v46, v46, v48
	v_lshlrev_b32_e32 v47, 16, v33
	v_and_b32_e32 v48, 0xffff0000, v33
	v_add_f32_e32 v45, v45, v47
	v_add_f32_e32 v46, v46, v48
	v_lshlrev_b32_e32 v47, 16, v34
	v_and_b32_e32 v48, 0xffff0000, v34
	v_add_f32_e32 v45, v45, v47
	v_add_f32_e32 v46, v46, v48
	v_lshlrev_b32_e32 v47, 16, v27
	v_and_b32_e32 v48, 0xffff0000, v27
	v_fma_f32 v45, v44, v45, -v47
	v_fma_f32 v46, v44, v46, -v48
	v_cvt_pk_bf16_f32 v45, v45, v46
	global_store_dword v0, v45, s[36:37]
	s_add_u32 s36, s36, 0x400
	s_addc_u32 s37, s37, 0
	s_add_i32 s0, s19, 22
	s_min_u32 s0, s0, s18
	s_add_i32 s1, s19, 6
	s_max_i32 s1, s1, 0
	s_sub_i32 s0, s0, s1
	v_cvt_f32_i32_e32 v37, s0
	v_div_scale_f32 v38, s[0:1], v37, v37, 1.0
	v_rcp_f32_e32 v39, v38
	v_div_scale_f32 v41, vcc, 1.0, v37, 1.0
	v_fma_f32 v40, -v38, v39, 1.0
	v_fmac_f32_e32 v39, v40, v39
	v_mul_f32_e32 v42, v41, v39
	v_fma_f32 v43, -v38, v42, v41
	v_fmac_f32_e32 v42, v43, v39
	v_fma_f32 v38, -v38, v42, v41
	v_div_fmas_f32 v38, v38, v39, v42
	v_div_fixup_f32 v44, v38, v37, 1.0
	s_waitcnt vmcnt(15)
	v_lshlrev_b32_e32 v47, 16, v20
	v_and_b32_e32 v48, 0xffff0000, v20
	v_add_f32_e32 v45, 0, v47
	v_add_f32_e32 v46, 0, v48
	v_lshlrev_b32_e32 v47, 16, v21
	v_and_b32_e32 v48, 0xffff0000, v21
	v_add_f32_e32 v45, v45, v47
	v_add_f32_e32 v46, v46, v48
	v_lshlrev_b32_e32 v47, 16, v22
	v_and_b32_e32 v48, 0xffff0000, v22
	v_add_f32_e32 v45, v45, v47
	v_add_f32_e32 v46, v46, v48
	v_lshlrev_b32_e32 v47, 16, v23
	v_and_b32_e32 v48, 0xffff0000, v23
	v_add_f32_e32 v45, v45, v47
	v_add_f32_e32 v46, v46, v48
	v_lshlrev_b32_e32 v47, 16, v24
	v_and_b32_e32 v48, 0xffff0000, v24
	v_add_f32_e32 v45, v45, v47
	v_add_f32_e32 v46, v46, v48
	v_lshlrev_b32_e32 v47, 16, v25
	v_and_b32_e32 v48, 0xffff0000, v25
	v_add_f32_e32 v45, v45, v47
	v_add_f32_e32 v46, v46, v48
	v_lshlrev_b32_e32 v47, 16, v26
	v_and_b32_e32 v48, 0xffff0000, v26
	v_add_f32_e32 v45, v45, v47
	v_add_f32_e32 v46, v46, v48
	v_lshlrev_b32_e32 v47, 16, v27
	v_and_b32_e32 v48, 0xffff0000, v27
	v_add_f32_e32 v45, v45, v47
	v_add_f32_e32 v46, v46, v48
	v_lshlrev_b32_e32 v47, 16, v28
	v_and_b32_e32 v48, 0xffff0000, v28
	v_add_f32_e32 v45, v45, v47
	v_add_f32_e32 v46, v46, v48
	v_lshlrev_b32_e32 v47, 16, v29
	v_and_b32_e32 v48, 0xffff0000, v29
	v_add_f32_e32 v45, v45, v47
	v_add_f32_e32 v46, v46, v48
	v_lshlrev_b32_e32 v47, 16, v30
	v_and_b32_e32 v48, 0xffff0000, v30
	v_add_f32_e32 v45, v45, v47
	v_add_f32_e32 v46, v46, v48
	v_lshlrev_b32_e32 v47, 16, v31
	v_and_b32_e32 v48, 0xffff0000, v31
	v_add_f32_e32 v45, v45, v47
	v_add_f32_e32 v46, v46, v48
	v_lshlrev_b32_e32 v47, 16, v32
	v_and_b32_e32 v48, 0xffff0000, v32
	v_add_f32_e32 v45, v45, v47
	v_add_f32_e32 v46, v46, v48
	v_lshlrev_b32_e32 v47, 16, v33
	v_and_b32_e32 v48, 0xffff0000, v33
	v_add_f32_e32 v45, v45, v47
	v_add_f32_e32 v46, v46, v48
	v_lshlrev_b32_e32 v47, 16, v34
	v_and_b32_e32 v48, 0xffff0000, v34
	v_add_f32_e32 v45, v45, v47
	v_add_f32_e32 v46, v46, v48
	v_lshlrev_b32_e32 v47, 16, v35
	v_and_b32_e32 v48, 0xffff0000, v35
	v_add_f32_e32 v45, v45, v47
	v_add_f32_e32 v46, v46, v48
	v_lshlrev_b32_e32 v47, 16, v28
	v_and_b32_e32 v48, 0xffff0000, v28
	v_fma_f32 v45, v44, v45, -v47
	v_fma_f32 v46, v44, v46, -v48
	v_cvt_pk_bf16_f32 v45, v45, v46
	global_store_dword v0, v45, s[36:37]
	s_add_u32 s36, s36, 0x400
	s_addc_u32 s37, s37, 0
	s_add_i32 s0, s19, 23
	s_min_u32 s0, s0, s18
	s_add_i32 s1, s19, 7
	s_max_i32 s1, s1, 0
	s_sub_i32 s0, s0, s1
	v_cvt_f32_i32_e32 v37, s0
	v_div_scale_f32 v38, s[0:1], v37, v37, 1.0
	v_rcp_f32_e32 v39, v38
	v_div_scale_f32 v41, vcc, 1.0, v37, 1.0
	v_fma_f32 v40, -v38, v39, 1.0
	v_fmac_f32_e32 v39, v40, v39
	v_mul_f32_e32 v42, v41, v39
	v_fma_f32 v43, -v38, v42, v41
	v_fmac_f32_e32 v42, v43, v39
	v_fma_f32 v38, -v38, v42, v41
	v_div_fmas_f32 v38, v38, v39, v42
	v_div_fixup_f32 v44, v38, v37, 1.0
	s_waitcnt vmcnt(15)
	v_lshlrev_b32_e32 v47, 16, v21
	v_and_b32_e32 v48, 0xffff0000, v21
	v_add_f32_e32 v45, 0, v47
	v_add_f32_e32 v46, 0, v48
	v_lshlrev_b32_e32 v47, 16, v22
	v_and_b32_e32 v48, 0xffff0000, v22
	v_add_f32_e32 v45, v45, v47
	v_add_f32_e32 v46, v46, v48
	v_lshlrev_b32_e32 v47, 16, v23
	v_and_b32_e32 v48, 0xffff0000, v23
	v_add_f32_e32 v45, v45, v47
	v_add_f32_e32 v46, v46, v48
	v_lshlrev_b32_e32 v47, 16, v24
	v_and_b32_e32 v48, 0xffff0000, v24
	v_add_f32_e32 v45, v45, v47
	v_add_f32_e32 v46, v46, v48
	v_lshlrev_b32_e32 v47, 16, v25
	v_and_b32_e32 v48, 0xffff0000, v25
	v_add_f32_e32 v45, v45, v47
	v_add_f32_e32 v46, v46, v48
	v_lshlrev_b32_e32 v47, 16, v26
	v_and_b32_e32 v48, 0xffff0000, v26
	v_add_f32_e32 v45, v45, v47
	v_add_f32_e32 v46, v46, v48
	v_lshlrev_b32_e32 v47, 16, v27
	v_and_b32_e32 v48, 0xffff0000, v27
	v_add_f32_e32 v45, v45, v47
	v_add_f32_e32 v46, v46, v48
	v_lshlrev_b32_e32 v47, 16, v28
	v_and_b32_e32 v48, 0xffff0000, v28
	v_add_f32_e32 v45, v45, v47
	v_add_f32_e32 v46, v46, v48
	v_lshlrev_b32_e32 v47, 16, v29
	v_and_b32_e32 v48, 0xffff0000, v29
	v_add_f32_e32 v45, v45, v47
	v_add_f32_e32 v46, v46, v48
	v_lshlrev_b32_e32 v47, 16, v30
	v_and_b32_e32 v48, 0xffff0000, v30
	v_add_f32_e32 v45, v45, v47
	v_add_f32_e32 v46, v46, v48
	v_lshlrev_b32_e32 v47, 16, v31
	v_and_b32_e32 v48, 0xffff0000, v31
	v_add_f32_e32 v45, v45, v47
	v_add_f32_e32 v46, v46, v48
	v_lshlrev_b32_e32 v47, 16, v32
	v_and_b32_e32 v48, 0xffff0000, v32
	v_add_f32_e32 v45, v45, v47
	v_add_f32_e32 v46, v46, v48
	v_lshlrev_b32_e32 v47, 16, v33
	v_and_b32_e32 v48, 0xffff0000, v33
	v_add_f32_e32 v45, v45, v47
	v_add_f32_e32 v46, v46, v48
	v_lshlrev_b32_e32 v47, 16, v34
	v_and_b32_e32 v48, 0xffff0000, v34
	v_add_f32_e32 v45, v45, v47
	v_add_f32_e32 v46, v46, v48
	v_lshlrev_b32_e32 v47, 16, v35
	v_and_b32_e32 v48, 0xffff0000, v35
	v_add_f32_e32 v45, v45, v47
	v_add_f32_e32 v46, v46, v48
	v_lshlrev_b32_e32 v47, 16, v36
	v_and_b32_e32 v48, 0xffff0000, v36
	v_add_f32_e32 v45, v45, v47
	v_add_f32_e32 v46, v46, v48
	v_lshlrev_b32_e32 v47, 16, v29
	v_and_b32_e32 v48, 0xffff0000, v29
	v_fma_f32 v45, v44, v45, -v47
	v_fma_f32 v46, v44, v46, -v48
	v_cvt_pk_bf16_f32 v45, v45, v46
	global_store_dword v0, v45, s[36:37]
	s_branch .Lpd_done
.Lpd_done:
	s_mov_b64 s[0:1], 0
.LBB0_328:
	s_andn2_b64 vcc, exec, s[0:1]
	s_cbranch_vccnz .LBB0_337
	s_and_saveexec_b64 s[10:11], s[40:41]
	s_cbranch_execz .LBB0_336
	s_lshl_b32 s2, s24, 7
	s_add_i32 s2, s2, 0xfff8c800
	s_mov_b64 s[12:13], 0
	v_mov_b32_e32 v12, v88
	s_branch .LBB0_332

.LBB0_430:
	s_or_b64 exec, exec, s[0:1]
	v_mul_f32_e32 v9, v9, v18
	s_waitcnt lgkmcnt(0)
	ds_bpermute_b32 v77, v71, v9
	s_and_saveexec_b64 s[0:1], s[16:17]
	s_cbranch_execz .LBB0_312
	v_mul_f32_e32 v13, v100, v13
	v_mul_f32_e32 v13, 0.15915494, v13
	v_sin_f32_e32 v156, v13
	v_cos_f32_e32 v13, v13
	s_waitcnt lgkmcnt(0)
	v_mul_f32_e32 v77, v156, v77
	v_cndmask_b32_e64 v77, v77, -v77, s[44:45]
	v_fmac_f32_e32 v77, v13, v9
	v_mov_b32_e32 v9, v77
	s_branch .LBB0_312
.LBB0_437:
	s_mov_b64 s[0:1], 0
	s_mov_b32 s56, 0x800000
	s_movk_i32 s57, 0x1320
	v_readlane_b32 s88, v225, 56
	s_mov_b64 s[24:25], 0x3000
	s_mov_b64 s[94:95], s[90:91]
